# k-loops: per-piece lane-offset VGPRs so each LDS-DMA needs one SALU (M0) instead of three; shared scalar base advances per k-tile
# speedup vs baseline: 1.0043x; 1.0043x over previous
.LBB0_114:
	v_mov_b32_e32 v6, v181
	s_ashr_i32 s93, s92, 6
	v_lshrrev_b32_e32 v7, 4, v6
	v_lshlrev_b32_e32 v1, 6, v6
	v_xor_b32_e32 v0, v7, v6
	v_and_b32_e32 v8, 0x3c0, v1
	v_lshlrev_b32_e32 v1, 7, v6
	s_bfe_u32 s94, s92, 0x20006
	s_and_b32 s86, s91, 63
	s_and_b32 s95, s92, 63
	s_and_b32 s21, s93, -4
	v_lshlrev_b32_e32 v0, 3, v0
	v_and_b32_e32 v1, 0xfffffc00, v1
	s_lshl_b32 s20, s86, 19
	s_or_b32 s58, s21, s94
	s_lshl_b32 s21, s95, 19
	v_and_or_b32 v0, v0, 56, v1
	s_waitcnt lgkmcnt(0)
	s_add_u32 s60, s3, s21
	v_ashrrev_i32_e32 v1, 31, v0
	v_lshl_add_u32 v129, v6, 4, 0
	s_addc_u32 s61, s90, 0
	v_lshlrev_b64 v[0:1], 1, v[0:1]
	v_readfirstlane_b32 s21, v129
	v_add_u32_e32 v9, 0x2000, v129
	v_lshl_add_u64 v[2:3], s[60:61], 0, v[0:1]
	s_mov_b32 m0, s21
	v_readfirstlane_b32 s21, v9
	v_add_u32_e32 v9, 0x4000, v129
	s_barrier
	global_load_lds_dwordx4 v[2:3], off
	v_lshl_add_u64 v[4:5], v[2:3], 0, s[10:11]
	s_mov_b32 m0, s21
	v_readfirstlane_b32 s21, v9
	global_load_lds_dwordx4 v[4:5], off
	v_lshl_add_u64 v[4:5], v[2:3], 0, s[12:13]
	s_mov_b32 m0, s21
	s_ashr_i32 s59, s58, 31
	global_load_lds_dwordx4 v[4:5], off
	v_add_u32_e32 v4, 0x6000, v129
	s_lshl_b64 s[88:89], s[58:59], 19
	v_readfirstlane_b32 s21, v4
	v_lshl_add_u64 v[2:3], v[2:3], 0, s[14:15]
	s_mov_b32 m0, s21
	s_add_u32 s88, s34, s88
	global_load_lds_dwordx4 v[2:3], off
	v_add_u32_e32 v2, 0x8000, v129
	s_addc_u32 s89, s35, s89
	v_readfirstlane_b32 s21, v2
	v_add_u32_e32 v4, 0xa000, v129
	v_lshl_add_u64 v[134:135], s[88:89], 0, v[0:1]
	s_mov_b32 m0, s21
	v_readfirstlane_b32 s21, v4
	v_add_u32_e32 v4, 0xc000, v129
	global_load_lds_dwordx4 v[134:135], off
	v_lshl_add_u64 v[2:3], v[134:135], 0, s[10:11]
	s_mov_b32 m0, s21
	v_readfirstlane_b32 s21, v4
	v_add_u32_e32 v4, 0xe000, v129
	global_load_lds_dwordx4 v[2:3], off
	v_lshl_add_u64 v[2:3], v[134:135], 0, s[12:13]
	s_mov_b32 m0, s21
	v_readfirstlane_b32 s21, v4
	global_load_lds_dwordx4 v[2:3], off
	v_lshl_add_u64 v[2:3], v[134:135], 0, s[14:15]
	s_mov_b32 m0, s21
	v_ashrrev_i32_e32 v4, 6, v6
	global_load_lds_dwordx4 v[2:3], off
	v_lshrrev_b32_e32 v5, 30, v4
	v_add_u32_e32 v5, v4, v5
	v_bfe_u32 v2, v6, 4, 2
	v_bfe_u32 v3, v6, 1, 3
	v_and_b32_e32 v6, 0x7fffc, v5
	v_sub_u32_e32 v4, v4, v6
	v_lshlrev_b32_e32 v139, 13, v4
	v_bitop3_b32 v4, v7, v3, 3 bitop3:0x6c
	v_bitop3_b32 v2, v2, v3, 4 bitop3:0x36
	s_add_u32 s60, s34, s20
	v_lshlrev_b32_e32 v5, 12, v5
	v_lshlrev_b32_e32 v4, 3, v4
	v_lshlrev_b32_e32 v2, 3, v2
	s_addc_u32 s61, s35, 0
	v_and_b32_e32 v138, 0xffffc000, v5
	v_lshl_add_u64 v[136:137], s[60:61], 0, v[0:1]
	s_mov_b64 s[60:61], 0
	v_lshlrev_b32_e32 v140, 1, v8
	v_lshlrev_b32_e32 v141, 1, v4
	v_lshlrev_b32_e32 v142, 1, v2
	s_mov_b32 s87, 0
	s_mov_b32 s59, 0
	v_mov_b32_e32 v8, v128
	v_mov_b32_e32 v9, v128
	v_mov_b32_e32 v10, v128
	v_mov_b32_e32 v11, v128
	v_mov_b32_e32 v20, v128
	v_mov_b32_e32 v21, v128
	v_mov_b32_e32 v22, v128
	v_mov_b32_e32 v23, v128
	v_mov_b32_e32 v0, v128
	v_mov_b32_e32 v1, v128
	v_mov_b32_e32 v2, v128
	v_mov_b32_e32 v3, v128
	v_mov_b32_e32 v4, v128
	v_mov_b32_e32 v5, v128
	v_mov_b32_e32 v6, v128
	v_mov_b32_e32 v7, v128
	v_mov_b32_e32 v12, v128
	v_mov_b32_e32 v13, v128
	v_mov_b32_e32 v14, v128
	v_mov_b32_e32 v15, v128
	v_mov_b32_e32 v24, v128
	v_mov_b32_e32 v25, v128
	v_mov_b32_e32 v26, v128
	v_mov_b32_e32 v27, v128
	v_mov_b32_e32 v16, v128
	v_mov_b32_e32 v17, v128
	v_mov_b32_e32 v18, v128
	v_mov_b32_e32 v19, v128
	v_mov_b32_e32 v28, v128
	v_mov_b32_e32 v29, v128
	v_mov_b32_e32 v30, v128
	v_mov_b32_e32 v31, v128
	v_mov_b32_e32 v32, v128
	v_mov_b32_e32 v33, v128
	v_mov_b32_e32 v34, v128
	v_mov_b32_e32 v35, v128
	v_mov_b32_e32 v40, v128
	v_mov_b32_e32 v41, v128
	v_mov_b32_e32 v42, v128
	v_mov_b32_e32 v43, v128
	v_mov_b32_e32 v36, v128
	v_mov_b32_e32 v37, v128
	v_mov_b32_e32 v38, v128
	v_mov_b32_e32 v39, v128
	v_mov_b32_e32 v44, v128
	v_mov_b32_e32 v45, v128
	v_mov_b32_e32 v46, v128
	v_mov_b32_e32 v47, v128
	v_mov_b32_e32 v48, v128
	v_mov_b32_e32 v49, v128
	v_mov_b32_e32 v50, v128
	v_mov_b32_e32 v51, v128
	v_mov_b32_e32 v56, v128
	v_mov_b32_e32 v57, v128
	v_mov_b32_e32 v58, v128
	v_mov_b32_e32 v59, v128
	v_mov_b32_e32 v52, v128
	v_mov_b32_e32 v53, v128
	v_mov_b32_e32 v54, v128
	v_mov_b32_e32 v55, v128
	v_mov_b32_e32 v60, v128
	v_mov_b32_e32 v61, v128
	v_mov_b32_e32 v62, v128
	v_mov_b32_e32 v63, v128
	v_mov_b32_e32 v64, v128
	v_mov_b32_e32 v65, v128
	v_mov_b32_e32 v66, v128
	v_mov_b32_e32 v67, v128
	v_mov_b32_e32 v72, v128
	v_mov_b32_e32 v73, v128
	v_mov_b32_e32 v74, v128
	v_mov_b32_e32 v75, v128
	v_mov_b32_e32 v68, v128
	v_mov_b32_e32 v69, v128
	v_mov_b32_e32 v70, v128
	v_mov_b32_e32 v71, v128
	v_mov_b32_e32 v76, v128
	v_mov_b32_e32 v77, v128
	v_mov_b32_e32 v78, v128
	v_mov_b32_e32 v79, v128
	v_mov_b32_e32 v80, v128
	v_mov_b32_e32 v81, v128
	v_mov_b32_e32 v82, v128
	v_mov_b32_e32 v83, v128
	v_mov_b32_e32 v88, v128
	v_mov_b32_e32 v89, v128
	v_mov_b32_e32 v90, v128
	v_mov_b32_e32 v91, v128
	v_mov_b32_e32 v84, v128
	v_mov_b32_e32 v85, v128
	v_mov_b32_e32 v86, v128
	v_mov_b32_e32 v87, v128
	v_mov_b32_e32 v92, v128
	v_mov_b32_e32 v93, v128
	v_mov_b32_e32 v94, v128
	v_mov_b32_e32 v95, v128
	v_mov_b32_e32 v96, v128
	v_mov_b32_e32 v97, v128
	v_mov_b32_e32 v98, v128
	v_mov_b32_e32 v99, v128
	v_mov_b32_e32 v104, v128
	v_mov_b32_e32 v105, v128
	v_mov_b32_e32 v106, v128
	v_mov_b32_e32 v107, v128
	v_mov_b32_e32 v100, v128
	v_mov_b32_e32 v101, v128
	v_mov_b32_e32 v102, v128
	v_mov_b32_e32 v103, v128
	v_mov_b32_e32 v108, v128
	v_mov_b32_e32 v109, v128
	v_mov_b32_e32 v110, v128
	v_mov_b32_e32 v111, v128
	v_mov_b32_e32 v112, v128
	v_mov_b32_e32 v113, v128
	v_mov_b32_e32 v114, v128
	v_mov_b32_e32 v115, v128
	v_mov_b32_e32 v120, v128
	v_mov_b32_e32 v121, v128
	v_mov_b32_e32 v122, v128
	v_mov_b32_e32 v123, v128
	v_mov_b32_e32 v116, v128
	v_mov_b32_e32 v117, v128
	v_mov_b32_e32 v118, v128
	v_mov_b32_e32 v119, v128
	v_mov_b32_e32 v124, v128
	v_mov_b32_e32 v125, v128
	v_mov_b32_e32 v126, v128
	v_mov_b32_e32 v127, v128
	s_waitcnt vmcnt(0) lgkmcnt(0)
	s_barrier
	v_add3_u32 v143, v138, v140, v141
	v_add3_u32 v180, v139, v140, v141
	v_add3_u32 v155, v138, v140, v142
	v_add3_u32 v222, v139, v140, v142
	v_readfirstlane_b32 s87, v129
	ds_read_b128 v[156:159], v143
	ds_read_b128 v[160:163], v143 offset:2048
	ds_read_b128 v[164:167], v143 offset:4096
	ds_read_b128 v[168:171], v143 offset:6144
	ds_read_b128 v[190:193], v180 offset:32768
	ds_read_b128 v[194:197], v180 offset:34816
	ds_read_b128 v[198:201], v180 offset:36864
	ds_read_b128 v[202:205], v180 offset:38912
	s_mov_b32 s59, 0
	s_mov_b64 s[60:61], s[34:35]
	v_subrev_u32_e32 v144, s34, v136
	v_subrev_u32_e32 v145, s34, v134
	v_xor_b32_e32 v223, 0x10000, v143
	v_xor_b32_e32 v224, 0x10000, v155
	v_xor_b32_e32 v225, 0x10000, v180
	v_xor_b32_e32 v226, 0x10000, v222
	s_add_u32 s87, s87, 0x10000
	v_add_u32_e32 v227, s18, v144
	v_add_u32_e32 v228, s22, v144
	v_add_u32_e32 v229, s40, v144
	v_add_u32_e32 v144, s16, v144
	v_add_u32_e32 v230, s52, v145
	v_add_u32_e32 v231, s54, v145
	v_add_u32_e32 v232, s56, v145
	v_add_u32_e32 v145, s42, v145
	s_mov_b32 m0, s87
	s_nop 0
	global_load_lds_dwordx4 v144, s[60:61]
	s_add_u32 m0, s87, 0x2000
	s_nop 0
	global_load_lds_dwordx4 v227, s[60:61]
	s_add_u32 m0, s87, 0x4000
	s_nop 0
	global_load_lds_dwordx4 v228, s[60:61]
	s_add_u32 m0, s87, 0x6000
	s_nop 0
	global_load_lds_dwordx4 v229, s[60:61]
	s_add_u32 m0, s87, 0x8000
	s_nop 0
	global_load_lds_dwordx4 v145, s[60:61]
	s_add_u32 m0, s87, 0xa000
	s_nop 0
	global_load_lds_dwordx4 v230, s[60:61]
	s_add_u32 m0, s87, 0xc000
	s_nop 0
	global_load_lds_dwordx4 v231, s[60:61]
	s_add_u32 m0, s87, 0xe000
	s_nop 0
	global_load_lds_dwordx4 v232, s[60:61]
	s_branch .Lg0_entry
.Lg0_top:
	s_waitcnt lgkmcnt(0)
	s_waitcnt vmcnt(0)
	s_barrier
	s_xor_b32 s87, s87, 0x10000
	ds_read_b128 v[156:159], v143
	ds_read_b128 v[160:163], v143 offset:2048
	ds_read_b128 v[164:167], v143 offset:4096
	ds_read_b128 v[168:171], v143 offset:6144
	ds_read_b128 v[190:193], v180 offset:32768
	ds_read_b128 v[194:197], v180 offset:34816
	ds_read_b128 v[198:201], v180 offset:36864
	ds_read_b128 v[202:205], v180 offset:38912
	s_mov_b32 m0, s87
	v_mfma_f32_16x16x32_bf16 v[60:63], v[172:175], v[206:209], v[60:63]
	v_mfma_f32_16x16x32_bf16 v[52:55], v[172:175], v[210:213], v[52:55]
	global_load_lds_dwordx4 v144, s[60:61]
	s_add_u32 m0, s87, 0x2000
	v_mfma_f32_16x16x32_bf16 v[56:59], v[172:175], v[214:217], v[56:59]
	v_mfma_f32_16x16x32_bf16 v[48:51], v[172:175], v[218:221], v[48:51]
	global_load_lds_dwordx4 v227, s[60:61]
	s_add_u32 m0, s87, 0x4000
	v_mfma_f32_16x16x32_bf16 v[44:47], v[176:179], v[206:209], v[44:47]
	v_mfma_f32_16x16x32_bf16 v[36:39], v[176:179], v[210:213], v[36:39]
	global_load_lds_dwordx4 v228, s[60:61]
	s_add_u32 m0, s87, 0x6000
	v_mfma_f32_16x16x32_bf16 v[40:43], v[176:179], v[214:217], v[40:43]
	v_mfma_f32_16x16x32_bf16 v[32:35], v[176:179], v[218:221], v[32:35]
	global_load_lds_dwordx4 v229, s[60:61]
	s_add_u32 m0, s87, 0x8000
	v_mfma_f32_16x16x32_bf16 v[28:31], v[182:185], v[206:209], v[28:31]
	v_mfma_f32_16x16x32_bf16 v[16:19], v[182:185], v[210:213], v[16:19]
	global_load_lds_dwordx4 v145, s[60:61]
	s_add_u32 m0, s87, 0xa000
	v_mfma_f32_16x16x32_bf16 v[24:27], v[182:185], v[214:217], v[24:27]
	v_mfma_f32_16x16x32_bf16 v[12:15], v[182:185], v[218:221], v[12:15]
	global_load_lds_dwordx4 v230, s[60:61]
	s_add_u32 m0, s87, 0xc000
	v_mfma_f32_16x16x32_bf16 v[4:7], v[186:189], v[206:209], v[4:7]
	v_mfma_f32_16x16x32_bf16 v[0:3], v[186:189], v[210:213], v[0:3]
	global_load_lds_dwordx4 v231, s[60:61]
	s_add_u32 m0, s87, 0xe000
	v_mfma_f32_16x16x32_bf16 v[20:23], v[186:189], v[214:217], v[20:23]
	v_mfma_f32_16x16x32_bf16 v[8:11], v[186:189], v[218:221], v[8:11]
	global_load_lds_dwordx4 v232, s[60:61]
.Lg0_entry:
	ds_read_b128 v[172:175], v143 offset:8192
	ds_read_b128 v[176:179], v143 offset:10240
	ds_read_b128 v[182:185], v143 offset:12288
	ds_read_b128 v[186:189], v143 offset:14336
	s_waitcnt lgkmcnt(4)
	v_mfma_f32_16x16x32_bf16 v[124:127], v[156:159], v[190:193], v[124:127]
	v_mfma_f32_16x16x32_bf16 v[116:119], v[156:159], v[194:197], v[116:119]
	v_mfma_f32_16x16x32_bf16 v[120:123], v[156:159], v[198:201], v[120:123]
	v_mfma_f32_16x16x32_bf16 v[112:115], v[156:159], v[202:205], v[112:115]
	v_mfma_f32_16x16x32_bf16 v[108:111], v[160:163], v[190:193], v[108:111]
	v_mfma_f32_16x16x32_bf16 v[100:103], v[160:163], v[194:197], v[100:103]
	v_mfma_f32_16x16x32_bf16 v[104:107], v[160:163], v[198:201], v[104:107]
	v_mfma_f32_16x16x32_bf16 v[96:99], v[160:163], v[202:205], v[96:99]
	v_mfma_f32_16x16x32_bf16 v[92:95], v[164:167], v[190:193], v[92:95]
	v_mfma_f32_16x16x32_bf16 v[84:87], v[164:167], v[194:197], v[84:87]
	v_mfma_f32_16x16x32_bf16 v[88:91], v[164:167], v[198:201], v[88:91]
	v_mfma_f32_16x16x32_bf16 v[80:83], v[164:167], v[202:205], v[80:83]
	v_mfma_f32_16x16x32_bf16 v[76:79], v[168:171], v[190:193], v[76:79]
	v_mfma_f32_16x16x32_bf16 v[68:71], v[168:171], v[194:197], v[68:71]
	v_mfma_f32_16x16x32_bf16 v[72:75], v[168:171], v[198:201], v[72:75]
	v_mfma_f32_16x16x32_bf16 v[64:67], v[168:171], v[202:205], v[64:67]
	ds_read_b128 v[156:159], v155
	ds_read_b128 v[160:163], v155 offset:2048
	ds_read_b128 v[164:167], v155 offset:4096
	ds_read_b128 v[168:171], v155 offset:6144
	ds_read_b128 v[206:209], v222 offset:32768
	ds_read_b128 v[210:213], v222 offset:34816
	ds_read_b128 v[214:217], v222 offset:36864
	ds_read_b128 v[218:221], v222 offset:38912
	s_waitcnt lgkmcnt(8)
	v_mfma_f32_16x16x32_bf16 v[60:63], v[172:175], v[190:193], v[60:63]
	v_mfma_f32_16x16x32_bf16 v[52:55], v[172:175], v[194:197], v[52:55]
	v_mfma_f32_16x16x32_bf16 v[56:59], v[172:175], v[198:201], v[56:59]
	v_mfma_f32_16x16x32_bf16 v[48:51], v[172:175], v[202:205], v[48:51]
	v_mfma_f32_16x16x32_bf16 v[44:47], v[176:179], v[190:193], v[44:47]
	v_mfma_f32_16x16x32_bf16 v[36:39], v[176:179], v[194:197], v[36:39]
	v_mfma_f32_16x16x32_bf16 v[40:43], v[176:179], v[198:201], v[40:43]
	v_mfma_f32_16x16x32_bf16 v[32:35], v[176:179], v[202:205], v[32:35]
	v_mfma_f32_16x16x32_bf16 v[28:31], v[182:185], v[190:193], v[28:31]
	v_mfma_f32_16x16x32_bf16 v[16:19], v[182:185], v[194:197], v[16:19]
	v_mfma_f32_16x16x32_bf16 v[24:27], v[182:185], v[198:201], v[24:27]
	v_mfma_f32_16x16x32_bf16 v[12:15], v[182:185], v[202:205], v[12:15]
	v_mfma_f32_16x16x32_bf16 v[4:7], v[186:189], v[190:193], v[4:7]
	v_mfma_f32_16x16x32_bf16 v[0:3], v[186:189], v[194:197], v[0:3]
	v_mfma_f32_16x16x32_bf16 v[20:23], v[186:189], v[198:201], v[20:23]
	v_mfma_f32_16x16x32_bf16 v[8:11], v[186:189], v[202:205], v[8:11]
	ds_read_b128 v[172:175], v155 offset:8192
	ds_read_b128 v[176:179], v155 offset:10240
	ds_read_b128 v[182:185], v155 offset:12288
	ds_read_b128 v[186:189], v155 offset:14336
	s_waitcnt lgkmcnt(4)
	v_mfma_f32_16x16x32_bf16 v[124:127], v[156:159], v[206:209], v[124:127]
	v_mfma_f32_16x16x32_bf16 v[116:119], v[156:159], v[210:213], v[116:119]
	v_mfma_f32_16x16x32_bf16 v[120:123], v[156:159], v[214:217], v[120:123]
	v_mfma_f32_16x16x32_bf16 v[112:115], v[156:159], v[218:221], v[112:115]
	v_mfma_f32_16x16x32_bf16 v[108:111], v[160:163], v[206:209], v[108:111]
	v_mfma_f32_16x16x32_bf16 v[100:103], v[160:163], v[210:213], v[100:103]
	v_mfma_f32_16x16x32_bf16 v[104:107], v[160:163], v[214:217], v[104:107]
	v_mfma_f32_16x16x32_bf16 v[96:99], v[160:163], v[218:221], v[96:99]
	v_mfma_f32_16x16x32_bf16 v[92:95], v[164:167], v[206:209], v[92:95]
	v_mfma_f32_16x16x32_bf16 v[84:87], v[164:167], v[210:213], v[84:87]
	v_mfma_f32_16x16x32_bf16 v[88:91], v[164:167], v[214:217], v[88:91]
	v_mfma_f32_16x16x32_bf16 v[80:83], v[164:167], v[218:221], v[80:83]
	v_mfma_f32_16x16x32_bf16 v[76:79], v[168:171], v[206:209], v[76:79]
	v_mfma_f32_16x16x32_bf16 v[68:71], v[168:171], v[210:213], v[68:71]
	v_mfma_f32_16x16x32_bf16 v[72:75], v[168:171], v[214:217], v[72:75]
	v_mfma_f32_16x16x32_bf16 v[64:67], v[168:171], v[218:221], v[64:67]
	s_add_u32 s60, s60, 0x80
	s_addc_u32 s61, s61, 0
	s_add_i32 s59, s59, 1
	s_cmp_lt_u32 s59, 15
	s_cbranch_scc0 .Lg0_last
	s_waitcnt lgkmcnt(0)
	s_waitcnt vmcnt(0)
	s_barrier
	s_xor_b32 s87, s87, 0x10000
	ds_read_b128 v[156:159], v223
	ds_read_b128 v[160:163], v223 offset:2048
	ds_read_b128 v[164:167], v223 offset:4096
	ds_read_b128 v[168:171], v223 offset:6144
	ds_read_b128 v[190:193], v225 offset:32768
	ds_read_b128 v[194:197], v225 offset:34816
	ds_read_b128 v[198:201], v225 offset:36864
	ds_read_b128 v[202:205], v225 offset:38912
	s_mov_b32 m0, s87
	v_mfma_f32_16x16x32_bf16 v[60:63], v[172:175], v[206:209], v[60:63]
	v_mfma_f32_16x16x32_bf16 v[52:55], v[172:175], v[210:213], v[52:55]
	global_load_lds_dwordx4 v144, s[60:61]
	s_add_u32 m0, s87, 0x2000
	v_mfma_f32_16x16x32_bf16 v[56:59], v[172:175], v[214:217], v[56:59]
	v_mfma_f32_16x16x32_bf16 v[48:51], v[172:175], v[218:221], v[48:51]
	global_load_lds_dwordx4 v227, s[60:61]
	s_add_u32 m0, s87, 0x4000
	v_mfma_f32_16x16x32_bf16 v[44:47], v[176:179], v[206:209], v[44:47]
	v_mfma_f32_16x16x32_bf16 v[36:39], v[176:179], v[210:213], v[36:39]
	global_load_lds_dwordx4 v228, s[60:61]
	s_add_u32 m0, s87, 0x6000
	v_mfma_f32_16x16x32_bf16 v[40:43], v[176:179], v[214:217], v[40:43]
	v_mfma_f32_16x16x32_bf16 v[32:35], v[176:179], v[218:221], v[32:35]
	global_load_lds_dwordx4 v229, s[60:61]
	s_add_u32 m0, s87, 0x8000
	v_mfma_f32_16x16x32_bf16 v[28:31], v[182:185], v[206:209], v[28:31]
	v_mfma_f32_16x16x32_bf16 v[16:19], v[182:185], v[210:213], v[16:19]
	global_load_lds_dwordx4 v145, s[60:61]
	s_add_u32 m0, s87, 0xa000
	v_mfma_f32_16x16x32_bf16 v[24:27], v[182:185], v[214:217], v[24:27]
	v_mfma_f32_16x16x32_bf16 v[12:15], v[182:185], v[218:221], v[12:15]
	global_load_lds_dwordx4 v230, s[60:61]
	s_add_u32 m0, s87, 0xc000
	v_mfma_f32_16x16x32_bf16 v[4:7], v[186:189], v[206:209], v[4:7]
	v_mfma_f32_16x16x32_bf16 v[0:3], v[186:189], v[210:213], v[0:3]
	global_load_lds_dwordx4 v231, s[60:61]
	s_add_u32 m0, s87, 0xe000
	v_mfma_f32_16x16x32_bf16 v[20:23], v[186:189], v[214:217], v[20:23]
	v_mfma_f32_16x16x32_bf16 v[8:11], v[186:189], v[218:221], v[8:11]
	global_load_lds_dwordx4 v232, s[60:61]
	ds_read_b128 v[172:175], v223 offset:8192
	ds_read_b128 v[176:179], v223 offset:10240
	ds_read_b128 v[182:185], v223 offset:12288
	ds_read_b128 v[186:189], v223 offset:14336
	s_waitcnt lgkmcnt(4)
	v_mfma_f32_16x16x32_bf16 v[124:127], v[156:159], v[190:193], v[124:127]
	v_mfma_f32_16x16x32_bf16 v[116:119], v[156:159], v[194:197], v[116:119]
	v_mfma_f32_16x16x32_bf16 v[120:123], v[156:159], v[198:201], v[120:123]
	v_mfma_f32_16x16x32_bf16 v[112:115], v[156:159], v[202:205], v[112:115]
	v_mfma_f32_16x16x32_bf16 v[108:111], v[160:163], v[190:193], v[108:111]
	v_mfma_f32_16x16x32_bf16 v[100:103], v[160:163], v[194:197], v[100:103]
	v_mfma_f32_16x16x32_bf16 v[104:107], v[160:163], v[198:201], v[104:107]
	v_mfma_f32_16x16x32_bf16 v[96:99], v[160:163], v[202:205], v[96:99]
	v_mfma_f32_16x16x32_bf16 v[92:95], v[164:167], v[190:193], v[92:95]
	v_mfma_f32_16x16x32_bf16 v[84:87], v[164:167], v[194:197], v[84:87]
	v_mfma_f32_16x16x32_bf16 v[88:91], v[164:167], v[198:201], v[88:91]
	v_mfma_f32_16x16x32_bf16 v[80:83], v[164:167], v[202:205], v[80:83]
	v_mfma_f32_16x16x32_bf16 v[76:79], v[168:171], v[190:193], v[76:79]
	v_mfma_f32_16x16x32_bf16 v[68:71], v[168:171], v[194:197], v[68:71]
	v_mfma_f32_16x16x32_bf16 v[72:75], v[168:171], v[198:201], v[72:75]
	v_mfma_f32_16x16x32_bf16 v[64:67], v[168:171], v[202:205], v[64:67]
	ds_read_b128 v[156:159], v224
	ds_read_b128 v[160:163], v224 offset:2048
	ds_read_b128 v[164:167], v224 offset:4096
	ds_read_b128 v[168:171], v224 offset:6144
	ds_read_b128 v[206:209], v226 offset:32768
	ds_read_b128 v[210:213], v226 offset:34816
	ds_read_b128 v[214:217], v226 offset:36864
	ds_read_b128 v[218:221], v226 offset:38912
	s_waitcnt lgkmcnt(8)
	v_mfma_f32_16x16x32_bf16 v[60:63], v[172:175], v[190:193], v[60:63]
	v_mfma_f32_16x16x32_bf16 v[52:55], v[172:175], v[194:197], v[52:55]
	v_mfma_f32_16x16x32_bf16 v[56:59], v[172:175], v[198:201], v[56:59]
	v_mfma_f32_16x16x32_bf16 v[48:51], v[172:175], v[202:205], v[48:51]
	v_mfma_f32_16x16x32_bf16 v[44:47], v[176:179], v[190:193], v[44:47]
	v_mfma_f32_16x16x32_bf16 v[36:39], v[176:179], v[194:197], v[36:39]
	v_mfma_f32_16x16x32_bf16 v[40:43], v[176:179], v[198:201], v[40:43]
	v_mfma_f32_16x16x32_bf16 v[32:35], v[176:179], v[202:205], v[32:35]
	v_mfma_f32_16x16x32_bf16 v[28:31], v[182:185], v[190:193], v[28:31]
	v_mfma_f32_16x16x32_bf16 v[16:19], v[182:185], v[194:197], v[16:19]
	v_mfma_f32_16x16x32_bf16 v[24:27], v[182:185], v[198:201], v[24:27]
	v_mfma_f32_16x16x32_bf16 v[12:15], v[182:185], v[202:205], v[12:15]
	v_mfma_f32_16x16x32_bf16 v[4:7], v[186:189], v[190:193], v[4:7]
	v_mfma_f32_16x16x32_bf16 v[0:3], v[186:189], v[194:197], v[0:3]
	v_mfma_f32_16x16x32_bf16 v[20:23], v[186:189], v[198:201], v[20:23]
	v_mfma_f32_16x16x32_bf16 v[8:11], v[186:189], v[202:205], v[8:11]
	ds_read_b128 v[172:175], v224 offset:8192
	ds_read_b128 v[176:179], v224 offset:10240
	ds_read_b128 v[182:185], v224 offset:12288
	ds_read_b128 v[186:189], v224 offset:14336
	s_waitcnt lgkmcnt(4)
	v_mfma_f32_16x16x32_bf16 v[124:127], v[156:159], v[206:209], v[124:127]
	v_mfma_f32_16x16x32_bf16 v[116:119], v[156:159], v[210:213], v[116:119]
	v_mfma_f32_16x16x32_bf16 v[120:123], v[156:159], v[214:217], v[120:123]
	v_mfma_f32_16x16x32_bf16 v[112:115], v[156:159], v[218:221], v[112:115]
	v_mfma_f32_16x16x32_bf16 v[108:111], v[160:163], v[206:209], v[108:111]
	v_mfma_f32_16x16x32_bf16 v[100:103], v[160:163], v[210:213], v[100:103]
	v_mfma_f32_16x16x32_bf16 v[104:107], v[160:163], v[214:217], v[104:107]
	v_mfma_f32_16x16x32_bf16 v[96:99], v[160:163], v[218:221], v[96:99]
	v_mfma_f32_16x16x32_bf16 v[92:95], v[164:167], v[206:209], v[92:95]
	v_mfma_f32_16x16x32_bf16 v[84:87], v[164:167], v[210:213], v[84:87]
	v_mfma_f32_16x16x32_bf16 v[88:91], v[164:167], v[214:217], v[88:91]
	v_mfma_f32_16x16x32_bf16 v[80:83], v[164:167], v[218:221], v[80:83]
	v_mfma_f32_16x16x32_bf16 v[76:79], v[168:171], v[206:209], v[76:79]
	v_mfma_f32_16x16x32_bf16 v[68:71], v[168:171], v[210:213], v[68:71]
	v_mfma_f32_16x16x32_bf16 v[72:75], v[168:171], v[214:217], v[72:75]
	v_mfma_f32_16x16x32_bf16 v[64:67], v[168:171], v[218:221], v[64:67]
	s_add_u32 s60, s60, 0x80
	s_addc_u32 s61, s61, 0
	s_add_i32 s59, s59, 1
	s_branch .Lg0_top

.LBB0_263:
	s_ashr_i32 s21, s58, 2
	v_mov_b32_e32 v6, v181
	s_and_b32 s6, s58, 7
	s_and_b32 s21, s21, -8
	s_or_b32 s48, s21, s6
	v_lshrrev_b32_e32 v7, 4, v6
	v_lshlrev_b32_e32 v1, 6, v6
	v_xor_b32_e32 v0, v7, v6
	v_and_b32_e32 v8, 0x3c0, v1
	v_lshlrev_b32_e32 v1, 8, v6
	s_ashr_i32 s49, s48, 31
	v_lshlrev_b32_e32 v0, 3, v0
	v_and_b32_e32 v1, 0xfffff800, v1
	s_and_b32 s20, s57, 7
	s_bfe_u32 s6, s58, 0x20003
	s_lshl_b64 s[50:51], s[48:49], 20
	v_and_or_b32 v0, v0, 56, v1
	s_add_u32 s50, s3, s50
	v_ashrrev_i32_e32 v1, 31, v0
	s_addc_u32 s51, s54, s51
	v_lshlrev_b64 v[0:1], 1, v[0:1]
	v_lshl_add_u32 v135, v6, 4, 0
	v_lshl_add_u64 v[2:3], s[50:51], 0, v[0:1]
	v_readfirstlane_b32 s50, v135
	v_add_u32_e32 v9, 0x2000, v135
	s_mov_b32 m0, s50
	v_readfirstlane_b32 s50, v9
	v_add_u32_e32 v9, 0x4000, v135
	s_waitcnt lgkmcnt(0)
	s_barrier
	global_load_lds_dwordx4 v[2:3], off
	v_lshl_add_u64 v[4:5], v[2:3], 0, s[8:9]
	s_mov_b32 m0, s50
	v_readfirstlane_b32 s50, v9
	global_load_lds_dwordx4 v[4:5], off
	v_lshl_add_u64 v[4:5], v[2:3], 0, s[10:11]
	s_mov_b32 m0, s50
	s_lshl_b32 s49, s6, 20
	global_load_lds_dwordx4 v[4:5], off
	v_add_u32_e32 v4, 0x6000, v135
	s_add_u32 s52, s55, s49
	v_readfirstlane_b32 s50, v4
	v_add_u32_e32 v4, 0x8000, v135
	s_addc_u32 s53, s56, 0
	v_lshl_add_u64 v[2:3], v[2:3], 0, s[12:13]
	s_mov_b32 m0, s50
	v_readfirstlane_b32 s50, v4
	v_add_u32_e32 v9, 0xa000, v135
	global_load_lds_dwordx4 v[2:3], off
	v_lshl_add_u64 v[2:3], s[52:53], 0, v[0:1]
	s_mov_b32 m0, s50
	v_readfirstlane_b32 s50, v9
	v_add_u32_e32 v9, 0xc000, v135
	global_load_lds_dwordx4 v[2:3], off
	v_lshl_add_u64 v[4:5], v[2:3], 0, s[8:9]
	s_mov_b32 m0, s50
	v_readfirstlane_b32 s50, v9
	global_load_lds_dwordx4 v[4:5], off
	v_lshl_add_u64 v[4:5], v[2:3], 0, s[10:11]
	s_mov_b32 m0, s50
	v_lshl_add_u64 v[2:3], v[2:3], 0, s[12:13]
	global_load_lds_dwordx4 v[4:5], off
	v_add_u32_e32 v4, 0xe000, v135
	v_mov_b32_e32 v12, 0
	v_readfirstlane_b32 s50, v4
	s_mov_b32 m0, s50
	v_ashrrev_i32_e32 v4, 6, v6
	global_load_lds_dwordx4 v[2:3], off
	s_or_b32 s50, s21, s20
	v_lshrrev_b32_e32 v5, 30, v4
	s_ashr_i32 s51, s50, 31
	v_add_u32_e32 v5, v4, v5
	s_lshl_b64 s[50:51], s[50:51], 20
	v_bfe_u32 v2, v6, 4, 2
	v_bfe_u32 v3, v6, 1, 3
	v_and_b32_e32 v6, 0x7fffc, v5
	s_add_u32 s50, s34, s50
	v_sub_u32_e32 v4, v4, v6
	s_addc_u32 s51, s35, s51
	v_lshlrev_b32_e32 v137, 13, v4
	v_bitop3_b32 v4, v7, v3, 3 bitop3:0x6c
	v_bitop3_b32 v2, v2, v3, 4 bitop3:0x36
	v_lshl_add_u64 v[130:131], s[50:51], 0, v[0:1]
	s_add_u32 s50, s34, s49
	v_lshlrev_b32_e32 v5, 12, v5
	v_lshlrev_b32_e32 v4, 3, v4
	v_lshlrev_b32_e32 v2, 3, v2
	s_addc_u32 s51, s35, 0
	v_and_b32_e32 v136, 0xffffc000, v5
	v_lshl_add_u64 v[132:133], s[50:51], 0, v[0:1]
	s_mov_b64 s[50:51], 0
	v_lshlrev_b32_e32 v138, 1, v8
	v_lshlrev_b32_e32 v139, 1, v4
	v_lshlrev_b32_e32 v140, 1, v2
	s_mov_b32 s59, 0
	s_mov_b32 s49, 0
	v_mov_b32_e32 v13, v12
	v_mov_b32_e32 v14, v12
	v_mov_b32_e32 v15, v12
	v_mov_b32_e32 v24, v12
	v_mov_b32_e32 v25, v12
	v_mov_b32_e32 v26, v12
	v_mov_b32_e32 v27, v12
	v_mov_b32_e32 v0, v12
	v_mov_b32_e32 v1, v12
	v_mov_b32_e32 v2, v12
	v_mov_b32_e32 v3, v12
	v_mov_b32_e32 v4, v12
	v_mov_b32_e32 v5, v12
	v_mov_b32_e32 v6, v12
	v_mov_b32_e32 v7, v12
	v_mov_b32_e32 v8, v12
	v_mov_b32_e32 v9, v12
	v_mov_b32_e32 v10, v12
	v_mov_b32_e32 v11, v12
	v_mov_b32_e32 v16, v12
	v_mov_b32_e32 v17, v12
	v_mov_b32_e32 v18, v12
	v_mov_b32_e32 v19, v12
	v_mov_b32_e32 v20, v12
	v_mov_b32_e32 v21, v12
	v_mov_b32_e32 v22, v12
	v_mov_b32_e32 v23, v12
	v_mov_b32_e32 v28, v12
	v_mov_b32_e32 v29, v12
	v_mov_b32_e32 v30, v12
	v_mov_b32_e32 v31, v12
	v_mov_b32_e32 v32, v12
	v_mov_b32_e32 v33, v12
	v_mov_b32_e32 v34, v12
	v_mov_b32_e32 v35, v12
	v_mov_b32_e32 v36, v12
	v_mov_b32_e32 v37, v12
	v_mov_b32_e32 v38, v12
	v_mov_b32_e32 v39, v12
	v_mov_b32_e32 v40, v12
	v_mov_b32_e32 v41, v12
	v_mov_b32_e32 v42, v12
	v_mov_b32_e32 v43, v12
	v_mov_b32_e32 v44, v12
	v_mov_b32_e32 v45, v12
	v_mov_b32_e32 v46, v12
	v_mov_b32_e32 v47, v12
	v_mov_b32_e32 v48, v12
	v_mov_b32_e32 v49, v12
	v_mov_b32_e32 v50, v12
	v_mov_b32_e32 v51, v12
	v_mov_b32_e32 v52, v12
	v_mov_b32_e32 v53, v12
	v_mov_b32_e32 v54, v12
	v_mov_b32_e32 v55, v12
	v_mov_b32_e32 v56, v12
	v_mov_b32_e32 v57, v12
	v_mov_b32_e32 v58, v12
	v_mov_b32_e32 v59, v12
	v_mov_b32_e32 v60, v12
	v_mov_b32_e32 v61, v12
	v_mov_b32_e32 v62, v12
	v_mov_b32_e32 v63, v12
	v_mov_b32_e32 v64, v12
	v_mov_b32_e32 v65, v12
	v_mov_b32_e32 v66, v12
	v_mov_b32_e32 v67, v12
	v_mov_b32_e32 v68, v12
	v_mov_b32_e32 v69, v12
	v_mov_b32_e32 v70, v12
	v_mov_b32_e32 v71, v12
	v_mov_b32_e32 v72, v12
	v_mov_b32_e32 v73, v12
	v_mov_b32_e32 v74, v12
	v_mov_b32_e32 v75, v12
	v_mov_b32_e32 v76, v12
	v_mov_b32_e32 v77, v12
	v_mov_b32_e32 v78, v12
	v_mov_b32_e32 v79, v12
	v_mov_b32_e32 v80, v12
	v_mov_b32_e32 v81, v12
	v_mov_b32_e32 v82, v12
	v_mov_b32_e32 v83, v12
	v_mov_b32_e32 v84, v12
	v_mov_b32_e32 v85, v12
	v_mov_b32_e32 v86, v12
	v_mov_b32_e32 v87, v12
	v_mov_b32_e32 v88, v12
	v_mov_b32_e32 v89, v12
	v_mov_b32_e32 v90, v12
	v_mov_b32_e32 v91, v12
	v_mov_b32_e32 v92, v12
	v_mov_b32_e32 v93, v12
	v_mov_b32_e32 v94, v12
	v_mov_b32_e32 v95, v12
	v_mov_b32_e32 v96, v12
	v_mov_b32_e32 v97, v12
	v_mov_b32_e32 v98, v12
	v_mov_b32_e32 v99, v12
	v_mov_b32_e32 v100, v12
	v_mov_b32_e32 v101, v12
	v_mov_b32_e32 v102, v12
	v_mov_b32_e32 v103, v12
	v_mov_b32_e32 v104, v12
	v_mov_b32_e32 v105, v12
	v_mov_b32_e32 v106, v12
	v_mov_b32_e32 v107, v12
	v_mov_b32_e32 v108, v12
	v_mov_b32_e32 v109, v12
	v_mov_b32_e32 v110, v12
	v_mov_b32_e32 v111, v12
	v_mov_b32_e32 v112, v12
	v_mov_b32_e32 v113, v12
	v_mov_b32_e32 v114, v12
	v_mov_b32_e32 v115, v12
	v_mov_b32_e32 v116, v12
	v_mov_b32_e32 v117, v12
	v_mov_b32_e32 v118, v12
	v_mov_b32_e32 v119, v12
	v_mov_b32_e32 v120, v12
	v_mov_b32_e32 v121, v12
	v_mov_b32_e32 v122, v12
	v_mov_b32_e32 v123, v12
	v_mov_b32_e32 v124, v12
	v_mov_b32_e32 v125, v12
	v_mov_b32_e32 v126, v12
	v_mov_b32_e32 v127, v12
	s_waitcnt vmcnt(0) lgkmcnt(0)
	s_barrier
	v_add3_u32 v141, v136, v138, v139
	v_add3_u32 v210, v137, v138, v139
	v_add3_u32 v180, v136, v138, v140
	v_add3_u32 v211, v137, v138, v140
	v_readfirstlane_b32 s59, v135
	ds_read_b128 v[142:145], v141
	ds_read_b128 v[146:149], v141 offset:2048
	ds_read_b128 v[150:153], v141 offset:4096
	ds_read_b128 v[154:157], v141 offset:6144
	ds_read_b128 v[174:177], v210 offset:32768
	ds_read_b128 v[182:185], v210 offset:34816
	ds_read_b128 v[186:189], v210 offset:36864
	ds_read_b128 v[190:193], v210 offset:38912
	s_mov_b32 s49, 0
	s_mov_b64 s[50:51], s[34:35]
	v_subrev_u32_e32 v178, s34, v130
	v_subrev_u32_e32 v179, s34, v132
	v_xor_b32_e32 v212, 0x10000, v141
	v_xor_b32_e32 v213, 0x10000, v180
	v_xor_b32_e32 v214, 0x10000, v210
	v_xor_b32_e32 v215, 0x10000, v211
	s_add_u32 s59, s59, 0x10000
	v_add_u32_e32 v216, s16, v178
	v_add_u32_e32 v217, s18, v178
	v_add_u32_e32 v218, s22, v178
	v_add_u32_e32 v178, s14, v178
	v_add_u32_e32 v219, s42, v179
	v_add_u32_e32 v220, s44, v179
	v_add_u32_e32 v221, s46, v179
	v_add_u32_e32 v179, s40, v179
	s_mov_b32 m0, s59
	s_nop 0
	global_load_lds_dwordx4 v178, s[50:51]
	s_add_u32 m0, s59, 0x2000
	s_nop 0
	global_load_lds_dwordx4 v216, s[50:51]
	s_add_u32 m0, s59, 0x4000
	s_nop 0
	global_load_lds_dwordx4 v217, s[50:51]
	s_add_u32 m0, s59, 0x6000
	s_nop 0
	global_load_lds_dwordx4 v218, s[50:51]
	s_add_u32 m0, s59, 0x8000
	s_nop 0
	global_load_lds_dwordx4 v179, s[50:51]
	s_add_u32 m0, s59, 0xa000
	s_nop 0
	global_load_lds_dwordx4 v219, s[50:51]
	s_add_u32 m0, s59, 0xc000
	s_nop 0
	global_load_lds_dwordx4 v220, s[50:51]
	s_add_u32 m0, s59, 0xe000
	s_nop 0
	global_load_lds_dwordx4 v221, s[50:51]
	s_branch .Lg1_entry
.Lg1_top:
	s_waitcnt lgkmcnt(0)
	s_waitcnt vmcnt(0)
	s_barrier
	s_xor_b32 s59, s59, 0x10000
	ds_read_b128 v[142:145], v141
	ds_read_b128 v[146:149], v141 offset:2048
	ds_read_b128 v[150:153], v141 offset:4096
	ds_read_b128 v[154:157], v141 offset:6144
	ds_read_b128 v[174:177], v210 offset:32768
	ds_read_b128 v[182:185], v210 offset:34816
	ds_read_b128 v[186:189], v210 offset:36864
	ds_read_b128 v[190:193], v210 offset:38912
	s_mov_b32 m0, s59
	v_mfma_f32_16x16x32_bf16 v[60:63], v[158:161], v[194:197], v[60:63]
	v_mfma_f32_16x16x32_bf16 v[56:59], v[158:161], v[198:201], v[56:59]
	global_load_lds_dwordx4 v178, s[50:51]
	s_add_u32 m0, s59, 0x2000
	v_mfma_f32_16x16x32_bf16 v[52:55], v[158:161], v[202:205], v[52:55]
	v_mfma_f32_16x16x32_bf16 v[48:51], v[158:161], v[206:209], v[48:51]
	global_load_lds_dwordx4 v216, s[50:51]
	s_add_u32 m0, s59, 0x4000
	v_mfma_f32_16x16x32_bf16 v[44:47], v[162:165], v[194:197], v[44:47]
	v_mfma_f32_16x16x32_bf16 v[40:43], v[162:165], v[198:201], v[40:43]
	global_load_lds_dwordx4 v217, s[50:51]
	s_add_u32 m0, s59, 0x6000
	v_mfma_f32_16x16x32_bf16 v[36:39], v[162:165], v[202:205], v[36:39]
	v_mfma_f32_16x16x32_bf16 v[32:35], v[162:165], v[206:209], v[32:35]
	global_load_lds_dwordx4 v218, s[50:51]
	s_add_u32 m0, s59, 0x8000
	v_mfma_f32_16x16x32_bf16 v[28:31], v[166:169], v[194:197], v[28:31]
	v_mfma_f32_16x16x32_bf16 v[20:23], v[166:169], v[198:201], v[20:23]
	global_load_lds_dwordx4 v179, s[50:51]
	s_add_u32 m0, s59, 0xa000
	v_mfma_f32_16x16x32_bf16 v[16:19], v[166:169], v[202:205], v[16:19]
	v_mfma_f32_16x16x32_bf16 v[8:11], v[166:169], v[206:209], v[8:11]
	global_load_lds_dwordx4 v219, s[50:51]
	s_add_u32 m0, s59, 0xc000
	v_mfma_f32_16x16x32_bf16 v[4:7], v[170:173], v[194:197], v[4:7]
	v_mfma_f32_16x16x32_bf16 v[0:3], v[170:173], v[198:201], v[0:3]
	global_load_lds_dwordx4 v220, s[50:51]
	s_add_u32 m0, s59, 0xe000
	v_mfma_f32_16x16x32_bf16 v[24:27], v[170:173], v[202:205], v[24:27]
	v_mfma_f32_16x16x32_bf16 v[12:15], v[170:173], v[206:209], v[12:15]
	global_load_lds_dwordx4 v221, s[50:51]
.Lg1_entry:
	ds_read_b128 v[158:161], v141 offset:8192
	ds_read_b128 v[162:165], v141 offset:10240
	ds_read_b128 v[166:169], v141 offset:12288
	ds_read_b128 v[170:173], v141 offset:14336
	s_waitcnt lgkmcnt(4)
	v_mfma_f32_16x16x32_bf16 v[124:127], v[142:145], v[174:177], v[124:127]
	v_mfma_f32_16x16x32_bf16 v[120:123], v[142:145], v[182:185], v[120:123]
	v_mfma_f32_16x16x32_bf16 v[116:119], v[142:145], v[186:189], v[116:119]
	v_mfma_f32_16x16x32_bf16 v[112:115], v[142:145], v[190:193], v[112:115]
	v_mfma_f32_16x16x32_bf16 v[108:111], v[146:149], v[174:177], v[108:111]
	v_mfma_f32_16x16x32_bf16 v[104:107], v[146:149], v[182:185], v[104:107]
	v_mfma_f32_16x16x32_bf16 v[100:103], v[146:149], v[186:189], v[100:103]
	v_mfma_f32_16x16x32_bf16 v[96:99], v[146:149], v[190:193], v[96:99]
	v_mfma_f32_16x16x32_bf16 v[92:95], v[150:153], v[174:177], v[92:95]
	v_mfma_f32_16x16x32_bf16 v[88:91], v[150:153], v[182:185], v[88:91]
	v_mfma_f32_16x16x32_bf16 v[84:87], v[150:153], v[186:189], v[84:87]
	v_mfma_f32_16x16x32_bf16 v[80:83], v[150:153], v[190:193], v[80:83]
	v_mfma_f32_16x16x32_bf16 v[76:79], v[154:157], v[174:177], v[76:79]
	v_mfma_f32_16x16x32_bf16 v[72:75], v[154:157], v[182:185], v[72:75]
	v_mfma_f32_16x16x32_bf16 v[68:71], v[154:157], v[186:189], v[68:71]
	v_mfma_f32_16x16x32_bf16 v[64:67], v[154:157], v[190:193], v[64:67]
	ds_read_b128 v[142:145], v180
	ds_read_b128 v[146:149], v180 offset:2048
	ds_read_b128 v[150:153], v180 offset:4096
	ds_read_b128 v[154:157], v180 offset:6144
	ds_read_b128 v[194:197], v211 offset:32768
	ds_read_b128 v[198:201], v211 offset:34816
	ds_read_b128 v[202:205], v211 offset:36864
	ds_read_b128 v[206:209], v211 offset:38912
	s_waitcnt lgkmcnt(8)
	v_mfma_f32_16x16x32_bf16 v[60:63], v[158:161], v[174:177], v[60:63]
	v_mfma_f32_16x16x32_bf16 v[56:59], v[158:161], v[182:185], v[56:59]
	v_mfma_f32_16x16x32_bf16 v[52:55], v[158:161], v[186:189], v[52:55]
	v_mfma_f32_16x16x32_bf16 v[48:51], v[158:161], v[190:193], v[48:51]
	v_mfma_f32_16x16x32_bf16 v[44:47], v[162:165], v[174:177], v[44:47]
	v_mfma_f32_16x16x32_bf16 v[40:43], v[162:165], v[182:185], v[40:43]
	v_mfma_f32_16x16x32_bf16 v[36:39], v[162:165], v[186:189], v[36:39]
	v_mfma_f32_16x16x32_bf16 v[32:35], v[162:165], v[190:193], v[32:35]
	v_mfma_f32_16x16x32_bf16 v[28:31], v[166:169], v[174:177], v[28:31]
	v_mfma_f32_16x16x32_bf16 v[20:23], v[166:169], v[182:185], v[20:23]
	v_mfma_f32_16x16x32_bf16 v[16:19], v[166:169], v[186:189], v[16:19]
	v_mfma_f32_16x16x32_bf16 v[8:11], v[166:169], v[190:193], v[8:11]
	v_mfma_f32_16x16x32_bf16 v[4:7], v[170:173], v[174:177], v[4:7]
	v_mfma_f32_16x16x32_bf16 v[0:3], v[170:173], v[182:185], v[0:3]
	v_mfma_f32_16x16x32_bf16 v[24:27], v[170:173], v[186:189], v[24:27]
	v_mfma_f32_16x16x32_bf16 v[12:15], v[170:173], v[190:193], v[12:15]
	ds_read_b128 v[158:161], v180 offset:8192
	ds_read_b128 v[162:165], v180 offset:10240
	ds_read_b128 v[166:169], v180 offset:12288
	ds_read_b128 v[170:173], v180 offset:14336
	s_waitcnt lgkmcnt(4)
	v_mfma_f32_16x16x32_bf16 v[124:127], v[142:145], v[194:197], v[124:127]
	v_mfma_f32_16x16x32_bf16 v[120:123], v[142:145], v[198:201], v[120:123]
	v_mfma_f32_16x16x32_bf16 v[116:119], v[142:145], v[202:205], v[116:119]
	v_mfma_f32_16x16x32_bf16 v[112:115], v[142:145], v[206:209], v[112:115]
	v_mfma_f32_16x16x32_bf16 v[108:111], v[146:149], v[194:197], v[108:111]
	v_mfma_f32_16x16x32_bf16 v[104:107], v[146:149], v[198:201], v[104:107]
	v_mfma_f32_16x16x32_bf16 v[100:103], v[146:149], v[202:205], v[100:103]
	v_mfma_f32_16x16x32_bf16 v[96:99], v[146:149], v[206:209], v[96:99]
	v_mfma_f32_16x16x32_bf16 v[92:95], v[150:153], v[194:197], v[92:95]
	v_mfma_f32_16x16x32_bf16 v[88:91], v[150:153], v[198:201], v[88:91]
	v_mfma_f32_16x16x32_bf16 v[84:87], v[150:153], v[202:205], v[84:87]
	v_mfma_f32_16x16x32_bf16 v[80:83], v[150:153], v[206:209], v[80:83]
	v_mfma_f32_16x16x32_bf16 v[76:79], v[154:157], v[194:197], v[76:79]
	v_mfma_f32_16x16x32_bf16 v[72:75], v[154:157], v[198:201], v[72:75]
	v_mfma_f32_16x16x32_bf16 v[68:71], v[154:157], v[202:205], v[68:71]
	v_mfma_f32_16x16x32_bf16 v[64:67], v[154:157], v[206:209], v[64:67]
	s_add_u32 s50, s50, 0x80
	s_addc_u32 s51, s51, 0
	s_add_i32 s49, s49, 1
	s_cmp_lt_u32 s49, 31
	s_cbranch_scc0 .Lg1_last
	s_waitcnt lgkmcnt(0)
	s_waitcnt vmcnt(0)
	s_barrier
	s_xor_b32 s59, s59, 0x10000
	ds_read_b128 v[142:145], v212
	ds_read_b128 v[146:149], v212 offset:2048
	ds_read_b128 v[150:153], v212 offset:4096
	ds_read_b128 v[154:157], v212 offset:6144
	ds_read_b128 v[174:177], v214 offset:32768
	ds_read_b128 v[182:185], v214 offset:34816
	ds_read_b128 v[186:189], v214 offset:36864
	ds_read_b128 v[190:193], v214 offset:38912
	s_mov_b32 m0, s59
	v_mfma_f32_16x16x32_bf16 v[60:63], v[158:161], v[194:197], v[60:63]
	v_mfma_f32_16x16x32_bf16 v[56:59], v[158:161], v[198:201], v[56:59]
	global_load_lds_dwordx4 v178, s[50:51]
	s_add_u32 m0, s59, 0x2000
	v_mfma_f32_16x16x32_bf16 v[52:55], v[158:161], v[202:205], v[52:55]
	v_mfma_f32_16x16x32_bf16 v[48:51], v[158:161], v[206:209], v[48:51]
	global_load_lds_dwordx4 v216, s[50:51]
	s_add_u32 m0, s59, 0x4000
	v_mfma_f32_16x16x32_bf16 v[44:47], v[162:165], v[194:197], v[44:47]
	v_mfma_f32_16x16x32_bf16 v[40:43], v[162:165], v[198:201], v[40:43]
	global_load_lds_dwordx4 v217, s[50:51]
	s_add_u32 m0, s59, 0x6000
	v_mfma_f32_16x16x32_bf16 v[36:39], v[162:165], v[202:205], v[36:39]
	v_mfma_f32_16x16x32_bf16 v[32:35], v[162:165], v[206:209], v[32:35]
	global_load_lds_dwordx4 v218, s[50:51]
	s_add_u32 m0, s59, 0x8000
	v_mfma_f32_16x16x32_bf16 v[28:31], v[166:169], v[194:197], v[28:31]
	v_mfma_f32_16x16x32_bf16 v[20:23], v[166:169], v[198:201], v[20:23]
	global_load_lds_dwordx4 v179, s[50:51]
	s_add_u32 m0, s59, 0xa000
	v_mfma_f32_16x16x32_bf16 v[16:19], v[166:169], v[202:205], v[16:19]
	v_mfma_f32_16x16x32_bf16 v[8:11], v[166:169], v[206:209], v[8:11]
	global_load_lds_dwordx4 v219, s[50:51]
	s_add_u32 m0, s59, 0xc000
	v_mfma_f32_16x16x32_bf16 v[4:7], v[170:173], v[194:197], v[4:7]
	v_mfma_f32_16x16x32_bf16 v[0:3], v[170:173], v[198:201], v[0:3]
	global_load_lds_dwordx4 v220, s[50:51]
	s_add_u32 m0, s59, 0xe000
	v_mfma_f32_16x16x32_bf16 v[24:27], v[170:173], v[202:205], v[24:27]
	v_mfma_f32_16x16x32_bf16 v[12:15], v[170:173], v[206:209], v[12:15]
	global_load_lds_dwordx4 v221, s[50:51]
	ds_read_b128 v[158:161], v212 offset:8192
	ds_read_b128 v[162:165], v212 offset:10240
	ds_read_b128 v[166:169], v212 offset:12288
	ds_read_b128 v[170:173], v212 offset:14336
	s_waitcnt lgkmcnt(4)
	v_mfma_f32_16x16x32_bf16 v[124:127], v[142:145], v[174:177], v[124:127]
	v_mfma_f32_16x16x32_bf16 v[120:123], v[142:145], v[182:185], v[120:123]
	v_mfma_f32_16x16x32_bf16 v[116:119], v[142:145], v[186:189], v[116:119]
	v_mfma_f32_16x16x32_bf16 v[112:115], v[142:145], v[190:193], v[112:115]
	v_mfma_f32_16x16x32_bf16 v[108:111], v[146:149], v[174:177], v[108:111]
	v_mfma_f32_16x16x32_bf16 v[104:107], v[146:149], v[182:185], v[104:107]
	v_mfma_f32_16x16x32_bf16 v[100:103], v[146:149], v[186:189], v[100:103]
	v_mfma_f32_16x16x32_bf16 v[96:99], v[146:149], v[190:193], v[96:99]
	v_mfma_f32_16x16x32_bf16 v[92:95], v[150:153], v[174:177], v[92:95]
	v_mfma_f32_16x16x32_bf16 v[88:91], v[150:153], v[182:185], v[88:91]
	v_mfma_f32_16x16x32_bf16 v[84:87], v[150:153], v[186:189], v[84:87]
	v_mfma_f32_16x16x32_bf16 v[80:83], v[150:153], v[190:193], v[80:83]
	v_mfma_f32_16x16x32_bf16 v[76:79], v[154:157], v[174:177], v[76:79]
	v_mfma_f32_16x16x32_bf16 v[72:75], v[154:157], v[182:185], v[72:75]
	v_mfma_f32_16x16x32_bf16 v[68:71], v[154:157], v[186:189], v[68:71]
	v_mfma_f32_16x16x32_bf16 v[64:67], v[154:157], v[190:193], v[64:67]
	ds_read_b128 v[142:145], v213
	ds_read_b128 v[146:149], v213 offset:2048
	ds_read_b128 v[150:153], v213 offset:4096
	ds_read_b128 v[154:157], v213 offset:6144
	ds_read_b128 v[194:197], v215 offset:32768
	ds_read_b128 v[198:201], v215 offset:34816
	ds_read_b128 v[202:205], v215 offset:36864
	ds_read_b128 v[206:209], v215 offset:38912
	s_waitcnt lgkmcnt(8)
	v_mfma_f32_16x16x32_bf16 v[60:63], v[158:161], v[174:177], v[60:63]
	v_mfma_f32_16x16x32_bf16 v[56:59], v[158:161], v[182:185], v[56:59]
	v_mfma_f32_16x16x32_bf16 v[52:55], v[158:161], v[186:189], v[52:55]
	v_mfma_f32_16x16x32_bf16 v[48:51], v[158:161], v[190:193], v[48:51]
	v_mfma_f32_16x16x32_bf16 v[44:47], v[162:165], v[174:177], v[44:47]
	v_mfma_f32_16x16x32_bf16 v[40:43], v[162:165], v[182:185], v[40:43]
	v_mfma_f32_16x16x32_bf16 v[36:39], v[162:165], v[186:189], v[36:39]
	v_mfma_f32_16x16x32_bf16 v[32:35], v[162:165], v[190:193], v[32:35]
	v_mfma_f32_16x16x32_bf16 v[28:31], v[166:169], v[174:177], v[28:31]
	v_mfma_f32_16x16x32_bf16 v[20:23], v[166:169], v[182:185], v[20:23]
	v_mfma_f32_16x16x32_bf16 v[16:19], v[166:169], v[186:189], v[16:19]
	v_mfma_f32_16x16x32_bf16 v[8:11], v[166:169], v[190:193], v[8:11]
	v_mfma_f32_16x16x32_bf16 v[4:7], v[170:173], v[174:177], v[4:7]
	v_mfma_f32_16x16x32_bf16 v[0:3], v[170:173], v[182:185], v[0:3]
	v_mfma_f32_16x16x32_bf16 v[24:27], v[170:173], v[186:189], v[24:27]
	v_mfma_f32_16x16x32_bf16 v[12:15], v[170:173], v[190:193], v[12:15]
	ds_read_b128 v[158:161], v213 offset:8192
	ds_read_b128 v[162:165], v213 offset:10240
	ds_read_b128 v[166:169], v213 offset:12288
	ds_read_b128 v[170:173], v213 offset:14336
	s_waitcnt lgkmcnt(4)
	v_mfma_f32_16x16x32_bf16 v[124:127], v[142:145], v[194:197], v[124:127]
	v_mfma_f32_16x16x32_bf16 v[120:123], v[142:145], v[198:201], v[120:123]
	v_mfma_f32_16x16x32_bf16 v[116:119], v[142:145], v[202:205], v[116:119]
	v_mfma_f32_16x16x32_bf16 v[112:115], v[142:145], v[206:209], v[112:115]
	v_mfma_f32_16x16x32_bf16 v[108:111], v[146:149], v[194:197], v[108:111]
	v_mfma_f32_16x16x32_bf16 v[104:107], v[146:149], v[198:201], v[104:107]
	v_mfma_f32_16x16x32_bf16 v[100:103], v[146:149], v[202:205], v[100:103]
	v_mfma_f32_16x16x32_bf16 v[96:99], v[146:149], v[206:209], v[96:99]
	v_mfma_f32_16x16x32_bf16 v[92:95], v[150:153], v[194:197], v[92:95]
	v_mfma_f32_16x16x32_bf16 v[88:91], v[150:153], v[198:201], v[88:91]
	v_mfma_f32_16x16x32_bf16 v[84:87], v[150:153], v[202:205], v[84:87]
	v_mfma_f32_16x16x32_bf16 v[80:83], v[150:153], v[206:209], v[80:83]
	v_mfma_f32_16x16x32_bf16 v[76:79], v[154:157], v[194:197], v[76:79]
	v_mfma_f32_16x16x32_bf16 v[72:75], v[154:157], v[198:201], v[72:75]
	v_mfma_f32_16x16x32_bf16 v[68:71], v[154:157], v[202:205], v[68:71]
	v_mfma_f32_16x16x32_bf16 v[64:67], v[154:157], v[206:209], v[64:67]
	s_add_u32 s50, s50, 0x80
	s_addc_u32 s51, s51, 0
	s_add_i32 s49, s49, 1
	s_branch .Lg1_top

.LBB0_452:
	s_ashr_i32 s46, s60, 3
	s_and_b32 s21, s60, 7
	s_and_b32 s62, s46, -8
	v_mov_b32_e32 v6, v181
	s_or_b32 s46, s62, s21
	s_ashr_i32 s47, s46, 31
	v_lshrrev_b32_e32 v7, 4, v6
	v_lshlrev_b32_e32 v1, 6, v6
	v_xor_b32_e32 v0, v7, v6
	v_and_b32_e32 v8, 0x3c0, v1
	v_lshlrev_b32_e32 v1, 7, v6
	s_and_b32 s20, s55, 7
	s_bfe_u32 s61, s60, 0x30003
	s_lshl_b64 s[48:49], s[46:47], 19
	v_lshlrev_b32_e32 v0, 3, v0
	v_and_b32_e32 v1, 0xfffffc00, v1
	s_add_u32 s48, s3, s48
	v_and_or_b32 v0, v0, 56, v1
	s_addc_u32 s49, s54, s49
	s_lshl_b32 s21, s61, 19
	v_ashrrev_i32_e32 v1, 31, v0
	v_lshl_add_u32 v140, v6, 4, 0
	s_add_u32 s50, s34, s21
	v_lshlrev_b64 v[0:1], 1, v[0:1]
	v_readfirstlane_b32 s21, v140
	v_add_u32_e32 v9, 0x2000, v140
	v_lshl_add_u64 v[2:3], s[48:49], 0, v[0:1]
	s_mov_b32 m0, s21
	v_readfirstlane_b32 s21, v9
	v_add_u32_e32 v9, 0x4000, v140
	s_barrier
	global_load_lds_dwordx4 v[2:3], off
	v_lshl_add_u64 v[4:5], v[2:3], 0, s[6:7]
	s_mov_b32 m0, s21
	v_readfirstlane_b32 s21, v9
	global_load_lds_dwordx4 v[4:5], off
	v_lshl_add_u64 v[4:5], v[2:3], 0, s[8:9]
	s_mov_b32 m0, s21
	v_lshl_add_u64 v[2:3], v[2:3], 0, s[10:11]
	global_load_lds_dwordx4 v[4:5], off
	v_add_u32_e32 v4, 0x6000, v140
	s_addc_u32 s51, s35, 0
	v_readfirstlane_b32 s21, v4
	s_mov_b32 m0, s21
	v_add_u32_e32 v4, 0xa000, v140
	global_load_lds_dwordx4 v[2:3], off
	v_add_u32_e32 v2, 0x8000, v140
	v_lshl_add_u64 v[132:133], s[50:51], 0, v[0:1]
	v_readfirstlane_b32 s21, v2
	s_mov_b32 m0, s21
	v_readfirstlane_b32 s21, v4
	v_add_u32_e32 v4, 0xc000, v140
	global_load_lds_dwordx4 v[132:133], off
	v_lshl_add_u64 v[2:3], v[132:133], 0, s[6:7]
	s_mov_b32 m0, s21
	v_readfirstlane_b32 s21, v4
	v_add_u32_e32 v4, 0xe000, v140
	global_load_lds_dwordx4 v[2:3], off
	v_lshl_add_u64 v[2:3], v[132:133], 0, s[8:9]
	s_mov_b32 m0, s21
	v_readfirstlane_b32 s21, v4
	global_load_lds_dwordx4 v[2:3], off
	v_lshl_add_u64 v[2:3], v[132:133], 0, s[10:11]
	s_mov_b32 m0, s21
	v_ashrrev_i32_e32 v4, 6, v6
	global_load_lds_dwordx4 v[2:3], off
	v_lshrrev_b32_e32 v5, 30, v4
	v_add_u32_e32 v5, v4, v5
	s_or_b32 s48, s62, s20
	v_bfe_u32 v2, v6, 4, 2
	v_bfe_u32 v3, v6, 1, 3
	v_and_b32_e32 v6, 0x7fffc, v5
	s_ashr_i32 s49, s48, 31
	v_sub_u32_e32 v4, v4, v6
	s_lshl_b64 s[48:49], s[48:49], 19
	v_lshlrev_b32_e32 v142, 13, v4
	v_bitop3_b32 v4, v7, v3, 3 bitop3:0x6c
	v_bitop3_b32 v2, v2, v3, 4 bitop3:0x36
	s_add_u32 s48, s34, s48
	v_lshlrev_b32_e32 v5, 12, v5
	v_lshlrev_b32_e32 v4, 3, v4
	v_lshlrev_b32_e32 v2, 3, v2
	s_addc_u32 s49, s35, s49
	v_and_b32_e32 v141, 0xffffc000, v5
	v_lshl_add_u64 v[134:135], s[48:49], 0, v[0:1]
	s_mov_b64 s[48:49], 0
	v_lshlrev_b32_e32 v143, 1, v8
	v_lshlrev_b32_e32 v144, 1, v4
	v_lshlrev_b32_e32 v145, 1, v2
	s_mov_b32 s62, 0
	s_mov_b32 s47, 0
	v_mov_b32_e32 v40, 0
	v_mov_b32_e32 v41, v129
	v_mov_b32_e32 v42, v129
	v_mov_b32_e32 v43, v129
	v_mov_b32_e32 v48, 0
	v_mov_b32_e32 v49, v129
	v_mov_b32_e32 v50, v129
	v_mov_b32_e32 v51, v129
	v_mov_b32_e32 v0, 0
	v_mov_b32_e32 v1, v129
	v_mov_b32_e32 v2, v129
	v_mov_b32_e32 v3, v129
	v_mov_b32_e32 v4, 0
	v_mov_b32_e32 v5, v129
	v_mov_b32_e32 v6, v129
	v_mov_b32_e32 v7, v129
	v_mov_b32_e32 v8, 0
	v_mov_b32_e32 v9, v129
	v_mov_b32_e32 v10, v129
	v_mov_b32_e32 v11, v129
	v_mov_b32_e32 v12, 0
	v_mov_b32_e32 v13, v129
	v_mov_b32_e32 v14, v129
	v_mov_b32_e32 v15, v129
	v_mov_b32_e32 v16, 0
	v_mov_b32_e32 v17, v129
	v_mov_b32_e32 v18, v129
	v_mov_b32_e32 v19, v129
	v_mov_b32_e32 v20, 0
	v_mov_b32_e32 v21, v129
	v_mov_b32_e32 v22, v129
	v_mov_b32_e32 v23, v129
	v_mov_b32_e32 v24, 0
	v_mov_b32_e32 v25, v129
	v_mov_b32_e32 v26, v129
	v_mov_b32_e32 v27, v129
	v_mov_b32_e32 v28, 0
	v_mov_b32_e32 v29, v129
	v_mov_b32_e32 v30, v129
	v_mov_b32_e32 v31, v129
	v_mov_b32_e32 v32, 0
	v_mov_b32_e32 v33, v129
	v_mov_b32_e32 v34, v129
	v_mov_b32_e32 v35, v129
	v_mov_b32_e32 v36, 0
	v_mov_b32_e32 v37, v129
	v_mov_b32_e32 v38, v129
	v_mov_b32_e32 v39, v129
	v_mov_b32_e32 v44, 0
	v_mov_b32_e32 v45, v129
	v_mov_b32_e32 v46, v129
	v_mov_b32_e32 v47, v129
	v_mov_b32_e32 v52, 0
	v_mov_b32_e32 v53, v129
	v_mov_b32_e32 v54, v129
	v_mov_b32_e32 v55, v129
	v_mov_b32_e32 v56, 0
	v_mov_b32_e32 v57, v129
	v_mov_b32_e32 v58, v129
	v_mov_b32_e32 v59, v129
	v_mov_b32_e32 v60, 0
	v_mov_b32_e32 v61, v129
	v_mov_b32_e32 v62, v129
	v_mov_b32_e32 v63, v129
	v_mov_b32_e32 v64, 0
	v_mov_b32_e32 v65, v129
	v_mov_b32_e32 v66, v129
	v_mov_b32_e32 v67, v129
	v_mov_b32_e32 v68, 0
	v_mov_b32_e32 v69, v129
	v_mov_b32_e32 v70, v129
	v_mov_b32_e32 v71, v129
	v_mov_b32_e32 v72, 0
	v_mov_b32_e32 v73, v129
	v_mov_b32_e32 v74, v129
	v_mov_b32_e32 v75, v129
	v_mov_b32_e32 v76, 0
	v_mov_b32_e32 v77, v129
	v_mov_b32_e32 v78, v129
	v_mov_b32_e32 v79, v129
	v_mov_b32_e32 v80, 0
	v_mov_b32_e32 v81, v129
	v_mov_b32_e32 v82, v129
	v_mov_b32_e32 v83, v129
	v_mov_b32_e32 v84, 0
	v_mov_b32_e32 v85, v129
	v_mov_b32_e32 v86, v129
	v_mov_b32_e32 v87, v129
	v_mov_b32_e32 v88, 0
	v_mov_b32_e32 v89, v129
	v_mov_b32_e32 v90, v129
	v_mov_b32_e32 v91, v129
	v_mov_b32_e32 v92, 0
	v_mov_b32_e32 v93, v129
	v_mov_b32_e32 v94, v129
	v_mov_b32_e32 v95, v129
	v_mov_b32_e32 v96, 0
	v_mov_b32_e32 v97, v129
	v_mov_b32_e32 v98, v129
	v_mov_b32_e32 v99, v129
	v_mov_b32_e32 v100, 0
	v_mov_b32_e32 v101, v129
	v_mov_b32_e32 v102, v129
	v_mov_b32_e32 v103, v129
	v_mov_b32_e32 v104, 0
	v_mov_b32_e32 v105, v129
	v_mov_b32_e32 v106, v129
	v_mov_b32_e32 v107, v129
	v_mov_b32_e32 v108, 0
	v_mov_b32_e32 v109, v129
	v_mov_b32_e32 v110, v129
	v_mov_b32_e32 v111, v129
	v_mov_b32_e32 v112, 0
	v_mov_b32_e32 v113, v129
	v_mov_b32_e32 v114, v129
	v_mov_b32_e32 v115, v129
	v_mov_b32_e32 v116, 0
	v_mov_b32_e32 v117, v129
	v_mov_b32_e32 v118, v129
	v_mov_b32_e32 v119, v129
	v_mov_b32_e32 v120, 0
	v_mov_b32_e32 v121, v129
	v_mov_b32_e32 v122, v129
	v_mov_b32_e32 v123, v129
	v_mov_b32_e32 v124, 0
	v_mov_b32_e32 v125, v129
	v_mov_b32_e32 v126, v129
	v_mov_b32_e32 v127, v129
	s_waitcnt vmcnt(0) lgkmcnt(0)
	s_barrier
	v_add3_u32 v180, v141, v143, v144
	v_add3_u32 v215, v142, v143, v144
	v_add3_u32 v214, v141, v143, v145
	v_add3_u32 v216, v142, v143, v145
	v_readfirstlane_b32 s62, v140
	ds_read_b128 v[146:149], v180
	ds_read_b128 v[150:153], v180 offset:2048
	ds_read_b128 v[154:157], v180 offset:4096
	ds_read_b128 v[158:161], v180 offset:6144
	ds_read_b128 v[182:185], v215 offset:32768
	ds_read_b128 v[186:189], v215 offset:34816
	ds_read_b128 v[190:193], v215 offset:36864
	ds_read_b128 v[194:197], v215 offset:38912
	s_mov_b32 s47, 0
	s_mov_b64 s[48:49], s[34:35]
	v_subrev_u32_e32 v178, s34, v134
	v_subrev_u32_e32 v179, s34, v132
	v_xor_b32_e32 v217, 0x10000, v180
	v_xor_b32_e32 v218, 0x10000, v214
	v_xor_b32_e32 v219, 0x10000, v215
	v_xor_b32_e32 v220, 0x10000, v216
	s_add_u32 s62, s62, 0x10000
	v_add_u32_e32 v221, s14, v178
	v_add_u32_e32 v222, s16, v178
	v_add_u32_e32 v223, s18, v178
	v_add_u32_e32 v178, s12, v178
	v_add_u32_e32 v224, s36, v179
	v_add_u32_e32 v225, s40, v179
	v_add_u32_e32 v226, s42, v179
	v_add_u32_e32 v179, s22, v179
	s_mov_b32 m0, s62
	s_nop 0
	global_load_lds_dwordx4 v178, s[48:49]
	s_add_u32 m0, s62, 0x2000
	s_nop 0
	global_load_lds_dwordx4 v221, s[48:49]
	s_add_u32 m0, s62, 0x4000
	s_nop 0
	global_load_lds_dwordx4 v222, s[48:49]
	s_add_u32 m0, s62, 0x6000
	s_nop 0
	global_load_lds_dwordx4 v223, s[48:49]
	s_add_u32 m0, s62, 0x8000
	s_nop 0
	global_load_lds_dwordx4 v179, s[48:49]
	s_add_u32 m0, s62, 0xa000
	s_nop 0
	global_load_lds_dwordx4 v224, s[48:49]
	s_add_u32 m0, s62, 0xc000
	s_nop 0
	global_load_lds_dwordx4 v225, s[48:49]
	s_add_u32 m0, s62, 0xe000
	s_nop 0
	global_load_lds_dwordx4 v226, s[48:49]
	s_branch .Lg2_entry
.Lg2_top:
	s_waitcnt lgkmcnt(0)
	s_waitcnt vmcnt(0)
	s_barrier
	s_xor_b32 s62, s62, 0x10000
	ds_read_b128 v[146:149], v180
	ds_read_b128 v[150:153], v180 offset:2048
	ds_read_b128 v[154:157], v180 offset:4096
	ds_read_b128 v[158:161], v180 offset:6144
	ds_read_b128 v[182:185], v215 offset:32768
	ds_read_b128 v[186:189], v215 offset:34816
	ds_read_b128 v[190:193], v215 offset:36864
	ds_read_b128 v[194:197], v215 offset:38912
	s_mov_b32 m0, s62
	v_mfma_f32_16x16x32_bf16 v[60:63], v[162:165], v[198:201], v[60:63]
	v_mfma_f32_16x16x32_bf16 v[56:59], v[162:165], v[202:205], v[56:59]
	global_load_lds_dwordx4 v178, s[48:49]
	s_add_u32 m0, s62, 0x2000
	v_mfma_f32_16x16x32_bf16 v[52:55], v[162:165], v[206:209], v[52:55]
	v_mfma_f32_16x16x32_bf16 v[44:47], v[162:165], v[210:213], v[44:47]
	global_load_lds_dwordx4 v221, s[48:49]
	s_add_u32 m0, s62, 0x4000
	v_mfma_f32_16x16x32_bf16 v[36:39], v[166:169], v[198:201], v[36:39]
	v_mfma_f32_16x16x32_bf16 v[32:35], v[166:169], v[202:205], v[32:35]
	global_load_lds_dwordx4 v222, s[48:49]
	s_add_u32 m0, s62, 0x6000
	v_mfma_f32_16x16x32_bf16 v[28:31], v[166:169], v[206:209], v[28:31]
	v_mfma_f32_16x16x32_bf16 v[24:27], v[166:169], v[210:213], v[24:27]
	global_load_lds_dwordx4 v223, s[48:49]
	s_add_u32 m0, s62, 0x8000
	v_mfma_f32_16x16x32_bf16 v[20:23], v[170:173], v[198:201], v[20:23]
	v_mfma_f32_16x16x32_bf16 v[16:19], v[170:173], v[202:205], v[16:19]
	global_load_lds_dwordx4 v179, s[48:49]
	s_add_u32 m0, s62, 0xa000
	v_mfma_f32_16x16x32_bf16 v[12:15], v[170:173], v[206:209], v[12:15]
	v_mfma_f32_16x16x32_bf16 v[8:11], v[170:173], v[210:213], v[8:11]
	global_load_lds_dwordx4 v224, s[48:49]
	s_add_u32 m0, s62, 0xc000
	v_mfma_f32_16x16x32_bf16 v[4:7], v[174:177], v[198:201], v[4:7]
	v_mfma_f32_16x16x32_bf16 v[0:3], v[174:177], v[202:205], v[0:3]
	global_load_lds_dwordx4 v225, s[48:49]
	s_add_u32 m0, s62, 0xe000
	v_mfma_f32_16x16x32_bf16 v[48:51], v[174:177], v[206:209], v[48:51]
	v_mfma_f32_16x16x32_bf16 v[40:43], v[174:177], v[210:213], v[40:43]
	global_load_lds_dwordx4 v226, s[48:49]
.Lg2_entry:
	ds_read_b128 v[162:165], v180 offset:8192
	ds_read_b128 v[166:169], v180 offset:10240
	ds_read_b128 v[170:173], v180 offset:12288
	ds_read_b128 v[174:177], v180 offset:14336
	s_waitcnt lgkmcnt(4)
	v_mfma_f32_16x16x32_bf16 v[124:127], v[146:149], v[182:185], v[124:127]
	v_mfma_f32_16x16x32_bf16 v[120:123], v[146:149], v[186:189], v[120:123]
	v_mfma_f32_16x16x32_bf16 v[116:119], v[146:149], v[190:193], v[116:119]
	v_mfma_f32_16x16x32_bf16 v[112:115], v[146:149], v[194:197], v[112:115]
	v_mfma_f32_16x16x32_bf16 v[108:111], v[150:153], v[182:185], v[108:111]
	v_mfma_f32_16x16x32_bf16 v[104:107], v[150:153], v[186:189], v[104:107]
	v_mfma_f32_16x16x32_bf16 v[100:103], v[150:153], v[190:193], v[100:103]
	v_mfma_f32_16x16x32_bf16 v[96:99], v[150:153], v[194:197], v[96:99]
	v_mfma_f32_16x16x32_bf16 v[92:95], v[154:157], v[182:185], v[92:95]
	v_mfma_f32_16x16x32_bf16 v[88:91], v[154:157], v[186:189], v[88:91]
	v_mfma_f32_16x16x32_bf16 v[84:87], v[154:157], v[190:193], v[84:87]
	v_mfma_f32_16x16x32_bf16 v[80:83], v[154:157], v[194:197], v[80:83]
	v_mfma_f32_16x16x32_bf16 v[76:79], v[158:161], v[182:185], v[76:79]
	v_mfma_f32_16x16x32_bf16 v[72:75], v[158:161], v[186:189], v[72:75]
	v_mfma_f32_16x16x32_bf16 v[68:71], v[158:161], v[190:193], v[68:71]
	v_mfma_f32_16x16x32_bf16 v[64:67], v[158:161], v[194:197], v[64:67]
	ds_read_b128 v[146:149], v214
	ds_read_b128 v[150:153], v214 offset:2048
	ds_read_b128 v[154:157], v214 offset:4096
	ds_read_b128 v[158:161], v214 offset:6144
	ds_read_b128 v[198:201], v216 offset:32768
	ds_read_b128 v[202:205], v216 offset:34816
	ds_read_b128 v[206:209], v216 offset:36864
	ds_read_b128 v[210:213], v216 offset:38912
	s_waitcnt lgkmcnt(8)
	v_mfma_f32_16x16x32_bf16 v[60:63], v[162:165], v[182:185], v[60:63]
	v_mfma_f32_16x16x32_bf16 v[56:59], v[162:165], v[186:189], v[56:59]
	v_mfma_f32_16x16x32_bf16 v[52:55], v[162:165], v[190:193], v[52:55]
	v_mfma_f32_16x16x32_bf16 v[44:47], v[162:165], v[194:197], v[44:47]
	v_mfma_f32_16x16x32_bf16 v[36:39], v[166:169], v[182:185], v[36:39]
	v_mfma_f32_16x16x32_bf16 v[32:35], v[166:169], v[186:189], v[32:35]
	v_mfma_f32_16x16x32_bf16 v[28:31], v[166:169], v[190:193], v[28:31]
	v_mfma_f32_16x16x32_bf16 v[24:27], v[166:169], v[194:197], v[24:27]
	v_mfma_f32_16x16x32_bf16 v[20:23], v[170:173], v[182:185], v[20:23]
	v_mfma_f32_16x16x32_bf16 v[16:19], v[170:173], v[186:189], v[16:19]
	v_mfma_f32_16x16x32_bf16 v[12:15], v[170:173], v[190:193], v[12:15]
	v_mfma_f32_16x16x32_bf16 v[8:11], v[170:173], v[194:197], v[8:11]
	v_mfma_f32_16x16x32_bf16 v[4:7], v[174:177], v[182:185], v[4:7]
	v_mfma_f32_16x16x32_bf16 v[0:3], v[174:177], v[186:189], v[0:3]
	v_mfma_f32_16x16x32_bf16 v[48:51], v[174:177], v[190:193], v[48:51]
	v_mfma_f32_16x16x32_bf16 v[40:43], v[174:177], v[194:197], v[40:43]
	ds_read_b128 v[162:165], v214 offset:8192
	ds_read_b128 v[166:169], v214 offset:10240
	ds_read_b128 v[170:173], v214 offset:12288
	ds_read_b128 v[174:177], v214 offset:14336
	s_waitcnt lgkmcnt(4)
	v_mfma_f32_16x16x32_bf16 v[124:127], v[146:149], v[198:201], v[124:127]
	v_mfma_f32_16x16x32_bf16 v[120:123], v[146:149], v[202:205], v[120:123]
	v_mfma_f32_16x16x32_bf16 v[116:119], v[146:149], v[206:209], v[116:119]
	v_mfma_f32_16x16x32_bf16 v[112:115], v[146:149], v[210:213], v[112:115]
	v_mfma_f32_16x16x32_bf16 v[108:111], v[150:153], v[198:201], v[108:111]
	v_mfma_f32_16x16x32_bf16 v[104:107], v[150:153], v[202:205], v[104:107]
	v_mfma_f32_16x16x32_bf16 v[100:103], v[150:153], v[206:209], v[100:103]
	v_mfma_f32_16x16x32_bf16 v[96:99], v[150:153], v[210:213], v[96:99]
	v_mfma_f32_16x16x32_bf16 v[92:95], v[154:157], v[198:201], v[92:95]
	v_mfma_f32_16x16x32_bf16 v[88:91], v[154:157], v[202:205], v[88:91]
	v_mfma_f32_16x16x32_bf16 v[84:87], v[154:157], v[206:209], v[84:87]
	v_mfma_f32_16x16x32_bf16 v[80:83], v[154:157], v[210:213], v[80:83]
	v_mfma_f32_16x16x32_bf16 v[76:79], v[158:161], v[198:201], v[76:79]
	v_mfma_f32_16x16x32_bf16 v[72:75], v[158:161], v[202:205], v[72:75]
	v_mfma_f32_16x16x32_bf16 v[68:71], v[158:161], v[206:209], v[68:71]
	v_mfma_f32_16x16x32_bf16 v[64:67], v[158:161], v[210:213], v[64:67]
	s_add_u32 s48, s48, 0x80
	s_addc_u32 s49, s49, 0
	s_add_i32 s47, s47, 1
	s_cmp_lt_u32 s47, 15
	s_cbranch_scc0 .Lg2_last
	s_waitcnt lgkmcnt(0)
	s_waitcnt vmcnt(0)
	s_barrier
	s_xor_b32 s62, s62, 0x10000
	ds_read_b128 v[146:149], v217
	ds_read_b128 v[150:153], v217 offset:2048
	ds_read_b128 v[154:157], v217 offset:4096
	ds_read_b128 v[158:161], v217 offset:6144
	ds_read_b128 v[182:185], v219 offset:32768
	ds_read_b128 v[186:189], v219 offset:34816
	ds_read_b128 v[190:193], v219 offset:36864
	ds_read_b128 v[194:197], v219 offset:38912
	s_mov_b32 m0, s62
	v_mfma_f32_16x16x32_bf16 v[60:63], v[162:165], v[198:201], v[60:63]
	v_mfma_f32_16x16x32_bf16 v[56:59], v[162:165], v[202:205], v[56:59]
	global_load_lds_dwordx4 v178, s[48:49]
	s_add_u32 m0, s62, 0x2000
	v_mfma_f32_16x16x32_bf16 v[52:55], v[162:165], v[206:209], v[52:55]
	v_mfma_f32_16x16x32_bf16 v[44:47], v[162:165], v[210:213], v[44:47]
	global_load_lds_dwordx4 v221, s[48:49]
	s_add_u32 m0, s62, 0x4000
	v_mfma_f32_16x16x32_bf16 v[36:39], v[166:169], v[198:201], v[36:39]
	v_mfma_f32_16x16x32_bf16 v[32:35], v[166:169], v[202:205], v[32:35]
	global_load_lds_dwordx4 v222, s[48:49]
	s_add_u32 m0, s62, 0x6000
	v_mfma_f32_16x16x32_bf16 v[28:31], v[166:169], v[206:209], v[28:31]
	v_mfma_f32_16x16x32_bf16 v[24:27], v[166:169], v[210:213], v[24:27]
	global_load_lds_dwordx4 v223, s[48:49]
	s_add_u32 m0, s62, 0x8000
	v_mfma_f32_16x16x32_bf16 v[20:23], v[170:173], v[198:201], v[20:23]
	v_mfma_f32_16x16x32_bf16 v[16:19], v[170:173], v[202:205], v[16:19]
	global_load_lds_dwordx4 v179, s[48:49]
	s_add_u32 m0, s62, 0xa000
	v_mfma_f32_16x16x32_bf16 v[12:15], v[170:173], v[206:209], v[12:15]
	v_mfma_f32_16x16x32_bf16 v[8:11], v[170:173], v[210:213], v[8:11]
	global_load_lds_dwordx4 v224, s[48:49]
	s_add_u32 m0, s62, 0xc000
	v_mfma_f32_16x16x32_bf16 v[4:7], v[174:177], v[198:201], v[4:7]
	v_mfma_f32_16x16x32_bf16 v[0:3], v[174:177], v[202:205], v[0:3]
	global_load_lds_dwordx4 v225, s[48:49]
	s_add_u32 m0, s62, 0xe000
	v_mfma_f32_16x16x32_bf16 v[48:51], v[174:177], v[206:209], v[48:51]
	v_mfma_f32_16x16x32_bf16 v[40:43], v[174:177], v[210:213], v[40:43]
	global_load_lds_dwordx4 v226, s[48:49]
	ds_read_b128 v[162:165], v217 offset:8192
	ds_read_b128 v[166:169], v217 offset:10240
	ds_read_b128 v[170:173], v217 offset:12288
	ds_read_b128 v[174:177], v217 offset:14336
	s_waitcnt lgkmcnt(4)
	v_mfma_f32_16x16x32_bf16 v[124:127], v[146:149], v[182:185], v[124:127]
	v_mfma_f32_16x16x32_bf16 v[120:123], v[146:149], v[186:189], v[120:123]
	v_mfma_f32_16x16x32_bf16 v[116:119], v[146:149], v[190:193], v[116:119]
	v_mfma_f32_16x16x32_bf16 v[112:115], v[146:149], v[194:197], v[112:115]
	v_mfma_f32_16x16x32_bf16 v[108:111], v[150:153], v[182:185], v[108:111]
	v_mfma_f32_16x16x32_bf16 v[104:107], v[150:153], v[186:189], v[104:107]
	v_mfma_f32_16x16x32_bf16 v[100:103], v[150:153], v[190:193], v[100:103]
	v_mfma_f32_16x16x32_bf16 v[96:99], v[150:153], v[194:197], v[96:99]
	v_mfma_f32_16x16x32_bf16 v[92:95], v[154:157], v[182:185], v[92:95]
	v_mfma_f32_16x16x32_bf16 v[88:91], v[154:157], v[186:189], v[88:91]
	v_mfma_f32_16x16x32_bf16 v[84:87], v[154:157], v[190:193], v[84:87]
	v_mfma_f32_16x16x32_bf16 v[80:83], v[154:157], v[194:197], v[80:83]
	v_mfma_f32_16x16x32_bf16 v[76:79], v[158:161], v[182:185], v[76:79]
	v_mfma_f32_16x16x32_bf16 v[72:75], v[158:161], v[186:189], v[72:75]
	v_mfma_f32_16x16x32_bf16 v[68:71], v[158:161], v[190:193], v[68:71]
	v_mfma_f32_16x16x32_bf16 v[64:67], v[158:161], v[194:197], v[64:67]
	ds_read_b128 v[146:149], v218
	ds_read_b128 v[150:153], v218 offset:2048
	ds_read_b128 v[154:157], v218 offset:4096
	ds_read_b128 v[158:161], v218 offset:6144
	ds_read_b128 v[198:201], v220 offset:32768
	ds_read_b128 v[202:205], v220 offset:34816
	ds_read_b128 v[206:209], v220 offset:36864
	ds_read_b128 v[210:213], v220 offset:38912
	s_waitcnt lgkmcnt(8)
	v_mfma_f32_16x16x32_bf16 v[60:63], v[162:165], v[182:185], v[60:63]
	v_mfma_f32_16x16x32_bf16 v[56:59], v[162:165], v[186:189], v[56:59]
	v_mfma_f32_16x16x32_bf16 v[52:55], v[162:165], v[190:193], v[52:55]
	v_mfma_f32_16x16x32_bf16 v[44:47], v[162:165], v[194:197], v[44:47]
	v_mfma_f32_16x16x32_bf16 v[36:39], v[166:169], v[182:185], v[36:39]
	v_mfma_f32_16x16x32_bf16 v[32:35], v[166:169], v[186:189], v[32:35]
	v_mfma_f32_16x16x32_bf16 v[28:31], v[166:169], v[190:193], v[28:31]
	v_mfma_f32_16x16x32_bf16 v[24:27], v[166:169], v[194:197], v[24:27]
	v_mfma_f32_16x16x32_bf16 v[20:23], v[170:173], v[182:185], v[20:23]
	v_mfma_f32_16x16x32_bf16 v[16:19], v[170:173], v[186:189], v[16:19]
	v_mfma_f32_16x16x32_bf16 v[12:15], v[170:173], v[190:193], v[12:15]
	v_mfma_f32_16x16x32_bf16 v[8:11], v[170:173], v[194:197], v[8:11]
	v_mfma_f32_16x16x32_bf16 v[4:7], v[174:177], v[182:185], v[4:7]
	v_mfma_f32_16x16x32_bf16 v[0:3], v[174:177], v[186:189], v[0:3]
	v_mfma_f32_16x16x32_bf16 v[48:51], v[174:177], v[190:193], v[48:51]
	v_mfma_f32_16x16x32_bf16 v[40:43], v[174:177], v[194:197], v[40:43]
	ds_read_b128 v[162:165], v218 offset:8192
	ds_read_b128 v[166:169], v218 offset:10240
	ds_read_b128 v[170:173], v218 offset:12288
	ds_read_b128 v[174:177], v218 offset:14336
	s_waitcnt lgkmcnt(4)
	v_mfma_f32_16x16x32_bf16 v[124:127], v[146:149], v[198:201], v[124:127]
	v_mfma_f32_16x16x32_bf16 v[120:123], v[146:149], v[202:205], v[120:123]
	v_mfma_f32_16x16x32_bf16 v[116:119], v[146:149], v[206:209], v[116:119]
	v_mfma_f32_16x16x32_bf16 v[112:115], v[146:149], v[210:213], v[112:115]
	v_mfma_f32_16x16x32_bf16 v[108:111], v[150:153], v[198:201], v[108:111]
	v_mfma_f32_16x16x32_bf16 v[104:107], v[150:153], v[202:205], v[104:107]
	v_mfma_f32_16x16x32_bf16 v[100:103], v[150:153], v[206:209], v[100:103]
	v_mfma_f32_16x16x32_bf16 v[96:99], v[150:153], v[210:213], v[96:99]
	v_mfma_f32_16x16x32_bf16 v[92:95], v[154:157], v[198:201], v[92:95]
	v_mfma_f32_16x16x32_bf16 v[88:91], v[154:157], v[202:205], v[88:91]
	v_mfma_f32_16x16x32_bf16 v[84:87], v[154:157], v[206:209], v[84:87]
	v_mfma_f32_16x16x32_bf16 v[80:83], v[154:157], v[210:213], v[80:83]
	v_mfma_f32_16x16x32_bf16 v[76:79], v[158:161], v[198:201], v[76:79]
	v_mfma_f32_16x16x32_bf16 v[72:75], v[158:161], v[202:205], v[72:75]
	v_mfma_f32_16x16x32_bf16 v[68:71], v[158:161], v[206:209], v[68:71]
	v_mfma_f32_16x16x32_bf16 v[64:67], v[158:161], v[210:213], v[64:67]
	s_add_u32 s48, s48, 0x80
	s_addc_u32 s49, s49, 0
	s_add_i32 s47, s47, 1
	s_branch .Lg2_top

.LBB0_746:
	s_ashr_i32 s20, s60, 2
	v_mov_b32_e32 v6, v181
	s_and_b32 s6, s60, 7
	s_and_b32 s51, s20, -8
	s_or_b32 s46, s51, s6
	v_lshrrev_b32_e32 v7, 4, v6
	v_lshlrev_b32_e32 v1, 6, v6
	v_xor_b32_e32 v0, v7, v6
	v_and_b32_e32 v8, 0x3c0, v1
	v_lshlrev_b32_e32 v1, 8, v6
	s_ashr_i32 s47, s46, 31
	v_lshlrev_b32_e32 v0, 3, v0
	v_and_b32_e32 v1, 0xfffff800, v1
	s_and_b32 s50, s55, 7
	s_bfe_u32 s6, s60, 0x20003
	s_lshl_b64 s[20:21], s[46:47], 20
	v_and_or_b32 v0, v0, 56, v1
	s_add_u32 s20, s3, s20
	v_ashrrev_i32_e32 v1, 31, v0
	s_addc_u32 s21, s52, s21
	v_lshlrev_b64 v[0:1], 1, v[0:1]
	v_lshl_add_u32 v134, v6, 4, 0
	v_lshl_add_u64 v[2:3], s[20:21], 0, v[0:1]
	v_readfirstlane_b32 s20, v134
	v_add_u32_e32 v9, 0x2000, v134
	s_mov_b32 m0, s20
	v_readfirstlane_b32 s20, v9
	v_add_u32_e32 v9, 0x4000, v134
	s_waitcnt vmcnt(63) expcnt(7) lgkmcnt(15)
	s_barrier
	global_load_lds_dwordx4 v[2:3], off
	v_lshl_add_u64 v[4:5], v[2:3], 0, s[8:9]
	s_mov_b32 m0, s20
	v_readfirstlane_b32 s20, v9
	global_load_lds_dwordx4 v[4:5], off
	v_lshl_add_u64 v[4:5], v[2:3], 0, s[10:11]
	s_mov_b32 m0, s20
	s_lshl_b32 s47, s6, 20
	global_load_lds_dwordx4 v[4:5], off
	v_add_u32_e32 v4, 0x6000, v134
	s_add_u32 s48, s53, s47
	v_readfirstlane_b32 s20, v4
	v_add_u32_e32 v4, 0x8000, v134
	s_addc_u32 s49, s54, 0
	v_lshl_add_u64 v[2:3], v[2:3], 0, s[12:13]
	s_mov_b32 m0, s20
	v_readfirstlane_b32 s20, v4
	v_add_u32_e32 v9, 0xa000, v134
	global_load_lds_dwordx4 v[2:3], off
	v_lshl_add_u64 v[2:3], s[48:49], 0, v[0:1]
	s_mov_b32 m0, s20
	v_readfirstlane_b32 s20, v9
	v_add_u32_e32 v9, 0xc000, v134
	global_load_lds_dwordx4 v[2:3], off
	v_lshl_add_u64 v[4:5], v[2:3], 0, s[8:9]
	s_mov_b32 m0, s20
	v_readfirstlane_b32 s20, v9
	global_load_lds_dwordx4 v[4:5], off
	v_lshl_add_u64 v[4:5], v[2:3], 0, s[10:11]
	s_mov_b32 m0, s20
	v_lshl_add_u64 v[2:3], v[2:3], 0, s[12:13]
	global_load_lds_dwordx4 v[4:5], off
	v_add_u32_e32 v4, 0xe000, v134
	v_mov_b32_e32 v36, 0
	v_readfirstlane_b32 s20, v4
	s_mov_b32 m0, s20
	v_ashrrev_i32_e32 v4, 6, v6
	global_load_lds_dwordx4 v[2:3], off
	s_or_b32 s20, s51, s50
	v_lshrrev_b32_e32 v5, 30, v4
	s_ashr_i32 s21, s20, 31
	v_add_u32_e32 v5, v4, v5
	s_lshl_b64 s[20:21], s[20:21], 20
	v_bfe_u32 v2, v6, 4, 2
	v_bfe_u32 v3, v6, 1, 3
	v_and_b32_e32 v6, 0x7fffc, v5
	s_add_u32 s20, s34, s20
	v_sub_u32_e32 v4, v4, v6
	s_addc_u32 s21, s35, s21
	v_lshlrev_b32_e32 v136, 13, v4
	v_bitop3_b32 v4, v7, v3, 3 bitop3:0x6c
	v_bitop3_b32 v2, v2, v3, 4 bitop3:0x36
	v_lshl_add_u64 v[130:131], s[20:21], 0, v[0:1]
	s_add_u32 s20, s34, s47
	v_lshlrev_b32_e32 v5, 12, v5
	v_lshlrev_b32_e32 v4, 3, v4
	v_lshlrev_b32_e32 v2, 3, v2
	s_addc_u32 s21, s35, 0
	v_and_b32_e32 v135, 0xffffc000, v5
	v_lshl_add_u64 v[132:133], s[20:21], 0, v[0:1]
	s_mov_b64 s[48:49], 0
	v_lshlrev_b32_e32 v137, 1, v8
	v_lshlrev_b32_e32 v138, 1, v4
	v_lshlrev_b32_e32 v139, 1, v2
	s_mov_b32 s61, 0
	s_mov_b32 s47, 0
	v_mov_b32_e32 v37, v36
	v_mov_b32_e32 v38, v36
	v_mov_b32_e32 v39, v36
	v_mov_b32_e32 v40, v36
	v_mov_b32_e32 v41, v36
	v_mov_b32_e32 v42, v36
	v_mov_b32_e32 v43, v36
	v_mov_b32_e32 v0, v36
	v_mov_b32_e32 v1, v36
	v_mov_b32_e32 v2, v36
	v_mov_b32_e32 v3, v36
	v_mov_b32_e32 v4, v36
	v_mov_b32_e32 v5, v36
	v_mov_b32_e32 v6, v36
	v_mov_b32_e32 v7, v36
	v_mov_b32_e32 v8, v36
	v_mov_b32_e32 v9, v36
	v_mov_b32_e32 v10, v36
	v_mov_b32_e32 v11, v36
	v_mov_b32_e32 v12, v36
	v_mov_b32_e32 v13, v36
	v_mov_b32_e32 v14, v36
	v_mov_b32_e32 v15, v36
	v_mov_b32_e32 v16, v36
	v_mov_b32_e32 v17, v36
	v_mov_b32_e32 v18, v36
	v_mov_b32_e32 v19, v36
	v_mov_b32_e32 v20, v36
	v_mov_b32_e32 v21, v36
	v_mov_b32_e32 v22, v36
	v_mov_b32_e32 v23, v36
	v_mov_b32_e32 v24, v36
	v_mov_b32_e32 v25, v36
	v_mov_b32_e32 v26, v36
	v_mov_b32_e32 v27, v36
	v_mov_b32_e32 v28, v36
	v_mov_b32_e32 v29, v36
	v_mov_b32_e32 v30, v36
	v_mov_b32_e32 v31, v36
	v_mov_b32_e32 v32, v36
	v_mov_b32_e32 v33, v36
	v_mov_b32_e32 v34, v36
	v_mov_b32_e32 v35, v36
	v_mov_b32_e32 v44, v36
	v_mov_b32_e32 v45, v36
	v_mov_b32_e32 v46, v36
	v_mov_b32_e32 v47, v36
	v_mov_b32_e32 v48, v36
	v_mov_b32_e32 v49, v36
	v_mov_b32_e32 v50, v36
	v_mov_b32_e32 v51, v36
	v_mov_b32_e32 v52, v36
	v_mov_b32_e32 v53, v36
	v_mov_b32_e32 v54, v36
	v_mov_b32_e32 v55, v36
	v_mov_b32_e32 v56, v36
	v_mov_b32_e32 v57, v36
	v_mov_b32_e32 v58, v36
	v_mov_b32_e32 v59, v36
	v_mov_b32_e32 v60, v36
	v_mov_b32_e32 v61, v36
	v_mov_b32_e32 v62, v36
	v_mov_b32_e32 v63, v36
	v_mov_b32_e32 v64, v36
	v_mov_b32_e32 v65, v36
	v_mov_b32_e32 v66, v36
	v_mov_b32_e32 v67, v36
	v_mov_b32_e32 v68, v36
	v_mov_b32_e32 v69, v36
	v_mov_b32_e32 v70, v36
	v_mov_b32_e32 v71, v36
	v_mov_b32_e32 v72, v36
	v_mov_b32_e32 v73, v36
	v_mov_b32_e32 v74, v36
	v_mov_b32_e32 v75, v36
	v_mov_b32_e32 v76, v36
	v_mov_b32_e32 v77, v36
	v_mov_b32_e32 v78, v36
	v_mov_b32_e32 v79, v36
	v_mov_b32_e32 v80, v36
	v_mov_b32_e32 v81, v36
	v_mov_b32_e32 v82, v36
	v_mov_b32_e32 v83, v36
	v_mov_b32_e32 v84, v36
	v_mov_b32_e32 v85, v36
	v_mov_b32_e32 v86, v36
	v_mov_b32_e32 v87, v36
	v_mov_b32_e32 v88, v36
	v_mov_b32_e32 v89, v36
	v_mov_b32_e32 v90, v36
	v_mov_b32_e32 v91, v36
	v_mov_b32_e32 v92, v36
	v_mov_b32_e32 v93, v36
	v_mov_b32_e32 v94, v36
	v_mov_b32_e32 v95, v36
	v_mov_b32_e32 v96, v36
	v_mov_b32_e32 v97, v36
	v_mov_b32_e32 v98, v36
	v_mov_b32_e32 v99, v36
	v_mov_b32_e32 v100, v36
	v_mov_b32_e32 v101, v36
	v_mov_b32_e32 v102, v36
	v_mov_b32_e32 v103, v36
	v_mov_b32_e32 v104, v36
	v_mov_b32_e32 v105, v36
	v_mov_b32_e32 v106, v36
	v_mov_b32_e32 v107, v36
	v_mov_b32_e32 v108, v36
	v_mov_b32_e32 v109, v36
	v_mov_b32_e32 v110, v36
	v_mov_b32_e32 v111, v36
	v_mov_b32_e32 v112, v36
	v_mov_b32_e32 v113, v36
	v_mov_b32_e32 v114, v36
	v_mov_b32_e32 v115, v36
	v_mov_b32_e32 v116, v36
	v_mov_b32_e32 v117, v36
	v_mov_b32_e32 v118, v36
	v_mov_b32_e32 v119, v36
	v_mov_b32_e32 v120, v36
	v_mov_b32_e32 v121, v36
	v_mov_b32_e32 v122, v36
	v_mov_b32_e32 v123, v36
	v_mov_b32_e32 v124, v36
	v_mov_b32_e32 v125, v36
	v_mov_b32_e32 v126, v36
	v_mov_b32_e32 v127, v36
	s_waitcnt vmcnt(0) lgkmcnt(0)
	s_barrier
	v_add3_u32 v141, v135, v137, v138
	v_add3_u32 v210, v136, v137, v138
	v_add3_u32 v180, v135, v137, v139
	v_add3_u32 v211, v136, v137, v139
	v_readfirstlane_b32 s61, v134
	ds_read_b128 v[142:145], v141
	ds_read_b128 v[146:149], v141 offset:2048
	ds_read_b128 v[150:153], v141 offset:4096
	ds_read_b128 v[154:157], v141 offset:6144
	ds_read_b128 v[174:177], v210 offset:32768
	ds_read_b128 v[182:185], v210 offset:34816
	ds_read_b128 v[186:189], v210 offset:36864
	ds_read_b128 v[190:193], v210 offset:38912
	s_mov_b32 s47, 0
	s_mov_b64 s[48:49], s[34:35]
	v_subrev_u32_e32 v178, s34, v130
	v_subrev_u32_e32 v179, s34, v132
	v_xor_b32_e32 v212, 0x10000, v141
	v_xor_b32_e32 v213, 0x10000, v180
	v_xor_b32_e32 v214, 0x10000, v210
	v_xor_b32_e32 v215, 0x10000, v211
	s_add_u32 s61, s61, 0x10000
	v_add_u32_e32 v216, s16, v178
	v_add_u32_e32 v217, s18, v178
	v_add_u32_e32 v218, s22, v178
	v_add_u32_e32 v178, s14, v178
	v_add_u32_e32 v219, s40, v179
	v_add_u32_e32 v220, s42, v179
	v_add_u32_e32 v221, s44, v179
	v_add_u32_e32 v179, s36, v179
	s_mov_b32 m0, s61
	s_nop 0
	global_load_lds_dwordx4 v178, s[48:49]
	s_add_u32 m0, s61, 0x2000
	s_nop 0
	global_load_lds_dwordx4 v216, s[48:49]
	s_add_u32 m0, s61, 0x4000
	s_nop 0
	global_load_lds_dwordx4 v217, s[48:49]
	s_add_u32 m0, s61, 0x6000
	s_nop 0
	global_load_lds_dwordx4 v218, s[48:49]
	s_add_u32 m0, s61, 0x8000
	s_nop 0
	global_load_lds_dwordx4 v179, s[48:49]
	s_add_u32 m0, s61, 0xa000
	s_nop 0
	global_load_lds_dwordx4 v219, s[48:49]
	s_add_u32 m0, s61, 0xc000
	s_nop 0
	global_load_lds_dwordx4 v220, s[48:49]
	s_add_u32 m0, s61, 0xe000
	s_nop 0
	global_load_lds_dwordx4 v221, s[48:49]
	s_branch .Lg7_entry
.Lg7_top:
	s_waitcnt lgkmcnt(0)
	s_waitcnt vmcnt(0)
	s_barrier
	s_xor_b32 s61, s61, 0x10000
	ds_read_b128 v[142:145], v141
	ds_read_b128 v[146:149], v141 offset:2048
	ds_read_b128 v[150:153], v141 offset:4096
	ds_read_b128 v[154:157], v141 offset:6144
	ds_read_b128 v[174:177], v210 offset:32768
	ds_read_b128 v[182:185], v210 offset:34816
	ds_read_b128 v[186:189], v210 offset:36864
	ds_read_b128 v[190:193], v210 offset:38912
	s_mov_b32 m0, s61
	v_mfma_f32_16x16x32_bf16 v[60:63], v[158:161], v[194:197], v[60:63]
	v_mfma_f32_16x16x32_bf16 v[56:59], v[158:161], v[198:201], v[56:59]
	global_load_lds_dwordx4 v178, s[48:49]
	s_add_u32 m0, s61, 0x2000
	v_mfma_f32_16x16x32_bf16 v[52:55], v[158:161], v[202:205], v[52:55]
	v_mfma_f32_16x16x32_bf16 v[48:51], v[158:161], v[206:209], v[48:51]
	global_load_lds_dwordx4 v216, s[48:49]
	s_add_u32 m0, s61, 0x4000
	v_mfma_f32_16x16x32_bf16 v[44:47], v[162:165], v[194:197], v[44:47]
	v_mfma_f32_16x16x32_bf16 v[32:35], v[162:165], v[198:201], v[32:35]
	global_load_lds_dwordx4 v217, s[48:49]
	s_add_u32 m0, s61, 0x6000
	v_mfma_f32_16x16x32_bf16 v[28:31], v[162:165], v[202:205], v[28:31]
	v_mfma_f32_16x16x32_bf16 v[24:27], v[162:165], v[206:209], v[24:27]
	global_load_lds_dwordx4 v218, s[48:49]
	s_add_u32 m0, s61, 0x8000
	v_mfma_f32_16x16x32_bf16 v[20:23], v[166:169], v[194:197], v[20:23]
	v_mfma_f32_16x16x32_bf16 v[16:19], v[166:169], v[198:201], v[16:19]
	global_load_lds_dwordx4 v179, s[48:49]
	s_add_u32 m0, s61, 0xa000
	v_mfma_f32_16x16x32_bf16 v[12:15], v[166:169], v[202:205], v[12:15]
	v_mfma_f32_16x16x32_bf16 v[8:11], v[166:169], v[206:209], v[8:11]
	global_load_lds_dwordx4 v219, s[48:49]
	s_add_u32 m0, s61, 0xc000
	v_mfma_f32_16x16x32_bf16 v[4:7], v[170:173], v[194:197], v[4:7]
	v_mfma_f32_16x16x32_bf16 v[0:3], v[170:173], v[198:201], v[0:3]
	global_load_lds_dwordx4 v220, s[48:49]
	s_add_u32 m0, s61, 0xe000
	v_mfma_f32_16x16x32_bf16 v[40:43], v[170:173], v[202:205], v[40:43]
	v_mfma_f32_16x16x32_bf16 v[36:39], v[170:173], v[206:209], v[36:39]
	global_load_lds_dwordx4 v221, s[48:49]
.Lg7_entry:
	ds_read_b128 v[158:161], v141 offset:8192
	ds_read_b128 v[162:165], v141 offset:10240
	ds_read_b128 v[166:169], v141 offset:12288
	ds_read_b128 v[170:173], v141 offset:14336
	s_waitcnt lgkmcnt(4)
	v_mfma_f32_16x16x32_bf16 v[124:127], v[142:145], v[174:177], v[124:127]
	v_mfma_f32_16x16x32_bf16 v[120:123], v[142:145], v[182:185], v[120:123]
	v_mfma_f32_16x16x32_bf16 v[116:119], v[142:145], v[186:189], v[116:119]
	v_mfma_f32_16x16x32_bf16 v[112:115], v[142:145], v[190:193], v[112:115]
	v_mfma_f32_16x16x32_bf16 v[108:111], v[146:149], v[174:177], v[108:111]
	v_mfma_f32_16x16x32_bf16 v[104:107], v[146:149], v[182:185], v[104:107]
	v_mfma_f32_16x16x32_bf16 v[100:103], v[146:149], v[186:189], v[100:103]
	v_mfma_f32_16x16x32_bf16 v[96:99], v[146:149], v[190:193], v[96:99]
	v_mfma_f32_16x16x32_bf16 v[92:95], v[150:153], v[174:177], v[92:95]
	v_mfma_f32_16x16x32_bf16 v[88:91], v[150:153], v[182:185], v[88:91]
	v_mfma_f32_16x16x32_bf16 v[84:87], v[150:153], v[186:189], v[84:87]
	v_mfma_f32_16x16x32_bf16 v[80:83], v[150:153], v[190:193], v[80:83]
	v_mfma_f32_16x16x32_bf16 v[76:79], v[154:157], v[174:177], v[76:79]
	v_mfma_f32_16x16x32_bf16 v[72:75], v[154:157], v[182:185], v[72:75]
	v_mfma_f32_16x16x32_bf16 v[68:71], v[154:157], v[186:189], v[68:71]
	v_mfma_f32_16x16x32_bf16 v[64:67], v[154:157], v[190:193], v[64:67]
	ds_read_b128 v[142:145], v180
	ds_read_b128 v[146:149], v180 offset:2048
	ds_read_b128 v[150:153], v180 offset:4096
	ds_read_b128 v[154:157], v180 offset:6144
	ds_read_b128 v[194:197], v211 offset:32768
	ds_read_b128 v[198:201], v211 offset:34816
	ds_read_b128 v[202:205], v211 offset:36864
	ds_read_b128 v[206:209], v211 offset:38912
	s_waitcnt lgkmcnt(8)
	v_mfma_f32_16x16x32_bf16 v[60:63], v[158:161], v[174:177], v[60:63]
	v_mfma_f32_16x16x32_bf16 v[56:59], v[158:161], v[182:185], v[56:59]
	v_mfma_f32_16x16x32_bf16 v[52:55], v[158:161], v[186:189], v[52:55]
	v_mfma_f32_16x16x32_bf16 v[48:51], v[158:161], v[190:193], v[48:51]
	v_mfma_f32_16x16x32_bf16 v[44:47], v[162:165], v[174:177], v[44:47]
	v_mfma_f32_16x16x32_bf16 v[32:35], v[162:165], v[182:185], v[32:35]
	v_mfma_f32_16x16x32_bf16 v[28:31], v[162:165], v[186:189], v[28:31]
	v_mfma_f32_16x16x32_bf16 v[24:27], v[162:165], v[190:193], v[24:27]
	v_mfma_f32_16x16x32_bf16 v[20:23], v[166:169], v[174:177], v[20:23]
	v_mfma_f32_16x16x32_bf16 v[16:19], v[166:169], v[182:185], v[16:19]
	v_mfma_f32_16x16x32_bf16 v[12:15], v[166:169], v[186:189], v[12:15]
	v_mfma_f32_16x16x32_bf16 v[8:11], v[166:169], v[190:193], v[8:11]
	v_mfma_f32_16x16x32_bf16 v[4:7], v[170:173], v[174:177], v[4:7]
	v_mfma_f32_16x16x32_bf16 v[0:3], v[170:173], v[182:185], v[0:3]
	v_mfma_f32_16x16x32_bf16 v[40:43], v[170:173], v[186:189], v[40:43]
	v_mfma_f32_16x16x32_bf16 v[36:39], v[170:173], v[190:193], v[36:39]
	ds_read_b128 v[158:161], v180 offset:8192
	ds_read_b128 v[162:165], v180 offset:10240
	ds_read_b128 v[166:169], v180 offset:12288
	ds_read_b128 v[170:173], v180 offset:14336
	s_waitcnt lgkmcnt(4)
	v_mfma_f32_16x16x32_bf16 v[124:127], v[142:145], v[194:197], v[124:127]
	v_mfma_f32_16x16x32_bf16 v[120:123], v[142:145], v[198:201], v[120:123]
	v_mfma_f32_16x16x32_bf16 v[116:119], v[142:145], v[202:205], v[116:119]
	v_mfma_f32_16x16x32_bf16 v[112:115], v[142:145], v[206:209], v[112:115]
	v_mfma_f32_16x16x32_bf16 v[108:111], v[146:149], v[194:197], v[108:111]
	v_mfma_f32_16x16x32_bf16 v[104:107], v[146:149], v[198:201], v[104:107]
	v_mfma_f32_16x16x32_bf16 v[100:103], v[146:149], v[202:205], v[100:103]
	v_mfma_f32_16x16x32_bf16 v[96:99], v[146:149], v[206:209], v[96:99]
	v_mfma_f32_16x16x32_bf16 v[92:95], v[150:153], v[194:197], v[92:95]
	v_mfma_f32_16x16x32_bf16 v[88:91], v[150:153], v[198:201], v[88:91]
	v_mfma_f32_16x16x32_bf16 v[84:87], v[150:153], v[202:205], v[84:87]
	v_mfma_f32_16x16x32_bf16 v[80:83], v[150:153], v[206:209], v[80:83]
	v_mfma_f32_16x16x32_bf16 v[76:79], v[154:157], v[194:197], v[76:79]
	v_mfma_f32_16x16x32_bf16 v[72:75], v[154:157], v[198:201], v[72:75]
	v_mfma_f32_16x16x32_bf16 v[68:71], v[154:157], v[202:205], v[68:71]
	v_mfma_f32_16x16x32_bf16 v[64:67], v[154:157], v[206:209], v[64:67]
	s_add_u32 s48, s48, 0x80
	s_addc_u32 s49, s49, 0
	s_add_i32 s47, s47, 1
	s_cmp_lt_u32 s47, 31
	s_cbranch_scc0 .Lg7_last
	s_waitcnt lgkmcnt(0)
	s_waitcnt vmcnt(0)
	s_barrier
	s_xor_b32 s61, s61, 0x10000
	ds_read_b128 v[142:145], v212
	ds_read_b128 v[146:149], v212 offset:2048
	ds_read_b128 v[150:153], v212 offset:4096
	ds_read_b128 v[154:157], v212 offset:6144
	ds_read_b128 v[174:177], v214 offset:32768
	ds_read_b128 v[182:185], v214 offset:34816
	ds_read_b128 v[186:189], v214 offset:36864
	ds_read_b128 v[190:193], v214 offset:38912
	s_mov_b32 m0, s61
	v_mfma_f32_16x16x32_bf16 v[60:63], v[158:161], v[194:197], v[60:63]
	v_mfma_f32_16x16x32_bf16 v[56:59], v[158:161], v[198:201], v[56:59]
	global_load_lds_dwordx4 v178, s[48:49]
	s_add_u32 m0, s61, 0x2000
	v_mfma_f32_16x16x32_bf16 v[52:55], v[158:161], v[202:205], v[52:55]
	v_mfma_f32_16x16x32_bf16 v[48:51], v[158:161], v[206:209], v[48:51]
	global_load_lds_dwordx4 v216, s[48:49]
	s_add_u32 m0, s61, 0x4000
	v_mfma_f32_16x16x32_bf16 v[44:47], v[162:165], v[194:197], v[44:47]
	v_mfma_f32_16x16x32_bf16 v[32:35], v[162:165], v[198:201], v[32:35]
	global_load_lds_dwordx4 v217, s[48:49]
	s_add_u32 m0, s61, 0x6000
	v_mfma_f32_16x16x32_bf16 v[28:31], v[162:165], v[202:205], v[28:31]
	v_mfma_f32_16x16x32_bf16 v[24:27], v[162:165], v[206:209], v[24:27]
	global_load_lds_dwordx4 v218, s[48:49]
	s_add_u32 m0, s61, 0x8000
	v_mfma_f32_16x16x32_bf16 v[20:23], v[166:169], v[194:197], v[20:23]
	v_mfma_f32_16x16x32_bf16 v[16:19], v[166:169], v[198:201], v[16:19]
	global_load_lds_dwordx4 v179, s[48:49]
	s_add_u32 m0, s61, 0xa000
	v_mfma_f32_16x16x32_bf16 v[12:15], v[166:169], v[202:205], v[12:15]
	v_mfma_f32_16x16x32_bf16 v[8:11], v[166:169], v[206:209], v[8:11]
	global_load_lds_dwordx4 v219, s[48:49]
	s_add_u32 m0, s61, 0xc000
	v_mfma_f32_16x16x32_bf16 v[4:7], v[170:173], v[194:197], v[4:7]
	v_mfma_f32_16x16x32_bf16 v[0:3], v[170:173], v[198:201], v[0:3]
	global_load_lds_dwordx4 v220, s[48:49]
	s_add_u32 m0, s61, 0xe000
	v_mfma_f32_16x16x32_bf16 v[40:43], v[170:173], v[202:205], v[40:43]
	v_mfma_f32_16x16x32_bf16 v[36:39], v[170:173], v[206:209], v[36:39]
	global_load_lds_dwordx4 v221, s[48:49]
	ds_read_b128 v[158:161], v212 offset:8192
	ds_read_b128 v[162:165], v212 offset:10240
	ds_read_b128 v[166:169], v212 offset:12288
	ds_read_b128 v[170:173], v212 offset:14336
	s_waitcnt lgkmcnt(4)
	v_mfma_f32_16x16x32_bf16 v[124:127], v[142:145], v[174:177], v[124:127]
	v_mfma_f32_16x16x32_bf16 v[120:123], v[142:145], v[182:185], v[120:123]
	v_mfma_f32_16x16x32_bf16 v[116:119], v[142:145], v[186:189], v[116:119]
	v_mfma_f32_16x16x32_bf16 v[112:115], v[142:145], v[190:193], v[112:115]
	v_mfma_f32_16x16x32_bf16 v[108:111], v[146:149], v[174:177], v[108:111]
	v_mfma_f32_16x16x32_bf16 v[104:107], v[146:149], v[182:185], v[104:107]
	v_mfma_f32_16x16x32_bf16 v[100:103], v[146:149], v[186:189], v[100:103]
	v_mfma_f32_16x16x32_bf16 v[96:99], v[146:149], v[190:193], v[96:99]
	v_mfma_f32_16x16x32_bf16 v[92:95], v[150:153], v[174:177], v[92:95]
	v_mfma_f32_16x16x32_bf16 v[88:91], v[150:153], v[182:185], v[88:91]
	v_mfma_f32_16x16x32_bf16 v[84:87], v[150:153], v[186:189], v[84:87]
	v_mfma_f32_16x16x32_bf16 v[80:83], v[150:153], v[190:193], v[80:83]
	v_mfma_f32_16x16x32_bf16 v[76:79], v[154:157], v[174:177], v[76:79]
	v_mfma_f32_16x16x32_bf16 v[72:75], v[154:157], v[182:185], v[72:75]
	v_mfma_f32_16x16x32_bf16 v[68:71], v[154:157], v[186:189], v[68:71]
	v_mfma_f32_16x16x32_bf16 v[64:67], v[154:157], v[190:193], v[64:67]
	ds_read_b128 v[142:145], v213
	ds_read_b128 v[146:149], v213 offset:2048
	ds_read_b128 v[150:153], v213 offset:4096
	ds_read_b128 v[154:157], v213 offset:6144
	ds_read_b128 v[194:197], v215 offset:32768
	ds_read_b128 v[198:201], v215 offset:34816
	ds_read_b128 v[202:205], v215 offset:36864
	ds_read_b128 v[206:209], v215 offset:38912
	s_waitcnt lgkmcnt(8)
	v_mfma_f32_16x16x32_bf16 v[60:63], v[158:161], v[174:177], v[60:63]
	v_mfma_f32_16x16x32_bf16 v[56:59], v[158:161], v[182:185], v[56:59]
	v_mfma_f32_16x16x32_bf16 v[52:55], v[158:161], v[186:189], v[52:55]
	v_mfma_f32_16x16x32_bf16 v[48:51], v[158:161], v[190:193], v[48:51]
	v_mfma_f32_16x16x32_bf16 v[44:47], v[162:165], v[174:177], v[44:47]
	v_mfma_f32_16x16x32_bf16 v[32:35], v[162:165], v[182:185], v[32:35]
	v_mfma_f32_16x16x32_bf16 v[28:31], v[162:165], v[186:189], v[28:31]
	v_mfma_f32_16x16x32_bf16 v[24:27], v[162:165], v[190:193], v[24:27]
	v_mfma_f32_16x16x32_bf16 v[20:23], v[166:169], v[174:177], v[20:23]
	v_mfma_f32_16x16x32_bf16 v[16:19], v[166:169], v[182:185], v[16:19]
	v_mfma_f32_16x16x32_bf16 v[12:15], v[166:169], v[186:189], v[12:15]
	v_mfma_f32_16x16x32_bf16 v[8:11], v[166:169], v[190:193], v[8:11]
	v_mfma_f32_16x16x32_bf16 v[4:7], v[170:173], v[174:177], v[4:7]
	v_mfma_f32_16x16x32_bf16 v[0:3], v[170:173], v[182:185], v[0:3]
	v_mfma_f32_16x16x32_bf16 v[40:43], v[170:173], v[186:189], v[40:43]
	v_mfma_f32_16x16x32_bf16 v[36:39], v[170:173], v[190:193], v[36:39]
	ds_read_b128 v[158:161], v213 offset:8192
	ds_read_b128 v[162:165], v213 offset:10240
	ds_read_b128 v[166:169], v213 offset:12288
	ds_read_b128 v[170:173], v213 offset:14336
	s_waitcnt lgkmcnt(4)
	v_mfma_f32_16x16x32_bf16 v[124:127], v[142:145], v[194:197], v[124:127]
	v_mfma_f32_16x16x32_bf16 v[120:123], v[142:145], v[198:201], v[120:123]
	v_mfma_f32_16x16x32_bf16 v[116:119], v[142:145], v[202:205], v[116:119]
	v_mfma_f32_16x16x32_bf16 v[112:115], v[142:145], v[206:209], v[112:115]
	v_mfma_f32_16x16x32_bf16 v[108:111], v[146:149], v[194:197], v[108:111]
	v_mfma_f32_16x16x32_bf16 v[104:107], v[146:149], v[198:201], v[104:107]
	v_mfma_f32_16x16x32_bf16 v[100:103], v[146:149], v[202:205], v[100:103]
	v_mfma_f32_16x16x32_bf16 v[96:99], v[146:149], v[206:209], v[96:99]
	v_mfma_f32_16x16x32_bf16 v[92:95], v[150:153], v[194:197], v[92:95]
	v_mfma_f32_16x16x32_bf16 v[88:91], v[150:153], v[198:201], v[88:91]
	v_mfma_f32_16x16x32_bf16 v[84:87], v[150:153], v[202:205], v[84:87]
	v_mfma_f32_16x16x32_bf16 v[80:83], v[150:153], v[206:209], v[80:83]
	v_mfma_f32_16x16x32_bf16 v[76:79], v[154:157], v[194:197], v[76:79]
	v_mfma_f32_16x16x32_bf16 v[72:75], v[154:157], v[198:201], v[72:75]
	v_mfma_f32_16x16x32_bf16 v[68:71], v[154:157], v[202:205], v[68:71]
	v_mfma_f32_16x16x32_bf16 v[64:67], v[154:157], v[206:209], v[64:67]
	s_add_u32 s48, s48, 0x80
	s_addc_u32 s49, s49, 0
	s_add_i32 s47, s47, 1
	s_branch .Lg7_top

.LBB0_933:
	s_mul_hi_i32 s21, s70, 0x2e8ba2e9
	s_lshr_b32 s56, s21, 31
	s_ashr_i32 s71, s21, 4
	s_add_i32 s71, s71, s56
	s_and_b32 s20, s70, 7
	s_lshl_b32 s62, s71, 3
	s_or_b32 s58, s62, s20
	s_ashr_i32 s20, s70, 3
	s_mul_hi_i32 s21, s20, 0x2e8ba2e9
	v_mov_b32_e32 v6, v181
	s_lshr_b32 s56, s21, 31
	s_ashr_i32 s21, s21, 1
	s_add_i32 s21, s21, s56
	v_lshrrev_b32_e32 v7, 4, v6
	v_lshlrev_b32_e32 v1, 6, v6
	v_xor_b32_e32 v0, v7, v6
	v_and_b32_e32 v8, 0x3c0, v1
	v_lshlrev_b32_e32 v1, 7, v6
	s_mul_i32 s21, s21, 11
	s_ashr_i32 s59, s58, 31
	v_lshlrev_b32_e32 v0, 3, v0
	v_and_b32_e32 v1, 0xfffffc00, v1
	s_and_b32 s64, s69, 7
	s_sub_i32 s56, s20, s21
	s_lshl_b64 s[20:21], s[58:59], 19
	v_and_or_b32 v0, v0, 56, v1
	s_add_u32 s20, s3, s20
	v_ashrrev_i32_e32 v1, 31, v0
	s_addc_u32 s21, s66, s21
	v_lshlrev_b64 v[0:1], 1, v[0:1]
	v_lshl_add_u32 v130, v6, 4, 0
	v_lshl_add_u64 v[2:3], s[20:21], 0, v[0:1]
	v_readfirstlane_b32 s20, v130
	v_add_u32_e32 v9, 0x2000, v130
	s_mov_b32 m0, s20
	v_readfirstlane_b32 s20, v9
	v_add_u32_e32 v9, 0x4000, v130
	s_waitcnt vmcnt(63) expcnt(7) lgkmcnt(15)
	s_barrier
	global_load_lds_dwordx4 v[2:3], off
	v_lshl_add_u64 v[4:5], v[2:3], 0, s[14:15]
	s_mov_b32 m0, s20
	v_readfirstlane_b32 s20, v9
	global_load_lds_dwordx4 v[4:5], off
	v_lshl_add_u64 v[4:5], v[2:3], 0, s[16:17]
	s_mov_b32 m0, s20
	s_ashr_i32 s57, s56, 31
	global_load_lds_dwordx4 v[4:5], off
	v_add_u32_e32 v4, 0x6000, v130
	s_lshl_b64 s[60:61], s[56:57], 19
	v_readfirstlane_b32 s20, v4
	v_lshl_add_u64 v[2:3], v[2:3], 0, s[18:19]
	s_mov_b32 m0, s20
	s_add_u32 s60, s34, s60
	global_load_lds_dwordx4 v[2:3], off
	v_add_u32_e32 v2, 0x8000, v130
	s_addc_u32 s61, s35, s61
	v_readfirstlane_b32 s20, v2
	v_add_u32_e32 v4, 0xa000, v130
	v_lshl_add_u64 v[140:141], s[60:61], 0, v[0:1]
	s_mov_b32 m0, s20
	v_readfirstlane_b32 s20, v4
	v_add_u32_e32 v4, 0xc000, v130
	global_load_lds_dwordx4 v[140:141], off
	v_lshl_add_u64 v[2:3], v[140:141], 0, s[14:15]
	s_mov_b32 m0, s20
	v_readfirstlane_b32 s20, v4
	v_add_u32_e32 v4, 0xe000, v130
	global_load_lds_dwordx4 v[2:3], off
	v_lshl_add_u64 v[2:3], v[140:141], 0, s[16:17]
	s_mov_b32 m0, s20
	v_readfirstlane_b32 s20, v4
	global_load_lds_dwordx4 v[2:3], off
	v_lshl_add_u64 v[2:3], v[140:141], 0, s[18:19]
	s_mov_b32 m0, s20
	v_ashrrev_i32_e32 v4, 6, v6
	global_load_lds_dwordx4 v[2:3], off
	v_lshrrev_b32_e32 v5, 30, v4
	v_add_u32_e32 v5, v4, v5
	s_or_b32 s20, s62, s64
	v_bfe_u32 v2, v6, 4, 2
	v_bfe_u32 v3, v6, 1, 3
	v_and_b32_e32 v6, 0x7fffc, v5
	s_ashr_i32 s21, s20, 31
	v_sub_u32_e32 v4, v4, v6
	s_lshl_b64 s[20:21], s[20:21], 19
	v_lshlrev_b32_e32 v150, 13, v4
	v_bitop3_b32 v4, v7, v3, 3 bitop3:0x6c
	v_bitop3_b32 v2, v2, v3, 4 bitop3:0x36
	s_add_u32 s20, s34, s20
	v_lshlrev_b32_e32 v5, 12, v5
	v_lshlrev_b32_e32 v4, 3, v4
	v_lshlrev_b32_e32 v2, 3, v2
	s_addc_u32 s21, s35, s21
	v_and_b32_e32 v149, 0xffffc000, v5
	v_lshl_add_u64 v[142:143], s[20:21], 0, v[0:1]
	s_mov_b64 s[60:61], 0
	v_lshlrev_b32_e32 v151, 1, v8
	v_lshlrev_b32_e32 v152, 1, v4
	v_lshlrev_b32_e32 v153, 1, v2
	s_mov_b32 s59, 0
	s_mov_b32 s57, 0
	v_mov_b32_e32 v40, 0
	v_mov_b32_e32 v41, v131
	v_mov_b32_e32 v42, v131
	v_mov_b32_e32 v43, v131
	v_mov_b32_e32 v48, 0
	v_mov_b32_e32 v49, v131
	v_mov_b32_e32 v50, v131
	v_mov_b32_e32 v51, v131
	v_mov_b32_e32 v0, 0
	v_mov_b32_e32 v1, v131
	v_mov_b32_e32 v2, v131
	v_mov_b32_e32 v3, v131
	v_mov_b32_e32 v4, 0
	v_mov_b32_e32 v5, v131
	v_mov_b32_e32 v6, v131
	v_mov_b32_e32 v7, v131
	v_mov_b32_e32 v8, 0
	v_mov_b32_e32 v9, v131
	v_mov_b32_e32 v10, v131
	v_mov_b32_e32 v11, v131
	v_mov_b32_e32 v12, 0
	v_mov_b32_e32 v13, v131
	v_mov_b32_e32 v14, v131
	v_mov_b32_e32 v15, v131
	v_mov_b32_e32 v16, 0
	v_mov_b32_e32 v17, v131
	v_mov_b32_e32 v18, v131
	v_mov_b32_e32 v19, v131
	v_mov_b32_e32 v20, 0
	v_mov_b32_e32 v21, v131
	v_mov_b32_e32 v22, v131
	v_mov_b32_e32 v23, v131
	v_mov_b32_e32 v24, 0
	v_mov_b32_e32 v25, v131
	v_mov_b32_e32 v26, v131
	v_mov_b32_e32 v27, v131
	v_mov_b32_e32 v28, 0
	v_mov_b32_e32 v29, v131
	v_mov_b32_e32 v30, v131
	v_mov_b32_e32 v31, v131
	v_mov_b32_e32 v32, 0
	v_mov_b32_e32 v33, v131
	v_mov_b32_e32 v34, v131
	v_mov_b32_e32 v35, v131
	v_mov_b32_e32 v36, 0
	v_mov_b32_e32 v37, v131
	v_mov_b32_e32 v38, v131
	v_mov_b32_e32 v39, v131
	v_mov_b32_e32 v44, 0
	v_mov_b32_e32 v45, v131
	v_mov_b32_e32 v46, v131
	v_mov_b32_e32 v47, v131
	v_mov_b32_e32 v52, 0
	v_mov_b32_e32 v53, v131
	v_mov_b32_e32 v54, v131
	v_mov_b32_e32 v55, v131
	v_mov_b32_e32 v56, 0
	v_mov_b32_e32 v57, v131
	v_mov_b32_e32 v58, v131
	v_mov_b32_e32 v59, v131
	v_mov_b32_e32 v60, 0
	v_mov_b32_e32 v61, v131
	v_mov_b32_e32 v62, v131
	v_mov_b32_e32 v63, v131
	v_mov_b32_e32 v64, 0
	v_mov_b32_e32 v65, v131
	v_mov_b32_e32 v66, v131
	v_mov_b32_e32 v67, v131
	v_mov_b32_e32 v68, 0
	v_mov_b32_e32 v69, v131
	v_mov_b32_e32 v70, v131
	v_mov_b32_e32 v71, v131
	v_mov_b32_e32 v72, 0
	v_mov_b32_e32 v73, v131
	v_mov_b32_e32 v74, v131
	v_mov_b32_e32 v75, v131
	v_mov_b32_e32 v76, 0
	v_mov_b32_e32 v77, v131
	v_mov_b32_e32 v78, v131
	v_mov_b32_e32 v79, v131
	v_mov_b32_e32 v80, 0
	v_mov_b32_e32 v81, v131
	v_mov_b32_e32 v82, v131
	v_mov_b32_e32 v83, v131
	v_mov_b32_e32 v84, 0
	v_mov_b32_e32 v85, v131
	v_mov_b32_e32 v86, v131
	v_mov_b32_e32 v87, v131
	v_mov_b32_e32 v88, 0
	v_mov_b32_e32 v89, v131
	v_mov_b32_e32 v90, v131
	v_mov_b32_e32 v91, v131
	v_mov_b32_e32 v92, 0
	v_mov_b32_e32 v93, v131
	v_mov_b32_e32 v94, v131
	v_mov_b32_e32 v95, v131
	v_mov_b32_e32 v96, 0
	v_mov_b32_e32 v97, v131
	v_mov_b32_e32 v98, v131
	v_mov_b32_e32 v99, v131
	v_mov_b32_e32 v100, 0
	v_mov_b32_e32 v101, v131
	v_mov_b32_e32 v102, v131
	v_mov_b32_e32 v103, v131
	v_mov_b32_e32 v104, 0
	v_mov_b32_e32 v105, v131
	v_mov_b32_e32 v106, v131
	v_mov_b32_e32 v107, v131
	v_mov_b32_e32 v108, 0
	v_mov_b32_e32 v109, v131
	v_mov_b32_e32 v110, v131
	v_mov_b32_e32 v111, v131
	v_mov_b32_e32 v112, 0
	v_mov_b32_e32 v113, v131
	v_mov_b32_e32 v114, v131
	v_mov_b32_e32 v115, v131
	v_mov_b32_e32 v116, 0
	v_mov_b32_e32 v117, v131
	v_mov_b32_e32 v118, v131
	v_mov_b32_e32 v119, v131
	v_mov_b32_e32 v120, 0
	v_mov_b32_e32 v121, v131
	v_mov_b32_e32 v122, v131
	v_mov_b32_e32 v123, v131
	v_mov_b32_e32 v124, 0
	v_mov_b32_e32 v125, v131
	v_mov_b32_e32 v126, v131
	v_mov_b32_e32 v127, v131
	s_waitcnt vmcnt(0) lgkmcnt(0)
	s_barrier
	v_add3_u32 v180, v149, v151, v152
	v_add3_u32 v223, v150, v151, v152
	v_add3_u32 v222, v149, v151, v153
	v_add3_u32 v224, v150, v151, v153
	v_readfirstlane_b32 s59, v130
	ds_read_b128 v[154:157], v180
	ds_read_b128 v[158:161], v180 offset:2048
	ds_read_b128 v[162:165], v180 offset:4096
	ds_read_b128 v[166:169], v180 offset:6144
	ds_read_b128 v[190:193], v223 offset:32768
	ds_read_b128 v[194:197], v223 offset:34816
	ds_read_b128 v[198:201], v223 offset:36864
	ds_read_b128 v[202:205], v223 offset:38912
	s_mov_b32 s57, 0
	s_mov_b64 s[60:61], s[34:35]
	v_subrev_u32_e32 v178, s34, v142
	v_subrev_u32_e32 v179, s34, v140
	v_xor_b32_e32 v225, 0x10000, v180
	v_xor_b32_e32 v226, 0x10000, v222
	v_xor_b32_e32 v227, 0x10000, v223
	v_xor_b32_e32 v228, 0x10000, v224
	s_add_u32 s59, s59, 0x10000
	v_add_u32_e32 v229, s36, v178
	v_add_u32_e32 v230, s38, v178
	v_add_u32_e32 v231, s40, v178
	v_add_u32_e32 v178, s22, v178
	v_add_u32_e32 v232, s44, v179
	v_add_u32_e32 v233, s46, v179
	v_add_u32_e32 v234, s48, v179
	v_add_u32_e32 v179, s42, v179
	s_mov_b32 m0, s59
	s_nop 0
	global_load_lds_dwordx4 v178, s[60:61]
	s_add_u32 m0, s59, 0x2000
	s_nop 0
	global_load_lds_dwordx4 v229, s[60:61]
	s_add_u32 m0, s59, 0x4000
	s_nop 0
	global_load_lds_dwordx4 v230, s[60:61]
	s_add_u32 m0, s59, 0x6000
	s_nop 0
	global_load_lds_dwordx4 v231, s[60:61]
	s_add_u32 m0, s59, 0x8000
	s_nop 0
	global_load_lds_dwordx4 v179, s[60:61]
	s_add_u32 m0, s59, 0xa000
	s_nop 0
	global_load_lds_dwordx4 v232, s[60:61]
	s_add_u32 m0, s59, 0xc000
	s_nop 0
	global_load_lds_dwordx4 v233, s[60:61]
	s_add_u32 m0, s59, 0xe000
	s_nop 0
	global_load_lds_dwordx4 v234, s[60:61]
	s_branch .Lg8_entry
.Lg8_top:
	s_waitcnt lgkmcnt(0)
	s_waitcnt vmcnt(0)
	s_barrier
	s_xor_b32 s59, s59, 0x10000
	ds_read_b128 v[154:157], v180
	ds_read_b128 v[158:161], v180 offset:2048
	ds_read_b128 v[162:165], v180 offset:4096
	ds_read_b128 v[166:169], v180 offset:6144
	ds_read_b128 v[190:193], v223 offset:32768
	ds_read_b128 v[194:197], v223 offset:34816
	ds_read_b128 v[198:201], v223 offset:36864
	ds_read_b128 v[202:205], v223 offset:38912
	s_mov_b32 m0, s59
	v_mfma_f32_16x16x32_bf16 v[60:63], v[170:173], v[206:209], v[60:63]
	v_mfma_f32_16x16x32_bf16 v[56:59], v[170:173], v[210:213], v[56:59]
	global_load_lds_dwordx4 v178, s[60:61]
	s_add_u32 m0, s59, 0x2000
	v_mfma_f32_16x16x32_bf16 v[52:55], v[170:173], v[214:217], v[52:55]
	v_mfma_f32_16x16x32_bf16 v[44:47], v[170:173], v[218:221], v[44:47]
	global_load_lds_dwordx4 v229, s[60:61]
	s_add_u32 m0, s59, 0x4000
	v_mfma_f32_16x16x32_bf16 v[36:39], v[174:177], v[206:209], v[36:39]
	v_mfma_f32_16x16x32_bf16 v[32:35], v[174:177], v[210:213], v[32:35]
	global_load_lds_dwordx4 v230, s[60:61]
	s_add_u32 m0, s59, 0x6000
	v_mfma_f32_16x16x32_bf16 v[28:31], v[174:177], v[214:217], v[28:31]
	v_mfma_f32_16x16x32_bf16 v[24:27], v[174:177], v[218:221], v[24:27]
	global_load_lds_dwordx4 v231, s[60:61]
	s_add_u32 m0, s59, 0x8000
	v_mfma_f32_16x16x32_bf16 v[20:23], v[182:185], v[206:209], v[20:23]
	v_mfma_f32_16x16x32_bf16 v[16:19], v[182:185], v[210:213], v[16:19]
	global_load_lds_dwordx4 v179, s[60:61]
	s_add_u32 m0, s59, 0xa000
	v_mfma_f32_16x16x32_bf16 v[12:15], v[182:185], v[214:217], v[12:15]
	v_mfma_f32_16x16x32_bf16 v[8:11], v[182:185], v[218:221], v[8:11]
	global_load_lds_dwordx4 v232, s[60:61]
	s_add_u32 m0, s59, 0xc000
	v_mfma_f32_16x16x32_bf16 v[4:7], v[186:189], v[206:209], v[4:7]
	v_mfma_f32_16x16x32_bf16 v[0:3], v[186:189], v[210:213], v[0:3]
	global_load_lds_dwordx4 v233, s[60:61]
	s_add_u32 m0, s59, 0xe000
	v_mfma_f32_16x16x32_bf16 v[48:51], v[186:189], v[214:217], v[48:51]
	v_mfma_f32_16x16x32_bf16 v[40:43], v[186:189], v[218:221], v[40:43]
	global_load_lds_dwordx4 v234, s[60:61]
.Lg8_entry:
	ds_read_b128 v[170:173], v180 offset:8192
	ds_read_b128 v[174:177], v180 offset:10240
	ds_read_b128 v[182:185], v180 offset:12288
	ds_read_b128 v[186:189], v180 offset:14336
	s_waitcnt lgkmcnt(4)
	v_mfma_f32_16x16x32_bf16 v[124:127], v[154:157], v[190:193], v[124:127]
	v_mfma_f32_16x16x32_bf16 v[120:123], v[154:157], v[194:197], v[120:123]
	v_mfma_f32_16x16x32_bf16 v[116:119], v[154:157], v[198:201], v[116:119]
	v_mfma_f32_16x16x32_bf16 v[112:115], v[154:157], v[202:205], v[112:115]
	v_mfma_f32_16x16x32_bf16 v[108:111], v[158:161], v[190:193], v[108:111]
	v_mfma_f32_16x16x32_bf16 v[104:107], v[158:161], v[194:197], v[104:107]
	v_mfma_f32_16x16x32_bf16 v[100:103], v[158:161], v[198:201], v[100:103]
	v_mfma_f32_16x16x32_bf16 v[96:99], v[158:161], v[202:205], v[96:99]
	v_mfma_f32_16x16x32_bf16 v[92:95], v[162:165], v[190:193], v[92:95]
	v_mfma_f32_16x16x32_bf16 v[88:91], v[162:165], v[194:197], v[88:91]
	v_mfma_f32_16x16x32_bf16 v[84:87], v[162:165], v[198:201], v[84:87]
	v_mfma_f32_16x16x32_bf16 v[80:83], v[162:165], v[202:205], v[80:83]
	v_mfma_f32_16x16x32_bf16 v[76:79], v[166:169], v[190:193], v[76:79]
	v_mfma_f32_16x16x32_bf16 v[72:75], v[166:169], v[194:197], v[72:75]
	v_mfma_f32_16x16x32_bf16 v[68:71], v[166:169], v[198:201], v[68:71]
	v_mfma_f32_16x16x32_bf16 v[64:67], v[166:169], v[202:205], v[64:67]
	ds_read_b128 v[154:157], v222
	ds_read_b128 v[158:161], v222 offset:2048
	ds_read_b128 v[162:165], v222 offset:4096
	ds_read_b128 v[166:169], v222 offset:6144
	ds_read_b128 v[206:209], v224 offset:32768
	ds_read_b128 v[210:213], v224 offset:34816
	ds_read_b128 v[214:217], v224 offset:36864
	ds_read_b128 v[218:221], v224 offset:38912
	s_waitcnt lgkmcnt(8)
	v_mfma_f32_16x16x32_bf16 v[60:63], v[170:173], v[190:193], v[60:63]
	v_mfma_f32_16x16x32_bf16 v[56:59], v[170:173], v[194:197], v[56:59]
	v_mfma_f32_16x16x32_bf16 v[52:55], v[170:173], v[198:201], v[52:55]
	v_mfma_f32_16x16x32_bf16 v[44:47], v[170:173], v[202:205], v[44:47]
	v_mfma_f32_16x16x32_bf16 v[36:39], v[174:177], v[190:193], v[36:39]
	v_mfma_f32_16x16x32_bf16 v[32:35], v[174:177], v[194:197], v[32:35]
	v_mfma_f32_16x16x32_bf16 v[28:31], v[174:177], v[198:201], v[28:31]
	v_mfma_f32_16x16x32_bf16 v[24:27], v[174:177], v[202:205], v[24:27]
	v_mfma_f32_16x16x32_bf16 v[20:23], v[182:185], v[190:193], v[20:23]
	v_mfma_f32_16x16x32_bf16 v[16:19], v[182:185], v[194:197], v[16:19]
	v_mfma_f32_16x16x32_bf16 v[12:15], v[182:185], v[198:201], v[12:15]
	v_mfma_f32_16x16x32_bf16 v[8:11], v[182:185], v[202:205], v[8:11]
	v_mfma_f32_16x16x32_bf16 v[4:7], v[186:189], v[190:193], v[4:7]
	v_mfma_f32_16x16x32_bf16 v[0:3], v[186:189], v[194:197], v[0:3]
	v_mfma_f32_16x16x32_bf16 v[48:51], v[186:189], v[198:201], v[48:51]
	v_mfma_f32_16x16x32_bf16 v[40:43], v[186:189], v[202:205], v[40:43]
	ds_read_b128 v[170:173], v222 offset:8192
	ds_read_b128 v[174:177], v222 offset:10240
	ds_read_b128 v[182:185], v222 offset:12288
	ds_read_b128 v[186:189], v222 offset:14336
	s_waitcnt lgkmcnt(4)
	v_mfma_f32_16x16x32_bf16 v[124:127], v[154:157], v[206:209], v[124:127]
	v_mfma_f32_16x16x32_bf16 v[120:123], v[154:157], v[210:213], v[120:123]
	v_mfma_f32_16x16x32_bf16 v[116:119], v[154:157], v[214:217], v[116:119]
	v_mfma_f32_16x16x32_bf16 v[112:115], v[154:157], v[218:221], v[112:115]
	v_mfma_f32_16x16x32_bf16 v[108:111], v[158:161], v[206:209], v[108:111]
	v_mfma_f32_16x16x32_bf16 v[104:107], v[158:161], v[210:213], v[104:107]
	v_mfma_f32_16x16x32_bf16 v[100:103], v[158:161], v[214:217], v[100:103]
	v_mfma_f32_16x16x32_bf16 v[96:99], v[158:161], v[218:221], v[96:99]
	v_mfma_f32_16x16x32_bf16 v[92:95], v[162:165], v[206:209], v[92:95]
	v_mfma_f32_16x16x32_bf16 v[88:91], v[162:165], v[210:213], v[88:91]
	v_mfma_f32_16x16x32_bf16 v[84:87], v[162:165], v[214:217], v[84:87]
	v_mfma_f32_16x16x32_bf16 v[80:83], v[162:165], v[218:221], v[80:83]
	v_mfma_f32_16x16x32_bf16 v[76:79], v[166:169], v[206:209], v[76:79]
	v_mfma_f32_16x16x32_bf16 v[72:75], v[166:169], v[210:213], v[72:75]
	v_mfma_f32_16x16x32_bf16 v[68:71], v[166:169], v[214:217], v[68:71]
	v_mfma_f32_16x16x32_bf16 v[64:67], v[166:169], v[218:221], v[64:67]
	s_add_u32 s60, s60, 0x80
	s_addc_u32 s61, s61, 0
	s_add_i32 s57, s57, 1
	s_cmp_lt_u32 s57, 15
	s_cbranch_scc0 .Lg8_last
	s_waitcnt lgkmcnt(0)
	s_waitcnt vmcnt(0)
	s_barrier
	s_xor_b32 s59, s59, 0x10000
	ds_read_b128 v[154:157], v225
	ds_read_b128 v[158:161], v225 offset:2048
	ds_read_b128 v[162:165], v225 offset:4096
	ds_read_b128 v[166:169], v225 offset:6144
	ds_read_b128 v[190:193], v227 offset:32768
	ds_read_b128 v[194:197], v227 offset:34816
	ds_read_b128 v[198:201], v227 offset:36864
	ds_read_b128 v[202:205], v227 offset:38912
	s_mov_b32 m0, s59
	v_mfma_f32_16x16x32_bf16 v[60:63], v[170:173], v[206:209], v[60:63]
	v_mfma_f32_16x16x32_bf16 v[56:59], v[170:173], v[210:213], v[56:59]
	global_load_lds_dwordx4 v178, s[60:61]
	s_add_u32 m0, s59, 0x2000
	v_mfma_f32_16x16x32_bf16 v[52:55], v[170:173], v[214:217], v[52:55]
	v_mfma_f32_16x16x32_bf16 v[44:47], v[170:173], v[218:221], v[44:47]
	global_load_lds_dwordx4 v229, s[60:61]
	s_add_u32 m0, s59, 0x4000
	v_mfma_f32_16x16x32_bf16 v[36:39], v[174:177], v[206:209], v[36:39]
	v_mfma_f32_16x16x32_bf16 v[32:35], v[174:177], v[210:213], v[32:35]
	global_load_lds_dwordx4 v230, s[60:61]
	s_add_u32 m0, s59, 0x6000
	v_mfma_f32_16x16x32_bf16 v[28:31], v[174:177], v[214:217], v[28:31]
	v_mfma_f32_16x16x32_bf16 v[24:27], v[174:177], v[218:221], v[24:27]
	global_load_lds_dwordx4 v231, s[60:61]
	s_add_u32 m0, s59, 0x8000
	v_mfma_f32_16x16x32_bf16 v[20:23], v[182:185], v[206:209], v[20:23]
	v_mfma_f32_16x16x32_bf16 v[16:19], v[182:185], v[210:213], v[16:19]
	global_load_lds_dwordx4 v179, s[60:61]
	s_add_u32 m0, s59, 0xa000
	v_mfma_f32_16x16x32_bf16 v[12:15], v[182:185], v[214:217], v[12:15]
	v_mfma_f32_16x16x32_bf16 v[8:11], v[182:185], v[218:221], v[8:11]
	global_load_lds_dwordx4 v232, s[60:61]
	s_add_u32 m0, s59, 0xc000
	v_mfma_f32_16x16x32_bf16 v[4:7], v[186:189], v[206:209], v[4:7]
	v_mfma_f32_16x16x32_bf16 v[0:3], v[186:189], v[210:213], v[0:3]
	global_load_lds_dwordx4 v233, s[60:61]
	s_add_u32 m0, s59, 0xe000
	v_mfma_f32_16x16x32_bf16 v[48:51], v[186:189], v[214:217], v[48:51]
	v_mfma_f32_16x16x32_bf16 v[40:43], v[186:189], v[218:221], v[40:43]
	global_load_lds_dwordx4 v234, s[60:61]
	ds_read_b128 v[170:173], v225 offset:8192
	ds_read_b128 v[174:177], v225 offset:10240
	ds_read_b128 v[182:185], v225 offset:12288
	ds_read_b128 v[186:189], v225 offset:14336
	s_waitcnt lgkmcnt(4)
	v_mfma_f32_16x16x32_bf16 v[124:127], v[154:157], v[190:193], v[124:127]
	v_mfma_f32_16x16x32_bf16 v[120:123], v[154:157], v[194:197], v[120:123]
	v_mfma_f32_16x16x32_bf16 v[116:119], v[154:157], v[198:201], v[116:119]
	v_mfma_f32_16x16x32_bf16 v[112:115], v[154:157], v[202:205], v[112:115]
	v_mfma_f32_16x16x32_bf16 v[108:111], v[158:161], v[190:193], v[108:111]
	v_mfma_f32_16x16x32_bf16 v[104:107], v[158:161], v[194:197], v[104:107]
	v_mfma_f32_16x16x32_bf16 v[100:103], v[158:161], v[198:201], v[100:103]
	v_mfma_f32_16x16x32_bf16 v[96:99], v[158:161], v[202:205], v[96:99]
	v_mfma_f32_16x16x32_bf16 v[92:95], v[162:165], v[190:193], v[92:95]
	v_mfma_f32_16x16x32_bf16 v[88:91], v[162:165], v[194:197], v[88:91]
	v_mfma_f32_16x16x32_bf16 v[84:87], v[162:165], v[198:201], v[84:87]
	v_mfma_f32_16x16x32_bf16 v[80:83], v[162:165], v[202:205], v[80:83]
	v_mfma_f32_16x16x32_bf16 v[76:79], v[166:169], v[190:193], v[76:79]
	v_mfma_f32_16x16x32_bf16 v[72:75], v[166:169], v[194:197], v[72:75]
	v_mfma_f32_16x16x32_bf16 v[68:71], v[166:169], v[198:201], v[68:71]
	v_mfma_f32_16x16x32_bf16 v[64:67], v[166:169], v[202:205], v[64:67]
	ds_read_b128 v[154:157], v226
	ds_read_b128 v[158:161], v226 offset:2048
	ds_read_b128 v[162:165], v226 offset:4096
	ds_read_b128 v[166:169], v226 offset:6144
	ds_read_b128 v[206:209], v228 offset:32768
	ds_read_b128 v[210:213], v228 offset:34816
	ds_read_b128 v[214:217], v228 offset:36864
	ds_read_b128 v[218:221], v228 offset:38912
	s_waitcnt lgkmcnt(8)
	v_mfma_f32_16x16x32_bf16 v[60:63], v[170:173], v[190:193], v[60:63]
	v_mfma_f32_16x16x32_bf16 v[56:59], v[170:173], v[194:197], v[56:59]
	v_mfma_f32_16x16x32_bf16 v[52:55], v[170:173], v[198:201], v[52:55]
	v_mfma_f32_16x16x32_bf16 v[44:47], v[170:173], v[202:205], v[44:47]
	v_mfma_f32_16x16x32_bf16 v[36:39], v[174:177], v[190:193], v[36:39]
	v_mfma_f32_16x16x32_bf16 v[32:35], v[174:177], v[194:197], v[32:35]
	v_mfma_f32_16x16x32_bf16 v[28:31], v[174:177], v[198:201], v[28:31]
	v_mfma_f32_16x16x32_bf16 v[24:27], v[174:177], v[202:205], v[24:27]
	v_mfma_f32_16x16x32_bf16 v[20:23], v[182:185], v[190:193], v[20:23]
	v_mfma_f32_16x16x32_bf16 v[16:19], v[182:185], v[194:197], v[16:19]
	v_mfma_f32_16x16x32_bf16 v[12:15], v[182:185], v[198:201], v[12:15]
	v_mfma_f32_16x16x32_bf16 v[8:11], v[182:185], v[202:205], v[8:11]
	v_mfma_f32_16x16x32_bf16 v[4:7], v[186:189], v[190:193], v[4:7]
	v_mfma_f32_16x16x32_bf16 v[0:3], v[186:189], v[194:197], v[0:3]
	v_mfma_f32_16x16x32_bf16 v[48:51], v[186:189], v[198:201], v[48:51]
	v_mfma_f32_16x16x32_bf16 v[40:43], v[186:189], v[202:205], v[40:43]
	ds_read_b128 v[170:173], v226 offset:8192
	ds_read_b128 v[174:177], v226 offset:10240
	ds_read_b128 v[182:185], v226 offset:12288
	ds_read_b128 v[186:189], v226 offset:14336
	s_waitcnt lgkmcnt(4)
	v_mfma_f32_16x16x32_bf16 v[124:127], v[154:157], v[206:209], v[124:127]
	v_mfma_f32_16x16x32_bf16 v[120:123], v[154:157], v[210:213], v[120:123]
	v_mfma_f32_16x16x32_bf16 v[116:119], v[154:157], v[214:217], v[116:119]
	v_mfma_f32_16x16x32_bf16 v[112:115], v[154:157], v[218:221], v[112:115]
	v_mfma_f32_16x16x32_bf16 v[108:111], v[158:161], v[206:209], v[108:111]
	v_mfma_f32_16x16x32_bf16 v[104:107], v[158:161], v[210:213], v[104:107]
	v_mfma_f32_16x16x32_bf16 v[100:103], v[158:161], v[214:217], v[100:103]
	v_mfma_f32_16x16x32_bf16 v[96:99], v[158:161], v[218:221], v[96:99]
	v_mfma_f32_16x16x32_bf16 v[92:95], v[162:165], v[206:209], v[92:95]
	v_mfma_f32_16x16x32_bf16 v[88:91], v[162:165], v[210:213], v[88:91]
	v_mfma_f32_16x16x32_bf16 v[84:87], v[162:165], v[214:217], v[84:87]
	v_mfma_f32_16x16x32_bf16 v[80:83], v[162:165], v[218:221], v[80:83]
	v_mfma_f32_16x16x32_bf16 v[76:79], v[166:169], v[206:209], v[76:79]
	v_mfma_f32_16x16x32_bf16 v[72:75], v[166:169], v[210:213], v[72:75]
	v_mfma_f32_16x16x32_bf16 v[68:71], v[166:169], v[214:217], v[68:71]
	v_mfma_f32_16x16x32_bf16 v[64:67], v[166:169], v[218:221], v[64:67]
	s_add_u32 s60, s60, 0x80
	s_addc_u32 s61, s61, 0
	s_add_i32 s57, s57, 1
	s_branch .Lg8_top

.LBB0_1331:
	s_ashr_i32 s20, s58, 2
	v_mov_b32_e32 v6, v181
	s_and_b32 s4, s58, 7
	s_and_b32 s47, s20, -8
	s_or_b32 s42, s47, s4
	v_lshrrev_b32_e32 v7, 4, v6
	v_lshlrev_b32_e32 v1, 6, v6
	v_xor_b32_e32 v0, v7, v6
	v_and_b32_e32 v8, 0x3c0, v1
	v_lshlrev_b32_e32 v1, 8, v6
	s_ashr_i32 s43, s42, 31
	v_lshlrev_b32_e32 v0, 3, v0
	v_and_b32_e32 v1, 0xfffff800, v1
	s_and_b32 s46, s57, 7
	s_bfe_u32 s4, s58, 0x20003
	s_lshl_b64 s[20:21], s[42:43], 20
	v_and_or_b32 v0, v0, 56, v1
	s_add_u32 s20, s3, s20
	v_ashrrev_i32_e32 v1, 31, v0
	s_addc_u32 s21, s48, s21
	v_lshlrev_b64 v[0:1], 1, v[0:1]
	v_lshl_add_u32 v134, v6, 4, 0
	v_lshl_add_u64 v[2:3], s[20:21], 0, v[0:1]
	v_readfirstlane_b32 s20, v134
	v_add_u32_e32 v9, 0x2000, v134
	s_mov_b32 m0, s20
	v_readfirstlane_b32 s20, v9
	v_add_u32_e32 v9, 0x4000, v134
	s_waitcnt vmcnt(63) expcnt(7) lgkmcnt(15)
	s_barrier
	global_load_lds_dwordx4 v[2:3], off
	v_lshl_add_u64 v[4:5], v[2:3], 0, s[6:7]
	s_mov_b32 m0, s20
	v_readfirstlane_b32 s20, v9
	global_load_lds_dwordx4 v[4:5], off
	v_lshl_add_u64 v[4:5], v[2:3], 0, s[8:9]
	s_mov_b32 m0, s20
	s_lshl_b32 s43, s4, 20
	global_load_lds_dwordx4 v[4:5], off
	v_add_u32_e32 v4, 0x6000, v134
	s_add_u32 s44, s49, s43
	v_readfirstlane_b32 s20, v4
	v_add_u32_e32 v4, 0x8000, v134
	s_addc_u32 s45, s56, 0
	v_lshl_add_u64 v[2:3], v[2:3], 0, s[10:11]
	s_mov_b32 m0, s20
	v_readfirstlane_b32 s20, v4
	v_add_u32_e32 v9, 0xa000, v134
	global_load_lds_dwordx4 v[2:3], off
	v_lshl_add_u64 v[2:3], s[44:45], 0, v[0:1]
	s_mov_b32 m0, s20
	v_readfirstlane_b32 s20, v9
	v_add_u32_e32 v9, 0xc000, v134
	global_load_lds_dwordx4 v[2:3], off
	v_lshl_add_u64 v[4:5], v[2:3], 0, s[6:7]
	s_mov_b32 m0, s20
	v_readfirstlane_b32 s20, v9
	global_load_lds_dwordx4 v[4:5], off
	v_lshl_add_u64 v[4:5], v[2:3], 0, s[8:9]
	s_mov_b32 m0, s20
	v_lshl_add_u64 v[2:3], v[2:3], 0, s[10:11]
	global_load_lds_dwordx4 v[4:5], off
	v_add_u32_e32 v4, 0xe000, v134
	v_mov_b32_e32 v36, 0
	v_readfirstlane_b32 s20, v4
	s_mov_b32 m0, s20
	v_ashrrev_i32_e32 v4, 6, v6
	global_load_lds_dwordx4 v[2:3], off
	s_or_b32 s20, s47, s46
	v_lshrrev_b32_e32 v5, 30, v4
	s_ashr_i32 s21, s20, 31
	v_add_u32_e32 v5, v4, v5
	s_lshl_b64 s[20:21], s[20:21], 20
	v_bfe_u32 v2, v6, 4, 2
	v_bfe_u32 v3, v6, 1, 3
	v_and_b32_e32 v6, 0x7fffc, v5
	s_add_u32 s20, s34, s20
	v_sub_u32_e32 v4, v4, v6
	s_addc_u32 s21, s35, s21
	v_lshlrev_b32_e32 v136, 13, v4
	v_bitop3_b32 v4, v7, v3, 3 bitop3:0x6c
	v_bitop3_b32 v2, v2, v3, 4 bitop3:0x36
	v_lshl_add_u64 v[130:131], s[20:21], 0, v[0:1]
	s_add_u32 s20, s34, s43
	v_lshlrev_b32_e32 v5, 12, v5
	v_lshlrev_b32_e32 v4, 3, v4
	v_lshlrev_b32_e32 v2, 3, v2
	s_addc_u32 s21, s35, 0
	v_and_b32_e32 v135, 0xffffc000, v5
	v_lshl_add_u64 v[132:133], s[20:21], 0, v[0:1]
	s_mov_b64 s[44:45], 0
	v_lshlrev_b32_e32 v137, 1, v8
	v_lshlrev_b32_e32 v138, 1, v4
	v_lshlrev_b32_e32 v139, 1, v2
	s_mov_b32 s59, 0
	s_mov_b32 s43, 0
	v_mov_b32_e32 v37, v36
	v_mov_b32_e32 v38, v36
	v_mov_b32_e32 v39, v36
	v_mov_b32_e32 v40, v36
	v_mov_b32_e32 v41, v36
	v_mov_b32_e32 v42, v36
	v_mov_b32_e32 v43, v36
	v_mov_b32_e32 v0, v36
	v_mov_b32_e32 v1, v36
	v_mov_b32_e32 v2, v36
	v_mov_b32_e32 v3, v36
	v_mov_b32_e32 v4, v36
	v_mov_b32_e32 v5, v36
	v_mov_b32_e32 v6, v36
	v_mov_b32_e32 v7, v36
	v_mov_b32_e32 v8, v36
	v_mov_b32_e32 v9, v36
	v_mov_b32_e32 v10, v36
	v_mov_b32_e32 v11, v36
	v_mov_b32_e32 v12, v36
	v_mov_b32_e32 v13, v36
	v_mov_b32_e32 v14, v36
	v_mov_b32_e32 v15, v36
	v_mov_b32_e32 v16, v36
	v_mov_b32_e32 v17, v36
	v_mov_b32_e32 v18, v36
	v_mov_b32_e32 v19, v36
	v_mov_b32_e32 v20, v36
	v_mov_b32_e32 v21, v36
	v_mov_b32_e32 v22, v36
	v_mov_b32_e32 v23, v36
	v_mov_b32_e32 v24, v36
	v_mov_b32_e32 v25, v36
	v_mov_b32_e32 v26, v36
	v_mov_b32_e32 v27, v36
	v_mov_b32_e32 v28, v36
	v_mov_b32_e32 v29, v36
	v_mov_b32_e32 v30, v36
	v_mov_b32_e32 v31, v36
	v_mov_b32_e32 v32, v36
	v_mov_b32_e32 v33, v36
	v_mov_b32_e32 v34, v36
	v_mov_b32_e32 v35, v36
	v_mov_b32_e32 v44, v36
	v_mov_b32_e32 v45, v36
	v_mov_b32_e32 v46, v36
	v_mov_b32_e32 v47, v36
	v_mov_b32_e32 v48, v36
	v_mov_b32_e32 v49, v36
	v_mov_b32_e32 v50, v36
	v_mov_b32_e32 v51, v36
	v_mov_b32_e32 v52, v36
	v_mov_b32_e32 v53, v36
	v_mov_b32_e32 v54, v36
	v_mov_b32_e32 v55, v36
	v_mov_b32_e32 v56, v36
	v_mov_b32_e32 v57, v36
	v_mov_b32_e32 v58, v36
	v_mov_b32_e32 v59, v36
	v_mov_b32_e32 v60, v36
	v_mov_b32_e32 v61, v36
	v_mov_b32_e32 v62, v36
	v_mov_b32_e32 v63, v36
	v_mov_b32_e32 v64, v36
	v_mov_b32_e32 v65, v36
	v_mov_b32_e32 v66, v36
	v_mov_b32_e32 v67, v36
	v_mov_b32_e32 v68, v36
	v_mov_b32_e32 v69, v36
	v_mov_b32_e32 v70, v36
	v_mov_b32_e32 v71, v36
	v_mov_b32_e32 v72, v36
	v_mov_b32_e32 v73, v36
	v_mov_b32_e32 v74, v36
	v_mov_b32_e32 v75, v36
	v_mov_b32_e32 v76, v36
	v_mov_b32_e32 v77, v36
	v_mov_b32_e32 v78, v36
	v_mov_b32_e32 v79, v36
	v_mov_b32_e32 v80, v36
	v_mov_b32_e32 v81, v36
	v_mov_b32_e32 v82, v36
	v_mov_b32_e32 v83, v36
	v_mov_b32_e32 v84, v36
	v_mov_b32_e32 v85, v36
	v_mov_b32_e32 v86, v36
	v_mov_b32_e32 v87, v36
	v_mov_b32_e32 v88, v36
	v_mov_b32_e32 v89, v36
	v_mov_b32_e32 v90, v36
	v_mov_b32_e32 v91, v36
	v_mov_b32_e32 v92, v36
	v_mov_b32_e32 v93, v36
	v_mov_b32_e32 v94, v36
	v_mov_b32_e32 v95, v36
	v_mov_b32_e32 v96, v36
	v_mov_b32_e32 v97, v36
	v_mov_b32_e32 v98, v36
	v_mov_b32_e32 v99, v36
	v_mov_b32_e32 v100, v36
	v_mov_b32_e32 v101, v36
	v_mov_b32_e32 v102, v36
	v_mov_b32_e32 v103, v36
	v_mov_b32_e32 v104, v36
	v_mov_b32_e32 v105, v36
	v_mov_b32_e32 v106, v36
	v_mov_b32_e32 v107, v36
	v_mov_b32_e32 v108, v36
	v_mov_b32_e32 v109, v36
	v_mov_b32_e32 v110, v36
	v_mov_b32_e32 v111, v36
	v_mov_b32_e32 v112, v36
	v_mov_b32_e32 v113, v36
	v_mov_b32_e32 v114, v36
	v_mov_b32_e32 v115, v36
	v_mov_b32_e32 v116, v36
	v_mov_b32_e32 v117, v36
	v_mov_b32_e32 v118, v36
	v_mov_b32_e32 v119, v36
	v_mov_b32_e32 v120, v36
	v_mov_b32_e32 v121, v36
	v_mov_b32_e32 v122, v36
	v_mov_b32_e32 v123, v36
	v_mov_b32_e32 v124, v36
	v_mov_b32_e32 v125, v36
	v_mov_b32_e32 v126, v36
	v_mov_b32_e32 v127, v36
	s_waitcnt vmcnt(0) lgkmcnt(0)
	s_barrier
	v_add3_u32 v141, v135, v137, v138
	v_add3_u32 v210, v136, v137, v138
	v_add3_u32 v180, v135, v137, v139
	v_add3_u32 v211, v136, v137, v139
	v_readfirstlane_b32 s59, v134
	ds_read_b128 v[142:145], v141
	ds_read_b128 v[146:149], v141 offset:2048
	ds_read_b128 v[150:153], v141 offset:4096
	ds_read_b128 v[154:157], v141 offset:6144
	ds_read_b128 v[174:177], v210 offset:32768
	ds_read_b128 v[182:185], v210 offset:34816
	ds_read_b128 v[186:189], v210 offset:36864
	ds_read_b128 v[190:193], v210 offset:38912
	s_mov_b32 s43, 0
	s_mov_b64 s[44:45], s[34:35]
	v_subrev_u32_e32 v178, s34, v130
	v_subrev_u32_e32 v179, s34, v132
	v_xor_b32_e32 v212, 0x10000, v141
	v_xor_b32_e32 v213, 0x10000, v180
	v_xor_b32_e32 v214, 0x10000, v210
	v_xor_b32_e32 v215, 0x10000, v211
	s_add_u32 s59, s59, 0x10000
	v_add_u32_e32 v216, s14, v178
	v_add_u32_e32 v217, s16, v178
	v_add_u32_e32 v218, s18, v178
	v_add_u32_e32 v178, s12, v178
	v_add_u32_e32 v219, s36, v179
	v_add_u32_e32 v220, s38, v179
	v_add_u32_e32 v221, s40, v179
	v_add_u32_e32 v179, s22, v179
	s_mov_b32 m0, s59
	s_nop 0
	global_load_lds_dwordx4 v178, s[44:45]
	s_add_u32 m0, s59, 0x2000
	s_nop 0
	global_load_lds_dwordx4 v216, s[44:45]
	s_add_u32 m0, s59, 0x4000
	s_nop 0
	global_load_lds_dwordx4 v217, s[44:45]
	s_add_u32 m0, s59, 0x6000
	s_nop 0
	global_load_lds_dwordx4 v218, s[44:45]
	s_add_u32 m0, s59, 0x8000
	s_nop 0
	global_load_lds_dwordx4 v179, s[44:45]
	s_add_u32 m0, s59, 0xa000
	s_nop 0
	global_load_lds_dwordx4 v219, s[44:45]
	s_add_u32 m0, s59, 0xc000
	s_nop 0
	global_load_lds_dwordx4 v220, s[44:45]
	s_add_u32 m0, s59, 0xe000
	s_nop 0
	global_load_lds_dwordx4 v221, s[44:45]
	s_branch .Lg9_entry
.Lg9_top:
	s_waitcnt lgkmcnt(0)
	s_waitcnt vmcnt(0)
	s_barrier
	s_xor_b32 s59, s59, 0x10000
	ds_read_b128 v[142:145], v141
	ds_read_b128 v[146:149], v141 offset:2048
	ds_read_b128 v[150:153], v141 offset:4096
	ds_read_b128 v[154:157], v141 offset:6144
	ds_read_b128 v[174:177], v210 offset:32768
	ds_read_b128 v[182:185], v210 offset:34816
	ds_read_b128 v[186:189], v210 offset:36864
	ds_read_b128 v[190:193], v210 offset:38912
	s_mov_b32 m0, s59
	v_mfma_f32_16x16x32_bf16 v[60:63], v[158:161], v[194:197], v[60:63]
	v_mfma_f32_16x16x32_bf16 v[56:59], v[158:161], v[198:201], v[56:59]
	global_load_lds_dwordx4 v178, s[44:45]
	s_add_u32 m0, s59, 0x2000
	v_mfma_f32_16x16x32_bf16 v[52:55], v[158:161], v[202:205], v[52:55]
	v_mfma_f32_16x16x32_bf16 v[48:51], v[158:161], v[206:209], v[48:51]
	global_load_lds_dwordx4 v216, s[44:45]
	s_add_u32 m0, s59, 0x4000
	v_mfma_f32_16x16x32_bf16 v[44:47], v[162:165], v[194:197], v[44:47]
	v_mfma_f32_16x16x32_bf16 v[32:35], v[162:165], v[198:201], v[32:35]
	global_load_lds_dwordx4 v217, s[44:45]
	s_add_u32 m0, s59, 0x6000
	v_mfma_f32_16x16x32_bf16 v[28:31], v[162:165], v[202:205], v[28:31]
	v_mfma_f32_16x16x32_bf16 v[24:27], v[162:165], v[206:209], v[24:27]
	global_load_lds_dwordx4 v218, s[44:45]
	s_add_u32 m0, s59, 0x8000
	v_mfma_f32_16x16x32_bf16 v[20:23], v[166:169], v[194:197], v[20:23]
	v_mfma_f32_16x16x32_bf16 v[16:19], v[166:169], v[198:201], v[16:19]
	global_load_lds_dwordx4 v179, s[44:45]
	s_add_u32 m0, s59, 0xa000
	v_mfma_f32_16x16x32_bf16 v[12:15], v[166:169], v[202:205], v[12:15]
	v_mfma_f32_16x16x32_bf16 v[8:11], v[166:169], v[206:209], v[8:11]
	global_load_lds_dwordx4 v219, s[44:45]
	s_add_u32 m0, s59, 0xc000
	v_mfma_f32_16x16x32_bf16 v[4:7], v[170:173], v[194:197], v[4:7]
	v_mfma_f32_16x16x32_bf16 v[0:3], v[170:173], v[198:201], v[0:3]
	global_load_lds_dwordx4 v220, s[44:45]
	s_add_u32 m0, s59, 0xe000
	v_mfma_f32_16x16x32_bf16 v[40:43], v[170:173], v[202:205], v[40:43]
	v_mfma_f32_16x16x32_bf16 v[36:39], v[170:173], v[206:209], v[36:39]
	global_load_lds_dwordx4 v221, s[44:45]
.Lg9_entry:
	ds_read_b128 v[158:161], v141 offset:8192
	ds_read_b128 v[162:165], v141 offset:10240
	ds_read_b128 v[166:169], v141 offset:12288
	ds_read_b128 v[170:173], v141 offset:14336
	s_waitcnt lgkmcnt(4)
	v_mfma_f32_16x16x32_bf16 v[124:127], v[142:145], v[174:177], v[124:127]
	v_mfma_f32_16x16x32_bf16 v[120:123], v[142:145], v[182:185], v[120:123]
	v_mfma_f32_16x16x32_bf16 v[116:119], v[142:145], v[186:189], v[116:119]
	v_mfma_f32_16x16x32_bf16 v[112:115], v[142:145], v[190:193], v[112:115]
	v_mfma_f32_16x16x32_bf16 v[108:111], v[146:149], v[174:177], v[108:111]
	v_mfma_f32_16x16x32_bf16 v[104:107], v[146:149], v[182:185], v[104:107]
	v_mfma_f32_16x16x32_bf16 v[100:103], v[146:149], v[186:189], v[100:103]
	v_mfma_f32_16x16x32_bf16 v[96:99], v[146:149], v[190:193], v[96:99]
	v_mfma_f32_16x16x32_bf16 v[92:95], v[150:153], v[174:177], v[92:95]
	v_mfma_f32_16x16x32_bf16 v[88:91], v[150:153], v[182:185], v[88:91]
	v_mfma_f32_16x16x32_bf16 v[84:87], v[150:153], v[186:189], v[84:87]
	v_mfma_f32_16x16x32_bf16 v[80:83], v[150:153], v[190:193], v[80:83]
	v_mfma_f32_16x16x32_bf16 v[76:79], v[154:157], v[174:177], v[76:79]
	v_mfma_f32_16x16x32_bf16 v[72:75], v[154:157], v[182:185], v[72:75]
	v_mfma_f32_16x16x32_bf16 v[68:71], v[154:157], v[186:189], v[68:71]
	v_mfma_f32_16x16x32_bf16 v[64:67], v[154:157], v[190:193], v[64:67]
	ds_read_b128 v[142:145], v180
	ds_read_b128 v[146:149], v180 offset:2048
	ds_read_b128 v[150:153], v180 offset:4096
	ds_read_b128 v[154:157], v180 offset:6144
	ds_read_b128 v[194:197], v211 offset:32768
	ds_read_b128 v[198:201], v211 offset:34816
	ds_read_b128 v[202:205], v211 offset:36864
	ds_read_b128 v[206:209], v211 offset:38912
	s_waitcnt lgkmcnt(8)
	v_mfma_f32_16x16x32_bf16 v[60:63], v[158:161], v[174:177], v[60:63]
	v_mfma_f32_16x16x32_bf16 v[56:59], v[158:161], v[182:185], v[56:59]
	v_mfma_f32_16x16x32_bf16 v[52:55], v[158:161], v[186:189], v[52:55]
	v_mfma_f32_16x16x32_bf16 v[48:51], v[158:161], v[190:193], v[48:51]
	v_mfma_f32_16x16x32_bf16 v[44:47], v[162:165], v[174:177], v[44:47]
	v_mfma_f32_16x16x32_bf16 v[32:35], v[162:165], v[182:185], v[32:35]
	v_mfma_f32_16x16x32_bf16 v[28:31], v[162:165], v[186:189], v[28:31]
	v_mfma_f32_16x16x32_bf16 v[24:27], v[162:165], v[190:193], v[24:27]
	v_mfma_f32_16x16x32_bf16 v[20:23], v[166:169], v[174:177], v[20:23]
	v_mfma_f32_16x16x32_bf16 v[16:19], v[166:169], v[182:185], v[16:19]
	v_mfma_f32_16x16x32_bf16 v[12:15], v[166:169], v[186:189], v[12:15]
	v_mfma_f32_16x16x32_bf16 v[8:11], v[166:169], v[190:193], v[8:11]
	v_mfma_f32_16x16x32_bf16 v[4:7], v[170:173], v[174:177], v[4:7]
	v_mfma_f32_16x16x32_bf16 v[0:3], v[170:173], v[182:185], v[0:3]
	v_mfma_f32_16x16x32_bf16 v[40:43], v[170:173], v[186:189], v[40:43]
	v_mfma_f32_16x16x32_bf16 v[36:39], v[170:173], v[190:193], v[36:39]
	ds_read_b128 v[158:161], v180 offset:8192
	ds_read_b128 v[162:165], v180 offset:10240
	ds_read_b128 v[166:169], v180 offset:12288
	ds_read_b128 v[170:173], v180 offset:14336
	s_waitcnt lgkmcnt(4)
	v_mfma_f32_16x16x32_bf16 v[124:127], v[142:145], v[194:197], v[124:127]
	v_mfma_f32_16x16x32_bf16 v[120:123], v[142:145], v[198:201], v[120:123]
	v_mfma_f32_16x16x32_bf16 v[116:119], v[142:145], v[202:205], v[116:119]
	v_mfma_f32_16x16x32_bf16 v[112:115], v[142:145], v[206:209], v[112:115]
	v_mfma_f32_16x16x32_bf16 v[108:111], v[146:149], v[194:197], v[108:111]
	v_mfma_f32_16x16x32_bf16 v[104:107], v[146:149], v[198:201], v[104:107]
	v_mfma_f32_16x16x32_bf16 v[100:103], v[146:149], v[202:205], v[100:103]
	v_mfma_f32_16x16x32_bf16 v[96:99], v[146:149], v[206:209], v[96:99]
	v_mfma_f32_16x16x32_bf16 v[92:95], v[150:153], v[194:197], v[92:95]
	v_mfma_f32_16x16x32_bf16 v[88:91], v[150:153], v[198:201], v[88:91]
	v_mfma_f32_16x16x32_bf16 v[84:87], v[150:153], v[202:205], v[84:87]
	v_mfma_f32_16x16x32_bf16 v[80:83], v[150:153], v[206:209], v[80:83]
	v_mfma_f32_16x16x32_bf16 v[76:79], v[154:157], v[194:197], v[76:79]
	v_mfma_f32_16x16x32_bf16 v[72:75], v[154:157], v[198:201], v[72:75]
	v_mfma_f32_16x16x32_bf16 v[68:71], v[154:157], v[202:205], v[68:71]
	v_mfma_f32_16x16x32_bf16 v[64:67], v[154:157], v[206:209], v[64:67]
	s_add_u32 s44, s44, 0x80
	s_addc_u32 s45, s45, 0
	s_add_i32 s43, s43, 1
	s_cmp_lt_u32 s43, 31
	s_cbranch_scc0 .Lg9_last
	s_waitcnt lgkmcnt(0)
	s_waitcnt vmcnt(0)
	s_barrier
	s_xor_b32 s59, s59, 0x10000
	ds_read_b128 v[142:145], v212
	ds_read_b128 v[146:149], v212 offset:2048
	ds_read_b128 v[150:153], v212 offset:4096
	ds_read_b128 v[154:157], v212 offset:6144
	ds_read_b128 v[174:177], v214 offset:32768
	ds_read_b128 v[182:185], v214 offset:34816
	ds_read_b128 v[186:189], v214 offset:36864
	ds_read_b128 v[190:193], v214 offset:38912
	s_mov_b32 m0, s59
	v_mfma_f32_16x16x32_bf16 v[60:63], v[158:161], v[194:197], v[60:63]
	v_mfma_f32_16x16x32_bf16 v[56:59], v[158:161], v[198:201], v[56:59]
	global_load_lds_dwordx4 v178, s[44:45]
	s_add_u32 m0, s59, 0x2000
	v_mfma_f32_16x16x32_bf16 v[52:55], v[158:161], v[202:205], v[52:55]
	v_mfma_f32_16x16x32_bf16 v[48:51], v[158:161], v[206:209], v[48:51]
	global_load_lds_dwordx4 v216, s[44:45]
	s_add_u32 m0, s59, 0x4000
	v_mfma_f32_16x16x32_bf16 v[44:47], v[162:165], v[194:197], v[44:47]
	v_mfma_f32_16x16x32_bf16 v[32:35], v[162:165], v[198:201], v[32:35]
	global_load_lds_dwordx4 v217, s[44:45]
	s_add_u32 m0, s59, 0x6000
	v_mfma_f32_16x16x32_bf16 v[28:31], v[162:165], v[202:205], v[28:31]
	v_mfma_f32_16x16x32_bf16 v[24:27], v[162:165], v[206:209], v[24:27]
	global_load_lds_dwordx4 v218, s[44:45]
	s_add_u32 m0, s59, 0x8000
	v_mfma_f32_16x16x32_bf16 v[20:23], v[166:169], v[194:197], v[20:23]
	v_mfma_f32_16x16x32_bf16 v[16:19], v[166:169], v[198:201], v[16:19]
	global_load_lds_dwordx4 v179, s[44:45]
	s_add_u32 m0, s59, 0xa000
	v_mfma_f32_16x16x32_bf16 v[12:15], v[166:169], v[202:205], v[12:15]
	v_mfma_f32_16x16x32_bf16 v[8:11], v[166:169], v[206:209], v[8:11]
	global_load_lds_dwordx4 v219, s[44:45]
	s_add_u32 m0, s59, 0xc000
	v_mfma_f32_16x16x32_bf16 v[4:7], v[170:173], v[194:197], v[4:7]
	v_mfma_f32_16x16x32_bf16 v[0:3], v[170:173], v[198:201], v[0:3]
	global_load_lds_dwordx4 v220, s[44:45]
	s_add_u32 m0, s59, 0xe000
	v_mfma_f32_16x16x32_bf16 v[40:43], v[170:173], v[202:205], v[40:43]
	v_mfma_f32_16x16x32_bf16 v[36:39], v[170:173], v[206:209], v[36:39]
	global_load_lds_dwordx4 v221, s[44:45]
	ds_read_b128 v[158:161], v212 offset:8192
	ds_read_b128 v[162:165], v212 offset:10240
	ds_read_b128 v[166:169], v212 offset:12288
	ds_read_b128 v[170:173], v212 offset:14336
	s_waitcnt lgkmcnt(4)
	v_mfma_f32_16x16x32_bf16 v[124:127], v[142:145], v[174:177], v[124:127]
	v_mfma_f32_16x16x32_bf16 v[120:123], v[142:145], v[182:185], v[120:123]
	v_mfma_f32_16x16x32_bf16 v[116:119], v[142:145], v[186:189], v[116:119]
	v_mfma_f32_16x16x32_bf16 v[112:115], v[142:145], v[190:193], v[112:115]
	v_mfma_f32_16x16x32_bf16 v[108:111], v[146:149], v[174:177], v[108:111]
	v_mfma_f32_16x16x32_bf16 v[104:107], v[146:149], v[182:185], v[104:107]
	v_mfma_f32_16x16x32_bf16 v[100:103], v[146:149], v[186:189], v[100:103]
	v_mfma_f32_16x16x32_bf16 v[96:99], v[146:149], v[190:193], v[96:99]
	v_mfma_f32_16x16x32_bf16 v[92:95], v[150:153], v[174:177], v[92:95]
	v_mfma_f32_16x16x32_bf16 v[88:91], v[150:153], v[182:185], v[88:91]
	v_mfma_f32_16x16x32_bf16 v[84:87], v[150:153], v[186:189], v[84:87]
	v_mfma_f32_16x16x32_bf16 v[80:83], v[150:153], v[190:193], v[80:83]
	v_mfma_f32_16x16x32_bf16 v[76:79], v[154:157], v[174:177], v[76:79]
	v_mfma_f32_16x16x32_bf16 v[72:75], v[154:157], v[182:185], v[72:75]
	v_mfma_f32_16x16x32_bf16 v[68:71], v[154:157], v[186:189], v[68:71]
	v_mfma_f32_16x16x32_bf16 v[64:67], v[154:157], v[190:193], v[64:67]
	ds_read_b128 v[142:145], v213
	ds_read_b128 v[146:149], v213 offset:2048
	ds_read_b128 v[150:153], v213 offset:4096
	ds_read_b128 v[154:157], v213 offset:6144
	ds_read_b128 v[194:197], v215 offset:32768
	ds_read_b128 v[198:201], v215 offset:34816
	ds_read_b128 v[202:205], v215 offset:36864
	ds_read_b128 v[206:209], v215 offset:38912
	s_waitcnt lgkmcnt(8)
	v_mfma_f32_16x16x32_bf16 v[60:63], v[158:161], v[174:177], v[60:63]
	v_mfma_f32_16x16x32_bf16 v[56:59], v[158:161], v[182:185], v[56:59]
	v_mfma_f32_16x16x32_bf16 v[52:55], v[158:161], v[186:189], v[52:55]
	v_mfma_f32_16x16x32_bf16 v[48:51], v[158:161], v[190:193], v[48:51]
	v_mfma_f32_16x16x32_bf16 v[44:47], v[162:165], v[174:177], v[44:47]
	v_mfma_f32_16x16x32_bf16 v[32:35], v[162:165], v[182:185], v[32:35]
	v_mfma_f32_16x16x32_bf16 v[28:31], v[162:165], v[186:189], v[28:31]
	v_mfma_f32_16x16x32_bf16 v[24:27], v[162:165], v[190:193], v[24:27]
	v_mfma_f32_16x16x32_bf16 v[20:23], v[166:169], v[174:177], v[20:23]
	v_mfma_f32_16x16x32_bf16 v[16:19], v[166:169], v[182:185], v[16:19]
	v_mfma_f32_16x16x32_bf16 v[12:15], v[166:169], v[186:189], v[12:15]
	v_mfma_f32_16x16x32_bf16 v[8:11], v[166:169], v[190:193], v[8:11]
	v_mfma_f32_16x16x32_bf16 v[4:7], v[170:173], v[174:177], v[4:7]
	v_mfma_f32_16x16x32_bf16 v[0:3], v[170:173], v[182:185], v[0:3]
	v_mfma_f32_16x16x32_bf16 v[40:43], v[170:173], v[186:189], v[40:43]
	v_mfma_f32_16x16x32_bf16 v[36:39], v[170:173], v[190:193], v[36:39]
	ds_read_b128 v[158:161], v213 offset:8192
	ds_read_b128 v[162:165], v213 offset:10240
	ds_read_b128 v[166:169], v213 offset:12288
	ds_read_b128 v[170:173], v213 offset:14336
	s_waitcnt lgkmcnt(4)
	v_mfma_f32_16x16x32_bf16 v[124:127], v[142:145], v[194:197], v[124:127]
	v_mfma_f32_16x16x32_bf16 v[120:123], v[142:145], v[198:201], v[120:123]
	v_mfma_f32_16x16x32_bf16 v[116:119], v[142:145], v[202:205], v[116:119]
	v_mfma_f32_16x16x32_bf16 v[112:115], v[142:145], v[206:209], v[112:115]
	v_mfma_f32_16x16x32_bf16 v[108:111], v[146:149], v[194:197], v[108:111]
	v_mfma_f32_16x16x32_bf16 v[104:107], v[146:149], v[198:201], v[104:107]
	v_mfma_f32_16x16x32_bf16 v[100:103], v[146:149], v[202:205], v[100:103]
	v_mfma_f32_16x16x32_bf16 v[96:99], v[146:149], v[206:209], v[96:99]
	v_mfma_f32_16x16x32_bf16 v[92:95], v[150:153], v[194:197], v[92:95]
	v_mfma_f32_16x16x32_bf16 v[88:91], v[150:153], v[198:201], v[88:91]
	v_mfma_f32_16x16x32_bf16 v[84:87], v[150:153], v[202:205], v[84:87]
	v_mfma_f32_16x16x32_bf16 v[80:83], v[150:153], v[206:209], v[80:83]
	v_mfma_f32_16x16x32_bf16 v[76:79], v[154:157], v[194:197], v[76:79]
	v_mfma_f32_16x16x32_bf16 v[72:75], v[154:157], v[198:201], v[72:75]
	v_mfma_f32_16x16x32_bf16 v[68:71], v[154:157], v[202:205], v[68:71]
	v_mfma_f32_16x16x32_bf16 v[64:67], v[154:157], v[206:209], v[64:67]
	s_add_u32 s44, s44, 0x80
	s_addc_u32 s45, s45, 0
	s_add_i32 s43, s43, 1
	s_branch .Lg9_top

.LBB0_1488:
	v_mov_b32_e32 v6, v181
	s_ashr_i32 s51, s50, 6
	v_lshrrev_b32_e32 v7, 4, v6
	v_lshlrev_b32_e32 v1, 6, v6
	v_xor_b32_e32 v0, v7, v6
	v_and_b32_e32 v8, 0x3c0, v1
	v_lshlrev_b32_e32 v1, 7, v6
	s_bfe_u32 s52, s50, 0x20006
	s_and_b32 s56, s49, 63
	s_and_b32 s53, s50, 63
	s_and_b32 s20, s51, -4
	v_lshlrev_b32_e32 v0, 3, v0
	v_and_b32_e32 v1, 0xfffffc00, v1
	s_lshl_b32 s46, s56, 19
	s_or_b32 s42, s20, s52
	s_lshl_b32 s20, s53, 19
	v_and_or_b32 v0, v0, 56, v1
	s_add_u32 s20, s3, s20
	v_ashrrev_i32_e32 v1, 31, v0
	s_addc_u32 s21, s48, 0
	v_lshlrev_b64 v[0:1], 1, v[0:1]
	v_lshl_add_u32 v129, v6, 4, 0
	v_lshl_add_u64 v[2:3], s[20:21], 0, v[0:1]
	v_readfirstlane_b32 s20, v129
	v_add_u32_e32 v9, 0x2000, v129
	s_mov_b32 m0, s20
	v_readfirstlane_b32 s20, v9
	v_add_u32_e32 v9, 0x4000, v129
	s_waitcnt vmcnt(63) expcnt(7) lgkmcnt(15)
	s_barrier
	global_load_lds_dwordx4 v[2:3], off
	v_lshl_add_u64 v[4:5], v[2:3], 0, s[8:9]
	s_mov_b32 m0, s20
	v_readfirstlane_b32 s20, v9
	global_load_lds_dwordx4 v[4:5], off
	v_lshl_add_u64 v[4:5], v[2:3], 0, s[10:11]
	s_mov_b32 m0, s20
	s_ashr_i32 s43, s42, 31
	global_load_lds_dwordx4 v[4:5], off
	v_add_u32_e32 v4, 0x6000, v129
	s_lshl_b64 s[44:45], s[42:43], 19
	v_readfirstlane_b32 s20, v4
	v_lshl_add_u64 v[2:3], v[2:3], 0, s[12:13]
	s_mov_b32 m0, s20
	s_add_u32 s44, s34, s44
	global_load_lds_dwordx4 v[2:3], off
	v_add_u32_e32 v2, 0x8000, v129
	s_addc_u32 s45, s35, s45
	v_readfirstlane_b32 s20, v2
	v_add_u32_e32 v4, 0xa000, v129
	v_lshl_add_u64 v[134:135], s[44:45], 0, v[0:1]
	s_mov_b32 m0, s20
	v_readfirstlane_b32 s20, v4
	v_add_u32_e32 v4, 0xc000, v129
	global_load_lds_dwordx4 v[134:135], off
	v_lshl_add_u64 v[2:3], v[134:135], 0, s[8:9]
	s_mov_b32 m0, s20
	v_readfirstlane_b32 s20, v4
	v_add_u32_e32 v4, 0xe000, v129
	global_load_lds_dwordx4 v[2:3], off
	v_lshl_add_u64 v[2:3], v[134:135], 0, s[10:11]
	s_mov_b32 m0, s20
	v_readfirstlane_b32 s20, v4
	global_load_lds_dwordx4 v[2:3], off
	v_lshl_add_u64 v[2:3], v[134:135], 0, s[12:13]
	s_mov_b32 m0, s20
	v_ashrrev_i32_e32 v4, 6, v6
	global_load_lds_dwordx4 v[2:3], off
	v_lshrrev_b32_e32 v5, 30, v4
	v_add_u32_e32 v5, v4, v5
	v_bfe_u32 v2, v6, 4, 2
	v_bfe_u32 v3, v6, 1, 3
	v_and_b32_e32 v6, 0x7fffc, v5
	v_sub_u32_e32 v4, v4, v6
	v_lshlrev_b32_e32 v139, 13, v4
	v_bitop3_b32 v4, v7, v3, 3 bitop3:0x6c
	v_bitop3_b32 v2, v2, v3, 4 bitop3:0x36
	s_add_u32 s20, s34, s46
	v_lshlrev_b32_e32 v5, 12, v5
	v_lshlrev_b32_e32 v4, 3, v4
	v_lshlrev_b32_e32 v2, 3, v2
	s_addc_u32 s21, s35, 0
	v_and_b32_e32 v138, 0xffffc000, v5
	v_lshl_add_u64 v[136:137], s[20:21], 0, v[0:1]
	s_mov_b64 s[44:45], 0
	s_waitcnt lgkmcnt(0)
	v_lshlrev_b32_e32 v140, 1, v8
	v_lshlrev_b32_e32 v141, 1, v4
	v_lshlrev_b32_e32 v142, 1, v2
	s_mov_b32 s57, 0
	s_mov_b32 s43, 0
	v_mov_b32_e32 v8, v128
	v_mov_b32_e32 v9, v128
	v_mov_b32_e32 v10, v128
	v_mov_b32_e32 v11, v128
	v_mov_b32_e32 v20, v128
	v_mov_b32_e32 v21, v128
	v_mov_b32_e32 v22, v128
	v_mov_b32_e32 v23, v128
	v_mov_b32_e32 v0, v128
	v_mov_b32_e32 v1, v128
	v_mov_b32_e32 v2, v128
	v_mov_b32_e32 v3, v128
	v_mov_b32_e32 v4, v128
	v_mov_b32_e32 v5, v128
	v_mov_b32_e32 v6, v128
	v_mov_b32_e32 v7, v128
	v_mov_b32_e32 v12, v128
	v_mov_b32_e32 v13, v128
	v_mov_b32_e32 v14, v128
	v_mov_b32_e32 v15, v128
	v_mov_b32_e32 v24, v128
	v_mov_b32_e32 v25, v128
	v_mov_b32_e32 v26, v128
	v_mov_b32_e32 v27, v128
	v_mov_b32_e32 v16, v128
	v_mov_b32_e32 v17, v128
	v_mov_b32_e32 v18, v128
	v_mov_b32_e32 v19, v128
	v_mov_b32_e32 v28, v128
	v_mov_b32_e32 v29, v128
	v_mov_b32_e32 v30, v128
	v_mov_b32_e32 v31, v128
	v_mov_b32_e32 v32, v128
	v_mov_b32_e32 v33, v128
	v_mov_b32_e32 v34, v128
	v_mov_b32_e32 v35, v128
	v_mov_b32_e32 v40, v128
	v_mov_b32_e32 v41, v128
	v_mov_b32_e32 v42, v128
	v_mov_b32_e32 v43, v128
	v_mov_b32_e32 v36, v128
	v_mov_b32_e32 v37, v128
	v_mov_b32_e32 v38, v128
	v_mov_b32_e32 v39, v128
	v_mov_b32_e32 v44, v128
	v_mov_b32_e32 v45, v128
	v_mov_b32_e32 v46, v128
	v_mov_b32_e32 v47, v128
	v_mov_b32_e32 v48, v128
	v_mov_b32_e32 v49, v128
	v_mov_b32_e32 v50, v128
	v_mov_b32_e32 v51, v128
	v_mov_b32_e32 v56, v128
	v_mov_b32_e32 v57, v128
	v_mov_b32_e32 v58, v128
	v_mov_b32_e32 v59, v128
	v_mov_b32_e32 v52, v128
	v_mov_b32_e32 v53, v128
	v_mov_b32_e32 v54, v128
	v_mov_b32_e32 v55, v128
	v_mov_b32_e32 v60, v128
	v_mov_b32_e32 v61, v128
	v_mov_b32_e32 v62, v128
	v_mov_b32_e32 v63, v128
	v_mov_b32_e32 v64, v128
	v_mov_b32_e32 v65, v128
	v_mov_b32_e32 v66, v128
	v_mov_b32_e32 v67, v128
	v_mov_b32_e32 v72, v128
	v_mov_b32_e32 v73, v128
	v_mov_b32_e32 v74, v128
	v_mov_b32_e32 v75, v128
	v_mov_b32_e32 v68, v128
	v_mov_b32_e32 v69, v128
	v_mov_b32_e32 v70, v128
	v_mov_b32_e32 v71, v128
	v_mov_b32_e32 v76, v128
	v_mov_b32_e32 v77, v128
	v_mov_b32_e32 v78, v128
	v_mov_b32_e32 v79, v128
	v_mov_b32_e32 v80, v128
	v_mov_b32_e32 v81, v128
	v_mov_b32_e32 v82, v128
	v_mov_b32_e32 v83, v128
	v_mov_b32_e32 v88, v128
	v_mov_b32_e32 v89, v128
	v_mov_b32_e32 v90, v128
	v_mov_b32_e32 v91, v128
	v_mov_b32_e32 v84, v128
	v_mov_b32_e32 v85, v128
	v_mov_b32_e32 v86, v128
	v_mov_b32_e32 v87, v128
	v_mov_b32_e32 v92, v128
	v_mov_b32_e32 v93, v128
	v_mov_b32_e32 v94, v128
	v_mov_b32_e32 v95, v128
	v_mov_b32_e32 v96, v128
	v_mov_b32_e32 v97, v128
	v_mov_b32_e32 v98, v128
	v_mov_b32_e32 v99, v128
	v_mov_b32_e32 v104, v128
	v_mov_b32_e32 v105, v128
	v_mov_b32_e32 v106, v128
	v_mov_b32_e32 v107, v128
	v_mov_b32_e32 v100, v128
	v_mov_b32_e32 v101, v128
	v_mov_b32_e32 v102, v128
	v_mov_b32_e32 v103, v128
	v_mov_b32_e32 v108, v128
	v_mov_b32_e32 v109, v128
	v_mov_b32_e32 v110, v128
	v_mov_b32_e32 v111, v128
	v_mov_b32_e32 v112, v128
	v_mov_b32_e32 v113, v128
	v_mov_b32_e32 v114, v128
	v_mov_b32_e32 v115, v128
	v_mov_b32_e32 v120, v128
	v_mov_b32_e32 v121, v128
	v_mov_b32_e32 v122, v128
	v_mov_b32_e32 v123, v128
	v_mov_b32_e32 v116, v128
	v_mov_b32_e32 v117, v128
	v_mov_b32_e32 v118, v128
	v_mov_b32_e32 v119, v128
	v_mov_b32_e32 v124, v128
	v_mov_b32_e32 v125, v128
	v_mov_b32_e32 v126, v128
	v_mov_b32_e32 v127, v128
	s_waitcnt vmcnt(0) lgkmcnt(0)
	s_barrier
	v_add3_u32 v143, v138, v140, v141
	v_add3_u32 v180, v139, v140, v141
	v_add3_u32 v155, v138, v140, v142
	v_add3_u32 v222, v139, v140, v142
	v_readfirstlane_b32 s57, v129
	ds_read_b128 v[156:159], v143
	ds_read_b128 v[160:163], v143 offset:2048
	ds_read_b128 v[164:167], v143 offset:4096
	ds_read_b128 v[168:171], v143 offset:6144
	ds_read_b128 v[190:193], v180 offset:32768
	ds_read_b128 v[194:197], v180 offset:34816
	ds_read_b128 v[198:201], v180 offset:36864
	ds_read_b128 v[202:205], v180 offset:38912
	s_mov_b32 s43, 0
	s_mov_b64 s[44:45], s[34:35]
	v_subrev_u32_e32 v144, s34, v136
	v_subrev_u32_e32 v145, s34, v134
	v_xor_b32_e32 v223, 0x10000, v143
	v_xor_b32_e32 v224, 0x10000, v155
	v_xor_b32_e32 v225, 0x10000, v180
	v_xor_b32_e32 v226, 0x10000, v222
	s_add_u32 s57, s57, 0x10000
	v_add_u32_e32 v227, s16, v144
	v_add_u32_e32 v228, s18, v144
	v_add_u32_e32 v229, s22, v144
	v_add_u32_e32 v144, s14, v144
	v_add_u32_e32 v230, s36, v145
	v_add_u32_e32 v231, s38, v145
	v_add_u32_e32 v232, s40, v145
	v_add_u32_e32 v145, s30, v145
	s_mov_b32 m0, s57
	s_nop 0
	global_load_lds_dwordx4 v144, s[44:45]
	s_add_u32 m0, s57, 0x2000
	s_nop 0
	global_load_lds_dwordx4 v227, s[44:45]
	s_add_u32 m0, s57, 0x4000
	s_nop 0
	global_load_lds_dwordx4 v228, s[44:45]
	s_add_u32 m0, s57, 0x6000
	s_nop 0
	global_load_lds_dwordx4 v229, s[44:45]
	s_add_u32 m0, s57, 0x8000
	s_nop 0
	global_load_lds_dwordx4 v145, s[44:45]
	s_add_u32 m0, s57, 0xa000
	s_nop 0
	global_load_lds_dwordx4 v230, s[44:45]
	s_add_u32 m0, s57, 0xc000
	s_nop 0
	global_load_lds_dwordx4 v231, s[44:45]
	s_add_u32 m0, s57, 0xe000
	s_nop 0
	global_load_lds_dwordx4 v232, s[44:45]
	s_branch .Lg10_entry
.Lg10_top:
	s_waitcnt lgkmcnt(0)
	s_waitcnt vmcnt(0)
	s_barrier
	s_xor_b32 s57, s57, 0x10000
	ds_read_b128 v[156:159], v143
	ds_read_b128 v[160:163], v143 offset:2048
	ds_read_b128 v[164:167], v143 offset:4096
	ds_read_b128 v[168:171], v143 offset:6144
	ds_read_b128 v[190:193], v180 offset:32768
	ds_read_b128 v[194:197], v180 offset:34816
	ds_read_b128 v[198:201], v180 offset:36864
	ds_read_b128 v[202:205], v180 offset:38912
	s_mov_b32 m0, s57
	v_mfma_f32_16x16x32_bf16 v[60:63], v[172:175], v[206:209], v[60:63]
	v_mfma_f32_16x16x32_bf16 v[52:55], v[172:175], v[210:213], v[52:55]
	global_load_lds_dwordx4 v144, s[44:45]
	s_add_u32 m0, s57, 0x2000
	v_mfma_f32_16x16x32_bf16 v[56:59], v[172:175], v[214:217], v[56:59]
	v_mfma_f32_16x16x32_bf16 v[48:51], v[172:175], v[218:221], v[48:51]
	global_load_lds_dwordx4 v227, s[44:45]
	s_add_u32 m0, s57, 0x4000
	v_mfma_f32_16x16x32_bf16 v[44:47], v[176:179], v[206:209], v[44:47]
	v_mfma_f32_16x16x32_bf16 v[36:39], v[176:179], v[210:213], v[36:39]
	global_load_lds_dwordx4 v228, s[44:45]
	s_add_u32 m0, s57, 0x6000
	v_mfma_f32_16x16x32_bf16 v[40:43], v[176:179], v[214:217], v[40:43]
	v_mfma_f32_16x16x32_bf16 v[32:35], v[176:179], v[218:221], v[32:35]
	global_load_lds_dwordx4 v229, s[44:45]
	s_add_u32 m0, s57, 0x8000
	v_mfma_f32_16x16x32_bf16 v[28:31], v[182:185], v[206:209], v[28:31]
	v_mfma_f32_16x16x32_bf16 v[16:19], v[182:185], v[210:213], v[16:19]
	global_load_lds_dwordx4 v145, s[44:45]
	s_add_u32 m0, s57, 0xa000
	v_mfma_f32_16x16x32_bf16 v[24:27], v[182:185], v[214:217], v[24:27]
	v_mfma_f32_16x16x32_bf16 v[12:15], v[182:185], v[218:221], v[12:15]
	global_load_lds_dwordx4 v230, s[44:45]
	s_add_u32 m0, s57, 0xc000
	v_mfma_f32_16x16x32_bf16 v[4:7], v[186:189], v[206:209], v[4:7]
	v_mfma_f32_16x16x32_bf16 v[0:3], v[186:189], v[210:213], v[0:3]
	global_load_lds_dwordx4 v231, s[44:45]
	s_add_u32 m0, s57, 0xe000
	v_mfma_f32_16x16x32_bf16 v[20:23], v[186:189], v[214:217], v[20:23]
	v_mfma_f32_16x16x32_bf16 v[8:11], v[186:189], v[218:221], v[8:11]
	global_load_lds_dwordx4 v232, s[44:45]
.Lg10_entry:
	ds_read_b128 v[172:175], v143 offset:8192
	ds_read_b128 v[176:179], v143 offset:10240
	ds_read_b128 v[182:185], v143 offset:12288
	ds_read_b128 v[186:189], v143 offset:14336
	s_waitcnt lgkmcnt(4)
	v_mfma_f32_16x16x32_bf16 v[124:127], v[156:159], v[190:193], v[124:127]
	v_mfma_f32_16x16x32_bf16 v[116:119], v[156:159], v[194:197], v[116:119]
	v_mfma_f32_16x16x32_bf16 v[120:123], v[156:159], v[198:201], v[120:123]
	v_mfma_f32_16x16x32_bf16 v[112:115], v[156:159], v[202:205], v[112:115]
	v_mfma_f32_16x16x32_bf16 v[108:111], v[160:163], v[190:193], v[108:111]
	v_mfma_f32_16x16x32_bf16 v[100:103], v[160:163], v[194:197], v[100:103]
	v_mfma_f32_16x16x32_bf16 v[104:107], v[160:163], v[198:201], v[104:107]
	v_mfma_f32_16x16x32_bf16 v[96:99], v[160:163], v[202:205], v[96:99]
	v_mfma_f32_16x16x32_bf16 v[92:95], v[164:167], v[190:193], v[92:95]
	v_mfma_f32_16x16x32_bf16 v[84:87], v[164:167], v[194:197], v[84:87]
	v_mfma_f32_16x16x32_bf16 v[88:91], v[164:167], v[198:201], v[88:91]
	v_mfma_f32_16x16x32_bf16 v[80:83], v[164:167], v[202:205], v[80:83]
	v_mfma_f32_16x16x32_bf16 v[76:79], v[168:171], v[190:193], v[76:79]
	v_mfma_f32_16x16x32_bf16 v[68:71], v[168:171], v[194:197], v[68:71]
	v_mfma_f32_16x16x32_bf16 v[72:75], v[168:171], v[198:201], v[72:75]
	v_mfma_f32_16x16x32_bf16 v[64:67], v[168:171], v[202:205], v[64:67]
	ds_read_b128 v[156:159], v155
	ds_read_b128 v[160:163], v155 offset:2048
	ds_read_b128 v[164:167], v155 offset:4096
	ds_read_b128 v[168:171], v155 offset:6144
	ds_read_b128 v[206:209], v222 offset:32768
	ds_read_b128 v[210:213], v222 offset:34816
	ds_read_b128 v[214:217], v222 offset:36864
	ds_read_b128 v[218:221], v222 offset:38912
	s_waitcnt lgkmcnt(8)
	v_mfma_f32_16x16x32_bf16 v[60:63], v[172:175], v[190:193], v[60:63]
	v_mfma_f32_16x16x32_bf16 v[52:55], v[172:175], v[194:197], v[52:55]
	v_mfma_f32_16x16x32_bf16 v[56:59], v[172:175], v[198:201], v[56:59]
	v_mfma_f32_16x16x32_bf16 v[48:51], v[172:175], v[202:205], v[48:51]
	v_mfma_f32_16x16x32_bf16 v[44:47], v[176:179], v[190:193], v[44:47]
	v_mfma_f32_16x16x32_bf16 v[36:39], v[176:179], v[194:197], v[36:39]
	v_mfma_f32_16x16x32_bf16 v[40:43], v[176:179], v[198:201], v[40:43]
	v_mfma_f32_16x16x32_bf16 v[32:35], v[176:179], v[202:205], v[32:35]
	v_mfma_f32_16x16x32_bf16 v[28:31], v[182:185], v[190:193], v[28:31]
	v_mfma_f32_16x16x32_bf16 v[16:19], v[182:185], v[194:197], v[16:19]
	v_mfma_f32_16x16x32_bf16 v[24:27], v[182:185], v[198:201], v[24:27]
	v_mfma_f32_16x16x32_bf16 v[12:15], v[182:185], v[202:205], v[12:15]
	v_mfma_f32_16x16x32_bf16 v[4:7], v[186:189], v[190:193], v[4:7]
	v_mfma_f32_16x16x32_bf16 v[0:3], v[186:189], v[194:197], v[0:3]
	v_mfma_f32_16x16x32_bf16 v[20:23], v[186:189], v[198:201], v[20:23]
	v_mfma_f32_16x16x32_bf16 v[8:11], v[186:189], v[202:205], v[8:11]
	ds_read_b128 v[172:175], v155 offset:8192
	ds_read_b128 v[176:179], v155 offset:10240
	ds_read_b128 v[182:185], v155 offset:12288
	ds_read_b128 v[186:189], v155 offset:14336
	s_waitcnt lgkmcnt(4)
	v_mfma_f32_16x16x32_bf16 v[124:127], v[156:159], v[206:209], v[124:127]
	v_mfma_f32_16x16x32_bf16 v[116:119], v[156:159], v[210:213], v[116:119]
	v_mfma_f32_16x16x32_bf16 v[120:123], v[156:159], v[214:217], v[120:123]
	v_mfma_f32_16x16x32_bf16 v[112:115], v[156:159], v[218:221], v[112:115]
	v_mfma_f32_16x16x32_bf16 v[108:111], v[160:163], v[206:209], v[108:111]
	v_mfma_f32_16x16x32_bf16 v[100:103], v[160:163], v[210:213], v[100:103]
	v_mfma_f32_16x16x32_bf16 v[104:107], v[160:163], v[214:217], v[104:107]
	v_mfma_f32_16x16x32_bf16 v[96:99], v[160:163], v[218:221], v[96:99]
	v_mfma_f32_16x16x32_bf16 v[92:95], v[164:167], v[206:209], v[92:95]
	v_mfma_f32_16x16x32_bf16 v[84:87], v[164:167], v[210:213], v[84:87]
	v_mfma_f32_16x16x32_bf16 v[88:91], v[164:167], v[214:217], v[88:91]
	v_mfma_f32_16x16x32_bf16 v[80:83], v[164:167], v[218:221], v[80:83]
	v_mfma_f32_16x16x32_bf16 v[76:79], v[168:171], v[206:209], v[76:79]
	v_mfma_f32_16x16x32_bf16 v[68:71], v[168:171], v[210:213], v[68:71]
	v_mfma_f32_16x16x32_bf16 v[72:75], v[168:171], v[214:217], v[72:75]
	v_mfma_f32_16x16x32_bf16 v[64:67], v[168:171], v[218:221], v[64:67]
	s_add_u32 s44, s44, 0x80
	s_addc_u32 s45, s45, 0
	s_add_i32 s43, s43, 1
	s_cmp_lt_u32 s43, 15
	s_cbranch_scc0 .Lg10_last
	s_waitcnt lgkmcnt(0)
	s_waitcnt vmcnt(0)
	s_barrier
	s_xor_b32 s57, s57, 0x10000
	ds_read_b128 v[156:159], v223
	ds_read_b128 v[160:163], v223 offset:2048
	ds_read_b128 v[164:167], v223 offset:4096
	ds_read_b128 v[168:171], v223 offset:6144
	ds_read_b128 v[190:193], v225 offset:32768
	ds_read_b128 v[194:197], v225 offset:34816
	ds_read_b128 v[198:201], v225 offset:36864
	ds_read_b128 v[202:205], v225 offset:38912
	s_mov_b32 m0, s57
	v_mfma_f32_16x16x32_bf16 v[60:63], v[172:175], v[206:209], v[60:63]
	v_mfma_f32_16x16x32_bf16 v[52:55], v[172:175], v[210:213], v[52:55]
	global_load_lds_dwordx4 v144, s[44:45]
	s_add_u32 m0, s57, 0x2000
	v_mfma_f32_16x16x32_bf16 v[56:59], v[172:175], v[214:217], v[56:59]
	v_mfma_f32_16x16x32_bf16 v[48:51], v[172:175], v[218:221], v[48:51]
	global_load_lds_dwordx4 v227, s[44:45]
	s_add_u32 m0, s57, 0x4000
	v_mfma_f32_16x16x32_bf16 v[44:47], v[176:179], v[206:209], v[44:47]
	v_mfma_f32_16x16x32_bf16 v[36:39], v[176:179], v[210:213], v[36:39]
	global_load_lds_dwordx4 v228, s[44:45]
	s_add_u32 m0, s57, 0x6000
	v_mfma_f32_16x16x32_bf16 v[40:43], v[176:179], v[214:217], v[40:43]
	v_mfma_f32_16x16x32_bf16 v[32:35], v[176:179], v[218:221], v[32:35]
	global_load_lds_dwordx4 v229, s[44:45]
	s_add_u32 m0, s57, 0x8000
	v_mfma_f32_16x16x32_bf16 v[28:31], v[182:185], v[206:209], v[28:31]
	v_mfma_f32_16x16x32_bf16 v[16:19], v[182:185], v[210:213], v[16:19]
	global_load_lds_dwordx4 v145, s[44:45]
	s_add_u32 m0, s57, 0xa000
	v_mfma_f32_16x16x32_bf16 v[24:27], v[182:185], v[214:217], v[24:27]
	v_mfma_f32_16x16x32_bf16 v[12:15], v[182:185], v[218:221], v[12:15]
	global_load_lds_dwordx4 v230, s[44:45]
	s_add_u32 m0, s57, 0xc000
	v_mfma_f32_16x16x32_bf16 v[4:7], v[186:189], v[206:209], v[4:7]
	v_mfma_f32_16x16x32_bf16 v[0:3], v[186:189], v[210:213], v[0:3]
	global_load_lds_dwordx4 v231, s[44:45]
	s_add_u32 m0, s57, 0xe000
	v_mfma_f32_16x16x32_bf16 v[20:23], v[186:189], v[214:217], v[20:23]
	v_mfma_f32_16x16x32_bf16 v[8:11], v[186:189], v[218:221], v[8:11]
	global_load_lds_dwordx4 v232, s[44:45]
	ds_read_b128 v[172:175], v223 offset:8192
	ds_read_b128 v[176:179], v223 offset:10240
	ds_read_b128 v[182:185], v223 offset:12288
	ds_read_b128 v[186:189], v223 offset:14336
	s_waitcnt lgkmcnt(4)
	v_mfma_f32_16x16x32_bf16 v[124:127], v[156:159], v[190:193], v[124:127]
	v_mfma_f32_16x16x32_bf16 v[116:119], v[156:159], v[194:197], v[116:119]
	v_mfma_f32_16x16x32_bf16 v[120:123], v[156:159], v[198:201], v[120:123]
	v_mfma_f32_16x16x32_bf16 v[112:115], v[156:159], v[202:205], v[112:115]
	v_mfma_f32_16x16x32_bf16 v[108:111], v[160:163], v[190:193], v[108:111]
	v_mfma_f32_16x16x32_bf16 v[100:103], v[160:163], v[194:197], v[100:103]
	v_mfma_f32_16x16x32_bf16 v[104:107], v[160:163], v[198:201], v[104:107]
	v_mfma_f32_16x16x32_bf16 v[96:99], v[160:163], v[202:205], v[96:99]
	v_mfma_f32_16x16x32_bf16 v[92:95], v[164:167], v[190:193], v[92:95]
	v_mfma_f32_16x16x32_bf16 v[84:87], v[164:167], v[194:197], v[84:87]
	v_mfma_f32_16x16x32_bf16 v[88:91], v[164:167], v[198:201], v[88:91]
	v_mfma_f32_16x16x32_bf16 v[80:83], v[164:167], v[202:205], v[80:83]
	v_mfma_f32_16x16x32_bf16 v[76:79], v[168:171], v[190:193], v[76:79]
	v_mfma_f32_16x16x32_bf16 v[68:71], v[168:171], v[194:197], v[68:71]
	v_mfma_f32_16x16x32_bf16 v[72:75], v[168:171], v[198:201], v[72:75]
	v_mfma_f32_16x16x32_bf16 v[64:67], v[168:171], v[202:205], v[64:67]
	ds_read_b128 v[156:159], v224
	ds_read_b128 v[160:163], v224 offset:2048
	ds_read_b128 v[164:167], v224 offset:4096
	ds_read_b128 v[168:171], v224 offset:6144
	ds_read_b128 v[206:209], v226 offset:32768
	ds_read_b128 v[210:213], v226 offset:34816
	ds_read_b128 v[214:217], v226 offset:36864
	ds_read_b128 v[218:221], v226 offset:38912
	s_waitcnt lgkmcnt(8)
	v_mfma_f32_16x16x32_bf16 v[60:63], v[172:175], v[190:193], v[60:63]
	v_mfma_f32_16x16x32_bf16 v[52:55], v[172:175], v[194:197], v[52:55]
	v_mfma_f32_16x16x32_bf16 v[56:59], v[172:175], v[198:201], v[56:59]
	v_mfma_f32_16x16x32_bf16 v[48:51], v[172:175], v[202:205], v[48:51]
	v_mfma_f32_16x16x32_bf16 v[44:47], v[176:179], v[190:193], v[44:47]
	v_mfma_f32_16x16x32_bf16 v[36:39], v[176:179], v[194:197], v[36:39]
	v_mfma_f32_16x16x32_bf16 v[40:43], v[176:179], v[198:201], v[40:43]
	v_mfma_f32_16x16x32_bf16 v[32:35], v[176:179], v[202:205], v[32:35]
	v_mfma_f32_16x16x32_bf16 v[28:31], v[182:185], v[190:193], v[28:31]
	v_mfma_f32_16x16x32_bf16 v[16:19], v[182:185], v[194:197], v[16:19]
	v_mfma_f32_16x16x32_bf16 v[24:27], v[182:185], v[198:201], v[24:27]
	v_mfma_f32_16x16x32_bf16 v[12:15], v[182:185], v[202:205], v[12:15]
	v_mfma_f32_16x16x32_bf16 v[4:7], v[186:189], v[190:193], v[4:7]
	v_mfma_f32_16x16x32_bf16 v[0:3], v[186:189], v[194:197], v[0:3]
	v_mfma_f32_16x16x32_bf16 v[20:23], v[186:189], v[198:201], v[20:23]
	v_mfma_f32_16x16x32_bf16 v[8:11], v[186:189], v[202:205], v[8:11]
	ds_read_b128 v[172:175], v224 offset:8192
	ds_read_b128 v[176:179], v224 offset:10240
	ds_read_b128 v[182:185], v224 offset:12288
	ds_read_b128 v[186:189], v224 offset:14336
	s_waitcnt lgkmcnt(4)
	v_mfma_f32_16x16x32_bf16 v[124:127], v[156:159], v[206:209], v[124:127]
	v_mfma_f32_16x16x32_bf16 v[116:119], v[156:159], v[210:213], v[116:119]
	v_mfma_f32_16x16x32_bf16 v[120:123], v[156:159], v[214:217], v[120:123]
	v_mfma_f32_16x16x32_bf16 v[112:115], v[156:159], v[218:221], v[112:115]
	v_mfma_f32_16x16x32_bf16 v[108:111], v[160:163], v[206:209], v[108:111]
	v_mfma_f32_16x16x32_bf16 v[100:103], v[160:163], v[210:213], v[100:103]
	v_mfma_f32_16x16x32_bf16 v[104:107], v[160:163], v[214:217], v[104:107]
	v_mfma_f32_16x16x32_bf16 v[96:99], v[160:163], v[218:221], v[96:99]
	v_mfma_f32_16x16x32_bf16 v[92:95], v[164:167], v[206:209], v[92:95]
	v_mfma_f32_16x16x32_bf16 v[84:87], v[164:167], v[210:213], v[84:87]
	v_mfma_f32_16x16x32_bf16 v[88:91], v[164:167], v[214:217], v[88:91]
	v_mfma_f32_16x16x32_bf16 v[80:83], v[164:167], v[218:221], v[80:83]
	v_mfma_f32_16x16x32_bf16 v[76:79], v[168:171], v[206:209], v[76:79]
	v_mfma_f32_16x16x32_bf16 v[68:71], v[168:171], v[210:213], v[68:71]
	v_mfma_f32_16x16x32_bf16 v[72:75], v[168:171], v[214:217], v[72:75]
	v_mfma_f32_16x16x32_bf16 v[64:67], v[168:171], v[218:221], v[64:67]
	s_add_u32 s44, s44, 0x80
	s_addc_u32 s45, s45, 0
	s_add_i32 s43, s43, 1
	s_branch .Lg10_top

.LBB0_1636:
	s_ashr_i32 s20, s44, 2
	v_mov_b32_e32 v6, v181
	s_and_b32 s4, s44, 7
	s_and_b32 s39, s20, -8
	s_or_b32 s30, s39, s4
	v_lshrrev_b32_e32 v7, 4, v6
	v_lshlrev_b32_e32 v1, 6, v6
	v_xor_b32_e32 v0, v7, v6
	v_and_b32_e32 v8, 0x3c0, v1
	v_lshlrev_b32_e32 v1, 8, v6
	s_ashr_i32 s31, s30, 31
	v_lshlrev_b32_e32 v0, 3, v0
	v_and_b32_e32 v1, 0xfffff800, v1
	s_and_b32 s38, s43, 7
	s_bfe_u32 s4, s44, 0x20003
	s_lshl_b64 s[20:21], s[30:31], 20
	v_and_or_b32 v0, v0, 56, v1
	s_add_u32 s20, s3, s20
	v_ashrrev_i32_e32 v1, 31, v0
	s_addc_u32 s21, s40, s21
	v_lshlrev_b64 v[0:1], 1, v[0:1]
	v_lshl_add_u32 v134, v6, 4, 0
	v_lshl_add_u64 v[2:3], s[20:21], 0, v[0:1]
	v_readfirstlane_b32 s20, v134
	v_add_u32_e32 v9, 0x2000, v134
	s_mov_b32 m0, s20
	v_readfirstlane_b32 s20, v9
	v_add_u32_e32 v9, 0x4000, v134
	s_waitcnt vmcnt(63) expcnt(7) lgkmcnt(15)
	s_barrier
	global_load_lds_dwordx4 v[2:3], off
	v_lshl_add_u64 v[4:5], v[2:3], 0, s[6:7]
	s_mov_b32 m0, s20
	v_readfirstlane_b32 s20, v9
	global_load_lds_dwordx4 v[4:5], off
	v_lshl_add_u64 v[4:5], v[2:3], 0, s[8:9]
	s_mov_b32 m0, s20
	s_lshl_b32 s31, s4, 20
	global_load_lds_dwordx4 v[4:5], off
	v_add_u32_e32 v4, 0x6000, v134
	s_add_u32 s36, s41, s31
	v_readfirstlane_b32 s20, v4
	v_add_u32_e32 v4, 0x8000, v134
	s_addc_u32 s37, s42, 0
	v_lshl_add_u64 v[2:3], v[2:3], 0, s[10:11]
	s_mov_b32 m0, s20
	v_readfirstlane_b32 s20, v4
	v_add_u32_e32 v9, 0xa000, v134
	global_load_lds_dwordx4 v[2:3], off
	v_lshl_add_u64 v[2:3], s[36:37], 0, v[0:1]
	s_mov_b32 m0, s20
	v_readfirstlane_b32 s20, v9
	v_add_u32_e32 v9, 0xc000, v134
	global_load_lds_dwordx4 v[2:3], off
	v_lshl_add_u64 v[4:5], v[2:3], 0, s[6:7]
	s_mov_b32 m0, s20
	v_readfirstlane_b32 s20, v9
	global_load_lds_dwordx4 v[4:5], off
	v_lshl_add_u64 v[4:5], v[2:3], 0, s[8:9]
	s_mov_b32 m0, s20
	v_lshl_add_u64 v[2:3], v[2:3], 0, s[10:11]
	global_load_lds_dwordx4 v[4:5], off
	v_add_u32_e32 v4, 0xe000, v134
	v_mov_b32_e32 v36, 0
	v_readfirstlane_b32 s20, v4
	s_mov_b32 m0, s20
	v_ashrrev_i32_e32 v4, 6, v6
	global_load_lds_dwordx4 v[2:3], off
	s_or_b32 s20, s39, s38
	v_lshrrev_b32_e32 v5, 30, v4
	s_ashr_i32 s21, s20, 31
	v_add_u32_e32 v5, v4, v5
	s_lshl_b64 s[20:21], s[20:21], 20
	v_bfe_u32 v2, v6, 4, 2
	v_bfe_u32 v3, v6, 1, 3
	v_and_b32_e32 v6, 0x7fffc, v5
	s_add_u32 s20, s34, s20
	v_sub_u32_e32 v4, v4, v6
	s_addc_u32 s21, s35, s21
	v_lshlrev_b32_e32 v136, 13, v4
	v_bitop3_b32 v4, v7, v3, 3 bitop3:0x6c
	v_bitop3_b32 v2, v2, v3, 4 bitop3:0x36
	v_lshl_add_u64 v[130:131], s[20:21], 0, v[0:1]
	s_add_u32 s20, s34, s31
	v_lshlrev_b32_e32 v5, 12, v5
	v_lshlrev_b32_e32 v4, 3, v4
	v_lshlrev_b32_e32 v2, 3, v2
	s_addc_u32 s21, s35, 0
	v_and_b32_e32 v135, 0xffffc000, v5
	v_lshl_add_u64 v[132:133], s[20:21], 0, v[0:1]
	s_mov_b64 s[36:37], 0
	v_lshlrev_b32_e32 v137, 1, v8
	v_lshlrev_b32_e32 v138, 1, v4
	v_lshlrev_b32_e32 v139, 1, v2
	s_mov_b32 s45, 0
	s_mov_b32 s31, 0
	v_mov_b32_e32 v37, v36
	v_mov_b32_e32 v38, v36
	v_mov_b32_e32 v39, v36
	v_mov_b32_e32 v40, v36
	v_mov_b32_e32 v41, v36
	v_mov_b32_e32 v42, v36
	v_mov_b32_e32 v43, v36
	v_mov_b32_e32 v0, v36
	v_mov_b32_e32 v1, v36
	v_mov_b32_e32 v2, v36
	v_mov_b32_e32 v3, v36
	v_mov_b32_e32 v4, v36
	v_mov_b32_e32 v5, v36
	v_mov_b32_e32 v6, v36
	v_mov_b32_e32 v7, v36
	v_mov_b32_e32 v8, v36
	v_mov_b32_e32 v9, v36
	v_mov_b32_e32 v10, v36
	v_mov_b32_e32 v11, v36
	v_mov_b32_e32 v12, v36
	v_mov_b32_e32 v13, v36
	v_mov_b32_e32 v14, v36
	v_mov_b32_e32 v15, v36
	v_mov_b32_e32 v16, v36
	v_mov_b32_e32 v17, v36
	v_mov_b32_e32 v18, v36
	v_mov_b32_e32 v19, v36
	v_mov_b32_e32 v20, v36
	v_mov_b32_e32 v21, v36
	v_mov_b32_e32 v22, v36
	v_mov_b32_e32 v23, v36
	v_mov_b32_e32 v24, v36
	v_mov_b32_e32 v25, v36
	v_mov_b32_e32 v26, v36
	v_mov_b32_e32 v27, v36
	v_mov_b32_e32 v28, v36
	v_mov_b32_e32 v29, v36
	v_mov_b32_e32 v30, v36
	v_mov_b32_e32 v31, v36
	v_mov_b32_e32 v32, v36
	v_mov_b32_e32 v33, v36
	v_mov_b32_e32 v34, v36
	v_mov_b32_e32 v35, v36
	v_mov_b32_e32 v44, v36
	v_mov_b32_e32 v45, v36
	v_mov_b32_e32 v46, v36
	v_mov_b32_e32 v47, v36
	v_mov_b32_e32 v48, v36
	v_mov_b32_e32 v49, v36
	v_mov_b32_e32 v50, v36
	v_mov_b32_e32 v51, v36
	v_mov_b32_e32 v52, v36
	v_mov_b32_e32 v53, v36
	v_mov_b32_e32 v54, v36
	v_mov_b32_e32 v55, v36
	v_mov_b32_e32 v56, v36
	v_mov_b32_e32 v57, v36
	v_mov_b32_e32 v58, v36
	v_mov_b32_e32 v59, v36
	v_mov_b32_e32 v60, v36
	v_mov_b32_e32 v61, v36
	v_mov_b32_e32 v62, v36
	v_mov_b32_e32 v63, v36
	v_mov_b32_e32 v64, v36
	v_mov_b32_e32 v65, v36
	v_mov_b32_e32 v66, v36
	v_mov_b32_e32 v67, v36
	v_mov_b32_e32 v68, v36
	v_mov_b32_e32 v69, v36
	v_mov_b32_e32 v70, v36
	v_mov_b32_e32 v71, v36
	v_mov_b32_e32 v72, v36
	v_mov_b32_e32 v73, v36
	v_mov_b32_e32 v74, v36
	v_mov_b32_e32 v75, v36
	v_mov_b32_e32 v76, v36
	v_mov_b32_e32 v77, v36
	v_mov_b32_e32 v78, v36
	v_mov_b32_e32 v79, v36
	v_mov_b32_e32 v80, v36
	v_mov_b32_e32 v81, v36
	v_mov_b32_e32 v82, v36
	v_mov_b32_e32 v83, v36
	v_mov_b32_e32 v84, v36
	v_mov_b32_e32 v85, v36
	v_mov_b32_e32 v86, v36
	v_mov_b32_e32 v87, v36
	v_mov_b32_e32 v88, v36
	v_mov_b32_e32 v89, v36
	v_mov_b32_e32 v90, v36
	v_mov_b32_e32 v91, v36
	v_mov_b32_e32 v92, v36
	v_mov_b32_e32 v93, v36
	v_mov_b32_e32 v94, v36
	v_mov_b32_e32 v95, v36
	v_mov_b32_e32 v96, v36
	v_mov_b32_e32 v97, v36
	v_mov_b32_e32 v98, v36
	v_mov_b32_e32 v99, v36
	v_mov_b32_e32 v100, v36
	v_mov_b32_e32 v101, v36
	v_mov_b32_e32 v102, v36
	v_mov_b32_e32 v103, v36
	v_mov_b32_e32 v104, v36
	v_mov_b32_e32 v105, v36
	v_mov_b32_e32 v106, v36
	v_mov_b32_e32 v107, v36
	v_mov_b32_e32 v108, v36
	v_mov_b32_e32 v109, v36
	v_mov_b32_e32 v110, v36
	v_mov_b32_e32 v111, v36
	v_mov_b32_e32 v112, v36
	v_mov_b32_e32 v113, v36
	v_mov_b32_e32 v114, v36
	v_mov_b32_e32 v115, v36
	v_mov_b32_e32 v116, v36
	v_mov_b32_e32 v117, v36
	v_mov_b32_e32 v118, v36
	v_mov_b32_e32 v119, v36
	v_mov_b32_e32 v120, v36
	v_mov_b32_e32 v121, v36
	v_mov_b32_e32 v122, v36
	v_mov_b32_e32 v123, v36
	v_mov_b32_e32 v124, v36
	v_mov_b32_e32 v125, v36
	v_mov_b32_e32 v126, v36
	v_mov_b32_e32 v127, v36
	s_waitcnt vmcnt(0) lgkmcnt(0)
	s_barrier
	v_add3_u32 v141, v135, v137, v138
	v_add3_u32 v210, v136, v137, v138
	v_add3_u32 v180, v135, v137, v139
	v_add3_u32 v211, v136, v137, v139
	v_readfirstlane_b32 s45, v134
	ds_read_b128 v[142:145], v141
	ds_read_b128 v[146:149], v141 offset:2048
	ds_read_b128 v[150:153], v141 offset:4096
	ds_read_b128 v[154:157], v141 offset:6144
	ds_read_b128 v[174:177], v210 offset:32768
	ds_read_b128 v[182:185], v210 offset:34816
	ds_read_b128 v[186:189], v210 offset:36864
	ds_read_b128 v[190:193], v210 offset:38912
	s_mov_b32 s31, 0
	s_mov_b64 s[36:37], s[34:35]
	v_subrev_u32_e32 v178, s34, v130
	v_subrev_u32_e32 v179, s34, v132
	v_xor_b32_e32 v212, 0x10000, v141
	v_xor_b32_e32 v213, 0x10000, v180
	v_xor_b32_e32 v214, 0x10000, v210
	v_xor_b32_e32 v215, 0x10000, v211
	s_add_u32 s45, s45, 0x10000
	v_add_u32_e32 v216, s14, v178
	v_add_u32_e32 v217, s16, v178
	v_add_u32_e32 v218, s18, v178
	v_add_u32_e32 v178, s12, v178
	v_add_u32_e32 v219, s24, v179
	v_add_u32_e32 v220, s26, v179
	v_add_u32_e32 v221, s28, v179
	v_add_u32_e32 v179, s22, v179
	s_mov_b32 m0, s45
	s_nop 0
	global_load_lds_dwordx4 v178, s[36:37]
	s_add_u32 m0, s45, 0x2000
	s_nop 0
	global_load_lds_dwordx4 v216, s[36:37]
	s_add_u32 m0, s45, 0x4000
	s_nop 0
	global_load_lds_dwordx4 v217, s[36:37]
	s_add_u32 m0, s45, 0x6000
	s_nop 0
	global_load_lds_dwordx4 v218, s[36:37]
	s_add_u32 m0, s45, 0x8000
	s_nop 0
	global_load_lds_dwordx4 v179, s[36:37]
	s_add_u32 m0, s45, 0xa000
	s_nop 0
	global_load_lds_dwordx4 v219, s[36:37]
	s_add_u32 m0, s45, 0xc000
	s_nop 0
	global_load_lds_dwordx4 v220, s[36:37]
	s_add_u32 m0, s45, 0xe000
	s_nop 0
	global_load_lds_dwordx4 v221, s[36:37]
	s_branch .Lg11_entry
.Lg11_top:
	s_waitcnt lgkmcnt(0)
	s_waitcnt vmcnt(0)
	s_barrier
	s_xor_b32 s45, s45, 0x10000
	ds_read_b128 v[142:145], v141
	ds_read_b128 v[146:149], v141 offset:2048
	ds_read_b128 v[150:153], v141 offset:4096
	ds_read_b128 v[154:157], v141 offset:6144
	ds_read_b128 v[174:177], v210 offset:32768
	ds_read_b128 v[182:185], v210 offset:34816
	ds_read_b128 v[186:189], v210 offset:36864
	ds_read_b128 v[190:193], v210 offset:38912
	s_mov_b32 m0, s45
	v_mfma_f32_16x16x32_bf16 v[60:63], v[158:161], v[194:197], v[60:63]
	v_mfma_f32_16x16x32_bf16 v[56:59], v[158:161], v[198:201], v[56:59]
	global_load_lds_dwordx4 v178, s[36:37]
	s_add_u32 m0, s45, 0x2000
	v_mfma_f32_16x16x32_bf16 v[52:55], v[158:161], v[202:205], v[52:55]
	v_mfma_f32_16x16x32_bf16 v[48:51], v[158:161], v[206:209], v[48:51]
	global_load_lds_dwordx4 v216, s[36:37]
	s_add_u32 m0, s45, 0x4000
	v_mfma_f32_16x16x32_bf16 v[44:47], v[162:165], v[194:197], v[44:47]
	v_mfma_f32_16x16x32_bf16 v[32:35], v[162:165], v[198:201], v[32:35]
	global_load_lds_dwordx4 v217, s[36:37]
	s_add_u32 m0, s45, 0x6000
	v_mfma_f32_16x16x32_bf16 v[28:31], v[162:165], v[202:205], v[28:31]
	v_mfma_f32_16x16x32_bf16 v[24:27], v[162:165], v[206:209], v[24:27]
	global_load_lds_dwordx4 v218, s[36:37]
	s_add_u32 m0, s45, 0x8000
	v_mfma_f32_16x16x32_bf16 v[20:23], v[166:169], v[194:197], v[20:23]
	v_mfma_f32_16x16x32_bf16 v[16:19], v[166:169], v[198:201], v[16:19]
	global_load_lds_dwordx4 v179, s[36:37]
	s_add_u32 m0, s45, 0xa000
	v_mfma_f32_16x16x32_bf16 v[12:15], v[166:169], v[202:205], v[12:15]
	v_mfma_f32_16x16x32_bf16 v[8:11], v[166:169], v[206:209], v[8:11]
	global_load_lds_dwordx4 v219, s[36:37]
	s_add_u32 m0, s45, 0xc000
	v_mfma_f32_16x16x32_bf16 v[4:7], v[170:173], v[194:197], v[4:7]
	v_mfma_f32_16x16x32_bf16 v[0:3], v[170:173], v[198:201], v[0:3]
	global_load_lds_dwordx4 v220, s[36:37]
	s_add_u32 m0, s45, 0xe000
	v_mfma_f32_16x16x32_bf16 v[40:43], v[170:173], v[202:205], v[40:43]
	v_mfma_f32_16x16x32_bf16 v[36:39], v[170:173], v[206:209], v[36:39]
	global_load_lds_dwordx4 v221, s[36:37]
.Lg11_entry:
	ds_read_b128 v[158:161], v141 offset:8192
	ds_read_b128 v[162:165], v141 offset:10240
	ds_read_b128 v[166:169], v141 offset:12288
	ds_read_b128 v[170:173], v141 offset:14336
	s_waitcnt lgkmcnt(4)
	v_mfma_f32_16x16x32_bf16 v[124:127], v[142:145], v[174:177], v[124:127]
	v_mfma_f32_16x16x32_bf16 v[120:123], v[142:145], v[182:185], v[120:123]
	v_mfma_f32_16x16x32_bf16 v[116:119], v[142:145], v[186:189], v[116:119]
	v_mfma_f32_16x16x32_bf16 v[112:115], v[142:145], v[190:193], v[112:115]
	v_mfma_f32_16x16x32_bf16 v[108:111], v[146:149], v[174:177], v[108:111]
	v_mfma_f32_16x16x32_bf16 v[104:107], v[146:149], v[182:185], v[104:107]
	v_mfma_f32_16x16x32_bf16 v[100:103], v[146:149], v[186:189], v[100:103]
	v_mfma_f32_16x16x32_bf16 v[96:99], v[146:149], v[190:193], v[96:99]
	v_mfma_f32_16x16x32_bf16 v[92:95], v[150:153], v[174:177], v[92:95]
	v_mfma_f32_16x16x32_bf16 v[88:91], v[150:153], v[182:185], v[88:91]
	v_mfma_f32_16x16x32_bf16 v[84:87], v[150:153], v[186:189], v[84:87]
	v_mfma_f32_16x16x32_bf16 v[80:83], v[150:153], v[190:193], v[80:83]
	v_mfma_f32_16x16x32_bf16 v[76:79], v[154:157], v[174:177], v[76:79]
	v_mfma_f32_16x16x32_bf16 v[72:75], v[154:157], v[182:185], v[72:75]
	v_mfma_f32_16x16x32_bf16 v[68:71], v[154:157], v[186:189], v[68:71]
	v_mfma_f32_16x16x32_bf16 v[64:67], v[154:157], v[190:193], v[64:67]
	ds_read_b128 v[142:145], v180
	ds_read_b128 v[146:149], v180 offset:2048
	ds_read_b128 v[150:153], v180 offset:4096
	ds_read_b128 v[154:157], v180 offset:6144
	ds_read_b128 v[194:197], v211 offset:32768
	ds_read_b128 v[198:201], v211 offset:34816
	ds_read_b128 v[202:205], v211 offset:36864
	ds_read_b128 v[206:209], v211 offset:38912
	s_waitcnt lgkmcnt(8)
	v_mfma_f32_16x16x32_bf16 v[60:63], v[158:161], v[174:177], v[60:63]
	v_mfma_f32_16x16x32_bf16 v[56:59], v[158:161], v[182:185], v[56:59]
	v_mfma_f32_16x16x32_bf16 v[52:55], v[158:161], v[186:189], v[52:55]
	v_mfma_f32_16x16x32_bf16 v[48:51], v[158:161], v[190:193], v[48:51]
	v_mfma_f32_16x16x32_bf16 v[44:47], v[162:165], v[174:177], v[44:47]
	v_mfma_f32_16x16x32_bf16 v[32:35], v[162:165], v[182:185], v[32:35]
	v_mfma_f32_16x16x32_bf16 v[28:31], v[162:165], v[186:189], v[28:31]
	v_mfma_f32_16x16x32_bf16 v[24:27], v[162:165], v[190:193], v[24:27]
	v_mfma_f32_16x16x32_bf16 v[20:23], v[166:169], v[174:177], v[20:23]
	v_mfma_f32_16x16x32_bf16 v[16:19], v[166:169], v[182:185], v[16:19]
	v_mfma_f32_16x16x32_bf16 v[12:15], v[166:169], v[186:189], v[12:15]
	v_mfma_f32_16x16x32_bf16 v[8:11], v[166:169], v[190:193], v[8:11]
	v_mfma_f32_16x16x32_bf16 v[4:7], v[170:173], v[174:177], v[4:7]
	v_mfma_f32_16x16x32_bf16 v[0:3], v[170:173], v[182:185], v[0:3]
	v_mfma_f32_16x16x32_bf16 v[40:43], v[170:173], v[186:189], v[40:43]
	v_mfma_f32_16x16x32_bf16 v[36:39], v[170:173], v[190:193], v[36:39]
	ds_read_b128 v[158:161], v180 offset:8192
	ds_read_b128 v[162:165], v180 offset:10240
	ds_read_b128 v[166:169], v180 offset:12288
	ds_read_b128 v[170:173], v180 offset:14336
	s_waitcnt lgkmcnt(4)
	v_mfma_f32_16x16x32_bf16 v[124:127], v[142:145], v[194:197], v[124:127]
	v_mfma_f32_16x16x32_bf16 v[120:123], v[142:145], v[198:201], v[120:123]
	v_mfma_f32_16x16x32_bf16 v[116:119], v[142:145], v[202:205], v[116:119]
	v_mfma_f32_16x16x32_bf16 v[112:115], v[142:145], v[206:209], v[112:115]
	v_mfma_f32_16x16x32_bf16 v[108:111], v[146:149], v[194:197], v[108:111]
	v_mfma_f32_16x16x32_bf16 v[104:107], v[146:149], v[198:201], v[104:107]
	v_mfma_f32_16x16x32_bf16 v[100:103], v[146:149], v[202:205], v[100:103]
	v_mfma_f32_16x16x32_bf16 v[96:99], v[146:149], v[206:209], v[96:99]
	v_mfma_f32_16x16x32_bf16 v[92:95], v[150:153], v[194:197], v[92:95]
	v_mfma_f32_16x16x32_bf16 v[88:91], v[150:153], v[198:201], v[88:91]
	v_mfma_f32_16x16x32_bf16 v[84:87], v[150:153], v[202:205], v[84:87]
	v_mfma_f32_16x16x32_bf16 v[80:83], v[150:153], v[206:209], v[80:83]
	v_mfma_f32_16x16x32_bf16 v[76:79], v[154:157], v[194:197], v[76:79]
	v_mfma_f32_16x16x32_bf16 v[72:75], v[154:157], v[198:201], v[72:75]
	v_mfma_f32_16x16x32_bf16 v[68:71], v[154:157], v[202:205], v[68:71]
	v_mfma_f32_16x16x32_bf16 v[64:67], v[154:157], v[206:209], v[64:67]
	s_add_u32 s36, s36, 0x80
	s_addc_u32 s37, s37, 0
	s_add_i32 s31, s31, 1
	s_cmp_lt_u32 s31, 31
	s_cbranch_scc0 .Lg11_last
	s_waitcnt lgkmcnt(0)
	s_waitcnt vmcnt(0)
	s_barrier
	s_xor_b32 s45, s45, 0x10000
	ds_read_b128 v[142:145], v212
	ds_read_b128 v[146:149], v212 offset:2048
	ds_read_b128 v[150:153], v212 offset:4096
	ds_read_b128 v[154:157], v212 offset:6144
	ds_read_b128 v[174:177], v214 offset:32768
	ds_read_b128 v[182:185], v214 offset:34816
	ds_read_b128 v[186:189], v214 offset:36864
	ds_read_b128 v[190:193], v214 offset:38912
	s_mov_b32 m0, s45
	v_mfma_f32_16x16x32_bf16 v[60:63], v[158:161], v[194:197], v[60:63]
	v_mfma_f32_16x16x32_bf16 v[56:59], v[158:161], v[198:201], v[56:59]
	global_load_lds_dwordx4 v178, s[36:37]
	s_add_u32 m0, s45, 0x2000
	v_mfma_f32_16x16x32_bf16 v[52:55], v[158:161], v[202:205], v[52:55]
	v_mfma_f32_16x16x32_bf16 v[48:51], v[158:161], v[206:209], v[48:51]
	global_load_lds_dwordx4 v216, s[36:37]
	s_add_u32 m0, s45, 0x4000
	v_mfma_f32_16x16x32_bf16 v[44:47], v[162:165], v[194:197], v[44:47]
	v_mfma_f32_16x16x32_bf16 v[32:35], v[162:165], v[198:201], v[32:35]
	global_load_lds_dwordx4 v217, s[36:37]
	s_add_u32 m0, s45, 0x6000
	v_mfma_f32_16x16x32_bf16 v[28:31], v[162:165], v[202:205], v[28:31]
	v_mfma_f32_16x16x32_bf16 v[24:27], v[162:165], v[206:209], v[24:27]
	global_load_lds_dwordx4 v218, s[36:37]
	s_add_u32 m0, s45, 0x8000
	v_mfma_f32_16x16x32_bf16 v[20:23], v[166:169], v[194:197], v[20:23]
	v_mfma_f32_16x16x32_bf16 v[16:19], v[166:169], v[198:201], v[16:19]
	global_load_lds_dwordx4 v179, s[36:37]
	s_add_u32 m0, s45, 0xa000
	v_mfma_f32_16x16x32_bf16 v[12:15], v[166:169], v[202:205], v[12:15]
	v_mfma_f32_16x16x32_bf16 v[8:11], v[166:169], v[206:209], v[8:11]
	global_load_lds_dwordx4 v219, s[36:37]
	s_add_u32 m0, s45, 0xc000
	v_mfma_f32_16x16x32_bf16 v[4:7], v[170:173], v[194:197], v[4:7]
	v_mfma_f32_16x16x32_bf16 v[0:3], v[170:173], v[198:201], v[0:3]
	global_load_lds_dwordx4 v220, s[36:37]
	s_add_u32 m0, s45, 0xe000
	v_mfma_f32_16x16x32_bf16 v[40:43], v[170:173], v[202:205], v[40:43]
	v_mfma_f32_16x16x32_bf16 v[36:39], v[170:173], v[206:209], v[36:39]
	global_load_lds_dwordx4 v221, s[36:37]
	ds_read_b128 v[158:161], v212 offset:8192
	ds_read_b128 v[162:165], v212 offset:10240
	ds_read_b128 v[166:169], v212 offset:12288
	ds_read_b128 v[170:173], v212 offset:14336
	s_waitcnt lgkmcnt(4)
	v_mfma_f32_16x16x32_bf16 v[124:127], v[142:145], v[174:177], v[124:127]
	v_mfma_f32_16x16x32_bf16 v[120:123], v[142:145], v[182:185], v[120:123]
	v_mfma_f32_16x16x32_bf16 v[116:119], v[142:145], v[186:189], v[116:119]
	v_mfma_f32_16x16x32_bf16 v[112:115], v[142:145], v[190:193], v[112:115]
	v_mfma_f32_16x16x32_bf16 v[108:111], v[146:149], v[174:177], v[108:111]
	v_mfma_f32_16x16x32_bf16 v[104:107], v[146:149], v[182:185], v[104:107]
	v_mfma_f32_16x16x32_bf16 v[100:103], v[146:149], v[186:189], v[100:103]
	v_mfma_f32_16x16x32_bf16 v[96:99], v[146:149], v[190:193], v[96:99]
	v_mfma_f32_16x16x32_bf16 v[92:95], v[150:153], v[174:177], v[92:95]
	v_mfma_f32_16x16x32_bf16 v[88:91], v[150:153], v[182:185], v[88:91]
	v_mfma_f32_16x16x32_bf16 v[84:87], v[150:153], v[186:189], v[84:87]
	v_mfma_f32_16x16x32_bf16 v[80:83], v[150:153], v[190:193], v[80:83]
	v_mfma_f32_16x16x32_bf16 v[76:79], v[154:157], v[174:177], v[76:79]
	v_mfma_f32_16x16x32_bf16 v[72:75], v[154:157], v[182:185], v[72:75]
	v_mfma_f32_16x16x32_bf16 v[68:71], v[154:157], v[186:189], v[68:71]
	v_mfma_f32_16x16x32_bf16 v[64:67], v[154:157], v[190:193], v[64:67]
	ds_read_b128 v[142:145], v213
	ds_read_b128 v[146:149], v213 offset:2048
	ds_read_b128 v[150:153], v213 offset:4096
	ds_read_b128 v[154:157], v213 offset:6144
	ds_read_b128 v[194:197], v215 offset:32768
	ds_read_b128 v[198:201], v215 offset:34816
	ds_read_b128 v[202:205], v215 offset:36864
	ds_read_b128 v[206:209], v215 offset:38912
	s_waitcnt lgkmcnt(8)
	v_mfma_f32_16x16x32_bf16 v[60:63], v[158:161], v[174:177], v[60:63]
	v_mfma_f32_16x16x32_bf16 v[56:59], v[158:161], v[182:185], v[56:59]
	v_mfma_f32_16x16x32_bf16 v[52:55], v[158:161], v[186:189], v[52:55]
	v_mfma_f32_16x16x32_bf16 v[48:51], v[158:161], v[190:193], v[48:51]
	v_mfma_f32_16x16x32_bf16 v[44:47], v[162:165], v[174:177], v[44:47]
	v_mfma_f32_16x16x32_bf16 v[32:35], v[162:165], v[182:185], v[32:35]
	v_mfma_f32_16x16x32_bf16 v[28:31], v[162:165], v[186:189], v[28:31]
	v_mfma_f32_16x16x32_bf16 v[24:27], v[162:165], v[190:193], v[24:27]
	v_mfma_f32_16x16x32_bf16 v[20:23], v[166:169], v[174:177], v[20:23]
	v_mfma_f32_16x16x32_bf16 v[16:19], v[166:169], v[182:185], v[16:19]
	v_mfma_f32_16x16x32_bf16 v[12:15], v[166:169], v[186:189], v[12:15]
	v_mfma_f32_16x16x32_bf16 v[8:11], v[166:169], v[190:193], v[8:11]
	v_mfma_f32_16x16x32_bf16 v[4:7], v[170:173], v[174:177], v[4:7]
	v_mfma_f32_16x16x32_bf16 v[0:3], v[170:173], v[182:185], v[0:3]
	v_mfma_f32_16x16x32_bf16 v[40:43], v[170:173], v[186:189], v[40:43]
	v_mfma_f32_16x16x32_bf16 v[36:39], v[170:173], v[190:193], v[36:39]
	ds_read_b128 v[158:161], v213 offset:8192
	ds_read_b128 v[162:165], v213 offset:10240
	ds_read_b128 v[166:169], v213 offset:12288
	ds_read_b128 v[170:173], v213 offset:14336
	s_waitcnt lgkmcnt(4)
	v_mfma_f32_16x16x32_bf16 v[124:127], v[142:145], v[194:197], v[124:127]
	v_mfma_f32_16x16x32_bf16 v[120:123], v[142:145], v[198:201], v[120:123]
	v_mfma_f32_16x16x32_bf16 v[116:119], v[142:145], v[202:205], v[116:119]
	v_mfma_f32_16x16x32_bf16 v[112:115], v[142:145], v[206:209], v[112:115]
	v_mfma_f32_16x16x32_bf16 v[108:111], v[146:149], v[194:197], v[108:111]
	v_mfma_f32_16x16x32_bf16 v[104:107], v[146:149], v[198:201], v[104:107]
	v_mfma_f32_16x16x32_bf16 v[100:103], v[146:149], v[202:205], v[100:103]
	v_mfma_f32_16x16x32_bf16 v[96:99], v[146:149], v[206:209], v[96:99]
	v_mfma_f32_16x16x32_bf16 v[92:95], v[150:153], v[194:197], v[92:95]
	v_mfma_f32_16x16x32_bf16 v[88:91], v[150:153], v[198:201], v[88:91]
	v_mfma_f32_16x16x32_bf16 v[84:87], v[150:153], v[202:205], v[84:87]
	v_mfma_f32_16x16x32_bf16 v[80:83], v[150:153], v[206:209], v[80:83]
	v_mfma_f32_16x16x32_bf16 v[76:79], v[154:157], v[194:197], v[76:79]
	v_mfma_f32_16x16x32_bf16 v[72:75], v[154:157], v[198:201], v[72:75]
	v_mfma_f32_16x16x32_bf16 v[68:71], v[154:157], v[202:205], v[68:71]
	v_mfma_f32_16x16x32_bf16 v[64:67], v[154:157], v[206:209], v[64:67]
	s_add_u32 s36, s36, 0x80
	s_addc_u32 s37, s37, 0
	s_add_i32 s31, s31, 1
	s_branch .Lg11_top
